# plus differential-attention loops run with ONE s_barrier per key tile: V staging write deferred past the barrier (K write stays before it), second-half V data parked in spare VGPRs
# speedup vs baseline: 1.0051x; 1.0051x over previous
; __device__ __forceinline__ int opaque_tid() { int t = threadIdx.x; asm volatile("" : "+v"(t)); return t; }
; __device__ __forceinline__ int crow(int r, int hi) { return (r & 3) + 8 * (r >> 2) + 4 * hi; }
; template <int DK, bool NA, bool QL, int SD> ...
;     ...
;   for (int r = 0; r < 16; ++r) { const float rl = __builtin_amdgcn_rcpf(li_l[crow(r, hi)]);
; #pragma unroll
;     for (int d = 0; d < 4; ++d) o[d][r] *= rl; }
; __global__ void __launch_bounds__(NTHR) mega_fwd(Params p) {
;     ...
;                     { const int t3 = opaque_tid(), l3 = t3 & 63, r32 = l3 & 31; const v4u* STv = (const v4u*)((char*)lds + 69632) + t3;
;                       const float* sg = p.diff_subln + l * 128;
;                       float gsub[4], ss[16];
; #pragma unroll
;                       for (int d = 0; d < 4; ++d) gsub[d] = sg[32 * d + r32] * (1.0f - lam_init);
; #pragma unroll
;                       for (int r = 0; r < 16; ++r) ss[r] = 0.f;
; #pragma unroll
;                       for (int k = 0; k < 8; ++k) { const int d = k >> 1, r0 = 8 * (k & 1); const v4u w = STv[k * 512];
; #pragma unroll
;                           for (int i = 0; i < 4; ++i) { const unsigned wi = i == 0 ? w.x : (i == 1 ? w.y : (i == 2 ? w.z : w.w));
;                               const float va = bf2f((unsigned short)(wi & 0xffffu)) - lam * o[d][r0 + 2 * i], vb = bf2f((unsigned short)(wi >> 16)) - lam * o[d][r0 + 2 * i + 1];
;                               o[d][r0 + 2 * i] = va; o[d][r0 + 2 * i + 1] = vb; ss[r0 + 2 * i] += va * va; ss[r0 + 2 * i + 1] += vb * vb; } }
.LBB0_368:
	s_or_b64 exec, exec, s[2:3]
	v_mov_b32_e32 v194, 0x3c23d70a
	v_mov_b32_e32 v195, 0x2800
	v_mov_b64_e32 v[196:197], 0x580
	s_waitcnt vmcnt(0) lgkmcnt(0)
	v_add_u32_e32 v0, v207, v0
	ds_read_b128 v[72:75], v0
	ds_read_b128 v[76:79], v0 offset:32
	v_readlane_b32 s0, v255, 40
	v_readlane_b32 s1, v255, 41
	s_mov_b32 s2, 0xf800000
	s_waitcnt lgkmcnt(1)
	v_rcp_f32_e32 v67, v72
	v_rcp_f32_e32 v68, v73
	v_mul_f32_e32 v70, v67, v34
	v_mul_f32_e32 v34, v67, v18
	v_rcp_f32_e32 v18, v74
	v_mul_f32_e32 v69, v67, v50
	v_mul_f32_e32 v71, v68, v35
	v_mul_f32_e32 v66, v68, v19
	v_mul_f32_e32 v50, v18, v4
	v_rcp_f32_e32 v4, v75
	v_mul_f32_e32 v72, v18, v52
	v_mul_f32_e32 v73, v18, v36
	v_mul_f32_e32 v36, v18, v20
	v_mul_f32_e32 v82, v4, v5
	v_mul_f32_e32 v74, v4, v53
	v_mul_f32_e32 v53, v4, v37
	v_mul_f32_e32 v52, v4, v21
	s_waitcnt lgkmcnt(0)
	v_rcp_f32_e32 v4, v76
	v_mul_f32_e32 v2, v67, v2
	v_mul_f32_e32 v3, v68, v3
	v_mul_f32_e32 v51, v68, v51
	v_mul_f32_e32 v37, v4, v6
	v_mul_f32_e32 v80, v4, v54
	v_mul_f32_e32 v76, v4, v38
	v_mul_f32_e32 v75, v4, v22
	v_rcp_f32_e32 v4, v77
	s_nop 0
	v_mul_f32_e32 v54, v4, v7
	v_mul_f32_e32 v38, v4, v55
	v_mul_f32_e32 v81, v4, v39
	v_mul_f32_e32 v77, v4, v23
	v_rcp_f32_e32 v4, v78
	ds_read_b128 v[20:23], v0 offset:64
	v_mul_f32_e32 v55, v4, v8
	v_mul_f32_e32 v88, v4, v56
	v_mul_f32_e32 v84, v4, v40
	v_mul_f32_e32 v40, v4, v24
	v_rcp_f32_e32 v4, v79
	s_nop 0
	v_mul_f32_e32 v86, v4, v9
	v_mul_f32_e32 v57, v4, v57
	v_mul_f32_e32 v85, v4, v41
	v_mul_f32_e32 v41, v4, v25
	s_waitcnt lgkmcnt(0)
	v_rcp_f32_e32 v4, v20
	s_nop 0
	v_mul_f32_e32 v7, v4, v10
	v_mul_f32_e32 v8, v4, v58
	v_mul_f32_e32 v10, v4, v42
	v_mul_f32_e32 v18, v4, v26
	v_rcp_f32_e32 v4, v21
	s_nop 0
	v_mul_f32_e32 v9, v4, v11
	v_mul_f32_e32 v21, v4, v59
	v_mul_f32_e32 v35, v4, v43
	v_mul_f32_e32 v20, v4, v27
	v_rcp_f32_e32 v4, v22
	s_nop 0
	v_mul_f32_e32 v12, v4, v12
	v_mul_f32_e32 v11, v4, v60
	v_mul_f32_e32 v25, v4, v44
	v_mul_f32_e32 v22, v4, v28
	v_rcp_f32_e32 v4, v23
	s_nop 0
	v_mul_f32_e32 v28, v4, v45
	ds_read_b128 v[42:45], v0 offset:96
	v_mul_f32_e32 v19, v4, v13
	v_mul_f32_e32 v27, v4, v61
	v_mul_f32_e32 v23, v4, v29
	s_waitcnt lgkmcnt(0)
	v_rcp_f32_e32 v0, v42
	s_nop 0
	v_mul_f32_e32 v42, v0, v14
	v_mul_f32_e32 v13, v0, v62
	v_mul_f32_e32 v46, v0, v46
	v_mul_f32_e32 v14, v0, v30
	v_rcp_f32_e32 v0, v43
	s_nop 0
	v_mul_f32_e32 v30, v0, v15
	v_mul_f32_e32 v61, v0, v63
	v_mul_f32_e32 v78, v0, v47
	v_mul_f32_e32 v24, v0, v31
	v_rcp_f32_e32 v0, v44
	v_mov_b32_e32 v15, v188
	v_mul_f32_e32 v16, v0, v16
	v_mul_f32_e32 v43, v0, v64
	v_mul_f32_e32 v56, v0, v48
	v_mul_f32_e32 v31, v0, v32
	v_rcp_f32_e32 v0, v45
	s_nop 0
	v_mul_f32_e32 v45, v0, v17
	v_mul_f32_e32 v17, v0, v65
	v_mul_f32_e32 v79, v0, v49
	v_mul_f32_e32 v32, v0, v33
	v_and_b32_e32 v0, 31, v15
	v_lshl_add_u32 v15, v15, 4, 0
	v_add_u32_e32 v92, 0x11000, v15
	ds_read_b128 v[62:65], v92
	ds_read_b128 v[94:97], v92 offset:8192
	v_lshlrev_b32_e32 v6, 2, v0
	global_load_dword v0, v6, s[0:1]
	global_load_dword v4, v6, s[0:1] offset:128
	global_load_dword v5, v6, s[0:1] offset:256
	s_waitcnt lgkmcnt(1)
	v_lshlrev_b32_e32 v15, 16, v62
	v_fma_f32 v87, -v202, v2, v15
	v_and_b32_e32 v2, 0xffff0000, v62
	v_fma_f32 v33, -v202, v3, v2
	v_lshlrev_b32_e32 v2, 16, v63
	v_fma_f32 v39, -v202, v50, v2
	v_and_b32_e32 v2, 0xffff0000, v63
	v_fma_f32 v49, -v202, v82, v2
	v_lshlrev_b32_e32 v2, 16, v64
	v_fma_f32 v58, -v202, v37, v2
	v_and_b32_e32 v2, 0xffff0000, v64
	v_fma_f32 v67, -v202, v54, v2
	v_lshlrev_b32_e32 v2, 16, v65
	v_fma_f32 v64, -v202, v55, v2
	v_and_b32_e32 v2, 0xffff0000, v65
	v_fma_f32 v54, -v202, v86, v2
	s_waitcnt lgkmcnt(0)
	v_lshlrev_b32_e32 v2, 16, v94
	v_fma_f32 v47, -v202, v7, v2
	v_and_b32_e32 v2, 0xffff0000, v94
	v_fma_f32 v37, -v202, v9, v2
	v_lshlrev_b32_e32 v2, 16, v95
	v_fma_f32 v29, -v202, v12, v2
	v_and_b32_e32 v2, 0xffff0000, v95
	v_fma_f32 v19, -v202, v19, v2
	v_lshlrev_b32_e32 v2, 16, v96
	v_fma_f32 v15, -v202, v42, v2
	v_and_b32_e32 v2, 0xffff0000, v96
	v_fma_f32 v9, -v202, v30, v2
	v_lshlrev_b32_e32 v2, 16, v97
	v_fma_f32 v7, -v202, v16, v2
	v_and_b32_e32 v2, 0xffff0000, v97
	ds_read_b128 v[94:97], v92 offset:16384
	global_load_dword v6, v6, s[0:1] offset:384
	v_mul_f32_e32 v83, v33, v33
	v_mul_f32_e32 v50, v49, v49
	v_mul_f32_e32 v68, v67, v67
	s_waitcnt lgkmcnt(0)
	v_lshlrev_b32_e32 v16, 16, v94
	v_fma_f32 v89, -v202, v69, v16
	v_and_b32_e32 v16, 0xffff0000, v94
	v_fma_f32 v86, -v202, v51, v16
	v_lshlrev_b32_e32 v16, 16, v95
	v_fma_f32 v42, -v202, v72, v16
	v_and_b32_e32 v16, 0xffff0000, v95
	v_fma_f32 v51, -v202, v74, v16
	v_lshlrev_b32_e32 v16, 16, v96
	v_fma_f32 v59, -v202, v80, v16
	v_and_b32_e32 v16, 0xffff0000, v96
	v_fma_f32 v69, -v202, v38, v16
	v_lshlrev_b32_e32 v16, 16, v97
	v_fma_f32 v72, -v202, v88, v16
	v_and_b32_e32 v16, 0xffff0000, v97
	ds_read_b128 v[94:97], v92 offset:24576
	v_fma_f32 v63, -v202, v57, v16
	v_mul_f32_e32 v91, v89, v89
	v_fmac_f32_e32 v91, v87, v87
	v_fmac_f32_e32 v83, v86, v86
	s_waitcnt lgkmcnt(0)
	v_lshlrev_b32_e32 v16, 16, v94
	v_fma_f32 v57, -v202, v8, v16
	v_and_b32_e32 v8, 0xffff0000, v94
	v_fma_f32 v48, -v202, v21, v8
	v_lshlrev_b32_e32 v8, 16, v95
	v_fma_f32 v38, -v202, v11, v8
	v_and_b32_e32 v8, 0xffff0000, v95
	v_fma_f32 v30, -v202, v27, v8
	v_lshlrev_b32_e32 v8, 16, v96
	v_fma_f32 v21, -v202, v13, v8
	v_and_b32_e32 v8, 0xffff0000, v96
	v_fma_f32 v16, -v202, v61, v8
	v_lshlrev_b32_e32 v8, 16, v97
	v_fma_f32 v11, -v202, v43, v8
	v_and_b32_e32 v8, 0xffff0000, v97
	ds_read_b128 v[94:97], v92 offset:32768
	v_fma_f32 v8, -v202, v17, v8
	v_mul_f32_e32 v82, v42, v42
	v_fmac_f32_e32 v82, v39, v39
	v_fmac_f32_e32 v50, v51, v51
	s_waitcnt lgkmcnt(0)
; __global__ void __launch_bounds__(NTHR) mega_fwd(Params p) {
;     ...
;                       for (int k = 0; k < 8; ++k) { const int d = k >> 1, r0 = 8 * (k & 1); const v4u w = STv[k * 512];
; #pragma unroll
;                           for (int i = 0; i < 4; ++i) { const unsigned wi = i == 0 ? w.x : (i == 1 ? w.y : (i == 2 ? w.z : w.w));
;                               const float va = bf2f((unsigned short)(wi & 0xffffu)) - lam * o[d][r0 + 2 * i], vb = bf2f((unsigned short)(wi >> 16)) - lam * o[d][r0 + 2 * i + 1];
;                               o[d][r0 + 2 * i] = va; o[d][r0 + 2 * i + 1] = vb; ss[r0 + 2 * i] += va * va; ss[r0 + 2 * i + 1] += vb * vb; } }
; #pragma unroll
;                       for (int r = 0; r < 16; ++r) { float q = ss[r]; q += __shfl_xor(q, 1); q += __shfl_xor(q, 2); q += __shfl_xor(q, 4); q += __shfl_xor(q, 8); q += __shfl_xor(q, 16);
;                           const float rstd = 1.0f / sqrtf(q * (1.0f / 128.0f) + EPS);
; #pragma unroll
;                           for (int d = 0; d < 4; ++d) o[d][r] *= rstd * gsub[d]; } }
	v_lshlrev_b32_e32 v17, 16, v94
	v_fma_f32 v93, -v202, v70, v17
	v_and_b32_e32 v17, 0xffff0000, v94
	v_fma_f32 v90, -v202, v71, v17
	v_lshlrev_b32_e32 v17, 16, v95
	v_fma_f32 v88, -v202, v73, v17
	v_and_b32_e32 v17, 0xffff0000, v95
	v_fma_f32 v80, -v202, v53, v17
	v_lshlrev_b32_e32 v17, 16, v96
	v_fma_f32 v61, -v202, v76, v17
	v_and_b32_e32 v17, 0xffff0000, v96
	v_fma_f32 v70, -v202, v81, v17
	v_lshlrev_b32_e32 v17, 16, v97
	v_fma_f32 v76, -v202, v84, v17
	v_and_b32_e32 v17, 0xffff0000, v97
	ds_read_b128 v[94:97], v92 offset:40960
	v_fma_f32 v73, -v202, v85, v17
	v_fmac_f32_e32 v91, v93, v93
	v_fmac_f32_e32 v83, v90, v90
	s_waitcnt vmcnt(3)
	v_mul_f32_e32 v0, v201, v0
	s_waitcnt lgkmcnt(0)
	v_lshlrev_b32_e32 v17, 16, v94
	v_fma_f32 v71, -v202, v10, v17
	v_and_b32_e32 v10, 0xffff0000, v94
	v_fma_f32 v62, -v202, v35, v10
	v_lshlrev_b32_e32 v10, 16, v95
	v_fma_f32 v53, -v202, v25, v10
	v_and_b32_e32 v10, 0xffff0000, v95
	v_fma_f32 v43, -v202, v28, v10
	v_lshlrev_b32_e32 v10, 16, v96
	v_fma_f32 v35, -v202, v46, v10
	v_and_b32_e32 v10, 0xffff0000, v96
	v_fma_f32 v25, -v202, v78, v10
	v_lshlrev_b32_e32 v10, 16, v97
	v_fma_f32 v17, -v202, v56, v10
	v_and_b32_e32 v10, 0xffff0000, v97
	ds_read_b128 v[94:97], v92 offset:49152
	v_fma_f32 v10, -v202, v79, v10
	s_waitcnt vmcnt(2)
	v_mul_f32_e32 v4, v201, v4
	s_waitcnt vmcnt(1)
	v_mul_f32_e32 v5, v201, v5
	s_waitcnt vmcnt(0)
	v_mul_f32_e32 v6, v201, v6
	s_waitcnt lgkmcnt(0)
	v_lshlrev_b32_e32 v28, 16, v94
	v_fma_f32 v85, -v202, v34, v28
	v_and_b32_e32 v28, 0xffff0000, v94
	v_fma_f32 v34, -v202, v66, v28
	v_lshlrev_b32_e32 v28, 16, v95
	v_fma_f32 v84, -v202, v36, v28
	v_and_b32_e32 v28, 0xffff0000, v95
	v_fma_f32 v52, -v202, v52, v28
	v_lshlrev_b32_e32 v28, 16, v96
	v_fma_f32 v81, -v202, v75, v28
	v_and_b32_e32 v28, 0xffff0000, v96
	v_fma_f32 v79, -v202, v77, v28
	v_lshlrev_b32_e32 v28, 16, v97
	v_fma_f32 v78, -v202, v40, v28
	v_and_b32_e32 v28, 0xffff0000, v97
	ds_read_b128 v[94:97], v92 offset:57344
	v_fma_f32 v77, -v202, v41, v28
	v_fmac_f32_e32 v91, v85, v85
	v_fmac_f32_e32 v83, v34, v34
	v_fmac_f32_e32 v82, v88, v88
	s_waitcnt lgkmcnt(0)
	v_lshlrev_b32_e32 v28, 16, v94
	v_fma_f32 v75, -v202, v18, v28
	v_and_b32_e32 v18, 0xffff0000, v94
	v_fma_f32 v66, -v202, v20, v18
	ds_bpermute_b32 v20, v162, v91
	v_lshlrev_b32_e32 v18, 16, v95
	v_fma_f32 v56, -v202, v22, v18
	v_and_b32_e32 v18, 0xffff0000, v95
	v_fma_f32 v46, -v202, v23, v18
	s_waitcnt lgkmcnt(0)
	v_add_f32_e32 v20, v91, v20
	ds_bpermute_b32 v22, v178, v20
	v_lshlrev_b32_e32 v18, 16, v96
	v_fma_f32 v36, -v202, v14, v18
	v_and_b32_e32 v14, 0xffff0000, v96
	v_fma_f32 v28, -v202, v24, v14
	s_waitcnt lgkmcnt(0)
	v_add_f32_e32 v20, v20, v22
	ds_bpermute_b32 v22, v179, v20
	v_lshlrev_b32_e32 v14, 16, v97
	v_fma_f32 v18, -v202, v31, v14
	v_and_b32_e32 v14, 0xffff0000, v97
	v_fma_f32 v14, -v202, v32, v14
	s_waitcnt lgkmcnt(0)
	v_add_f32_e32 v20, v20, v22
	ds_bpermute_b32 v22, v180, v20
	v_fmac_f32_e32 v82, v84, v84
	v_fmac_f32_e32 v50, v80, v80
	v_fmac_f32_e32 v50, v52, v52
	v_mul_f32_e32 v60, v59, v59
	s_waitcnt lgkmcnt(0)
	v_add_f32_e32 v20, v20, v22
	ds_bpermute_b32 v22, v187, v20
	v_fmac_f32_e32 v60, v58, v58
	v_fmac_f32_e32 v60, v61, v61
	v_fmac_f32_e32 v60, v81, v81
	v_fmac_f32_e32 v68, v69, v69
	s_waitcnt lgkmcnt(0)
	v_add_f32_e32 v20, v20, v22
	v_fmamk_f32 v20, v20, 0x3c000000, v189
	v_cmp_gt_f32_e32 vcc, s2, v20
	v_mul_f32_e32 v22, 0x4f800000, v20
	v_fmac_f32_e32 v68, v70, v70
	v_cndmask_b32_e32 v20, v20, v22, vcc
	v_sqrt_f32_e32 v22, v20
	v_fmac_f32_e32 v68, v79, v79
	v_mul_f32_e32 v74, v72, v72
	v_fmac_f32_e32 v74, v64, v64
	v_add_u32_e32 v23, -1, v22
	v_fma_f32 v24, -v23, v22, v20
	v_cmp_ge_f32_e64 s[0:1], 0, v24
	v_add_u32_e32 v24, 1, v22
	v_fmac_f32_e32 v74, v76, v76
	v_cndmask_b32_e64 v23, v22, v23, s[0:1]
	v_fma_f32 v22, -v24, v22, v20
	v_cmp_lt_f32_e64 s[0:1], 0, v22
	v_fmac_f32_e32 v74, v78, v78
	v_mul_f32_e32 v55, v54, v54
	v_cndmask_b32_e64 v22, v23, v24, s[0:1]
	v_mul_f32_e32 v23, 0x37800000, v22
	v_cndmask_b32_e32 v22, v22, v23, vcc
	v_cmp_class_f32_e32 vcc, v20, v190
	v_fmac_f32_e32 v55, v63, v63
	v_fmac_f32_e32 v55, v73, v73
	v_cndmask_b32_e32 v20, v22, v20, vcc
	v_div_scale_f32 v22, s[0:1], v20, v20, 1.0
	v_rcp_f32_e32 v23, v22
	v_fmac_f32_e32 v55, v77, v77
	v_mul_f32_e32 v65, v57, v57
	v_fmac_f32_e32 v65, v47, v47
	v_fma_f32 v24, -v22, v23, 1.0
	v_fmac_f32_e32 v23, v24, v23
	v_div_scale_f32 v24, vcc, 1.0, v20, 1.0
	v_mul_f32_e32 v31, v24, v23
	v_fma_f32 v32, -v22, v31, v24
	v_fmac_f32_e32 v31, v32, v23
	v_fma_f32 v22, -v22, v31, v24
	v_div_fmas_f32 v22, v22, v23, v31
	ds_bpermute_b32 v31, v162, v83
	v_div_fixup_f32 v24, v22, v20, 1.0
	v_mul_f32_e32 v20, v24, v0
	v_mul_f32_e32 v22, v24, v4
	v_mul_f32_e32 v23, v24, v5
	s_waitcnt lgkmcnt(0)
	v_add_f32_e32 v31, v83, v31
	ds_bpermute_b32 v32, v178, v31
	v_mul_f32_e32 v24, v24, v6
	v_mul_f32_e32 v24, v24, v85
	v_fmac_f32_e32 v65, v71, v71
	v_fmac_f32_e32 v65, v75, v75
	s_waitcnt lgkmcnt(0)
	v_add_f32_e32 v31, v31, v32
	ds_bpermute_b32 v32, v179, v31
	v_mul_f32_e32 v44, v37, v37
	v_fmac_f32_e32 v44, v48, v48
	v_fmac_f32_e32 v44, v62, v62
	v_fmac_f32_e32 v44, v66, v66
	s_waitcnt lgkmcnt(0)
	v_add_f32_e32 v31, v31, v32
	ds_bpermute_b32 v32, v180, v31
	v_fma_f32 v2, -v202, v45, v2
	v_mul_f32_e32 v45, v38, v38
	v_fmac_f32_e32 v45, v29, v29
	v_fmac_f32_e32 v45, v53, v53
	s_waitcnt lgkmcnt(0)
	v_add_f32_e32 v31, v31, v32
	ds_bpermute_b32 v32, v187, v31
	v_fmac_f32_e32 v45, v56, v56
	v_mul_f32_e32 v26, v19, v19
	v_fmac_f32_e32 v26, v30, v30
	v_fmac_f32_e32 v26, v43, v43
	s_waitcnt lgkmcnt(0)
; __global__ void __launch_bounds__(NTHR) mega_fwd(Params p) {
;     ...
;                       for (int r = 0; r < 16; ++r) { float q = ss[r]; q += __shfl_xor(q, 1); q += __shfl_xor(q, 2); q += __shfl_xor(q, 4); q += __shfl_xor(q, 8); q += __shfl_xor(q, 16);
;                           const float rstd = 1.0f / sqrtf(q * (1.0f / 128.0f) + EPS);
; #pragma unroll
;                           for (int d = 0; d < 4; ++d) o[d][r] *= rstd * gsub[d]; } }
	v_add_f32_e32 v31, v31, v32
	v_fmamk_f32 v31, v31, 0x3c000000, v189
	v_cmp_gt_f32_e32 vcc, s2, v31
	v_mul_f32_e32 v32, 0x4f800000, v31
	v_fmac_f32_e32 v26, v46, v46
	v_cndmask_b32_e32 v31, v31, v32, vcc
	v_sqrt_f32_e32 v32, v31
	v_mul_f32_e32 v27, v21, v21
	v_fmac_f32_e32 v27, v15, v15
	v_fmac_f32_e32 v27, v35, v35
	v_add_u32_e32 v40, -1, v32
	v_fma_f32 v41, -v40, v32, v31
	v_cmp_ge_f32_e64 s[0:1], 0, v41
	v_add_u32_e32 v41, 1, v32
	v_fmac_f32_e32 v27, v36, v36
	v_cndmask_b32_e64 v40, v32, v40, s[0:1]
	v_fma_f32 v32, -v41, v32, v31
	v_cmp_lt_f32_e64 s[0:1], 0, v32
	v_mul_f32_e32 v12, v9, v9
	v_fmac_f32_e32 v12, v16, v16
	v_cndmask_b32_e64 v32, v40, v41, s[0:1]
	v_mul_f32_e32 v40, 0x37800000, v32
	v_cndmask_b32_e32 v32, v32, v40, vcc
	v_cmp_class_f32_e32 vcc, v31, v190
	v_fmac_f32_e32 v12, v25, v25
	v_fmac_f32_e32 v12, v28, v28
	v_cndmask_b32_e32 v31, v32, v31, vcc
	v_div_scale_f32 v32, s[0:1], v31, v31, 1.0
	v_rcp_f32_e32 v40, v32
	v_mul_f32_e32 v13, v11, v11
	v_fmac_f32_e32 v13, v7, v7
	v_fmac_f32_e32 v13, v17, v17
	v_fma_f32 v41, -v32, v40, 1.0
	v_fmac_f32_e32 v40, v41, v40
	v_div_scale_f32 v41, vcc, 1.0, v31, 1.0
	v_mul_f32_e32 v83, v41, v40
	v_fma_f32 v85, -v32, v83, v41
	v_fmac_f32_e32 v83, v85, v40
	v_fma_f32 v32, -v32, v83, v41
	v_div_fmas_f32 v32, v32, v40, v83
	v_div_fixup_f32 v40, v32, v31, 1.0
	v_mul_f32_e32 v31, v40, v0
	v_mul_f32_e32 v31, v31, v33
	v_mul_f32_e32 v32, v40, v4
	v_mul_f32_e32 v33, v40, v5
	v_mul_f32_e32 v40, v40, v6
	v_mul_f32_e32 v34, v40, v34
	ds_bpermute_b32 v40, v162, v82
	v_mul_f32_e32 v32, v32, v86
	v_fmac_f32_e32 v13, v18, v18
	v_mul_f32_e32 v3, v2, v2
	v_fmac_f32_e32 v3, v8, v8
	s_waitcnt lgkmcnt(0)
	v_add_f32_e32 v40, v82, v40
	ds_bpermute_b32 v41, v178, v40
	v_fmac_f32_e32 v3, v10, v10
	v_fmac_f32_e32 v3, v14, v14
	v_mul_f32_e32 v20, v20, v87
	v_mul_f32_e32 v22, v22, v89
	s_waitcnt lgkmcnt(0)
	v_add_f32_e32 v40, v40, v41
	ds_bpermute_b32 v41, v179, v40
	v_mul_f32_e32 v23, v23, v93
	v_mul_f32_e32 v33, v33, v90
	s_waitcnt lgkmcnt(0)
	v_add_f32_e32 v40, v40, v41
	ds_bpermute_b32 v41, v180, v40
	s_waitcnt lgkmcnt(0)
	v_add_f32_e32 v40, v40, v41
	ds_bpermute_b32 v41, v187, v40
	s_waitcnt lgkmcnt(0)
	v_add_f32_e32 v40, v40, v41
	v_fmamk_f32 v40, v40, 0x3c000000, v189
	v_cmp_gt_f32_e32 vcc, s2, v40
	v_mul_f32_e32 v41, 0x4f800000, v40
	s_nop 0
	v_cndmask_b32_e32 v40, v40, v41, vcc
	v_sqrt_f32_e32 v41, v40
	s_nop 0
	v_add_u32_e32 v82, -1, v41
	v_fma_f32 v83, -v82, v41, v40
	v_cmp_ge_f32_e64 s[0:1], 0, v83
	v_add_u32_e32 v83, 1, v41
	s_nop 0
	v_cndmask_b32_e64 v82, v41, v82, s[0:1]
	v_fma_f32 v41, -v83, v41, v40
	v_cmp_lt_f32_e64 s[0:1], 0, v41
	s_nop 1
	v_cndmask_b32_e64 v41, v82, v83, s[0:1]
	v_mul_f32_e32 v82, 0x37800000, v41
	v_cndmask_b32_e32 v41, v41, v82, vcc
	v_cmp_class_f32_e32 vcc, v40, v190
	s_nop 1
	v_cndmask_b32_e32 v40, v41, v40, vcc
	v_div_scale_f32 v41, s[0:1], v40, v40, 1.0
	v_rcp_f32_e32 v82, v41
	s_nop 0
	v_fma_f32 v83, -v41, v82, 1.0
	v_fmac_f32_e32 v82, v83, v82
	v_div_scale_f32 v83, vcc, 1.0, v40, 1.0
	v_mul_f32_e32 v85, v83, v82
	v_fma_f32 v86, -v41, v85, v83
	v_fmac_f32_e32 v85, v86, v82
	v_fma_f32 v41, -v41, v85, v83
	v_div_fmas_f32 v41, v41, v82, v85
	v_div_fixup_f32 v82, v41, v40, 1.0
	v_mul_f32_e32 v40, v82, v0
	v_mul_f32_e32 v39, v40, v39
	v_mul_f32_e32 v40, v82, v4
	v_mul_f32_e32 v40, v40, v42
	v_mul_f32_e32 v41, v82, v5
	v_mul_f32_e32 v42, v82, v6
	ds_bpermute_b32 v82, v162, v50
	v_mul_f32_e32 v42, v42, v84
	v_mul_f32_e32 v41, v41, v88
	s_waitcnt lgkmcnt(0)
	v_add_f32_e32 v50, v50, v82
	ds_bpermute_b32 v82, v178, v50
	s_waitcnt lgkmcnt(0)
	v_add_f32_e32 v50, v50, v82
	ds_bpermute_b32 v82, v179, v50
	s_waitcnt lgkmcnt(0)
	v_add_f32_e32 v50, v50, v82
	ds_bpermute_b32 v82, v180, v50
	s_waitcnt lgkmcnt(0)
	v_add_f32_e32 v50, v50, v82
	ds_bpermute_b32 v82, v187, v50
	s_waitcnt lgkmcnt(0)
	v_add_f32_e32 v50, v50, v82
	v_fmamk_f32 v50, v50, 0x3c000000, v189
	v_cmp_gt_f32_e32 vcc, s2, v50
	v_mul_f32_e32 v82, 0x4f800000, v50
	s_nop 0
	v_cndmask_b32_e32 v50, v50, v82, vcc
	v_sqrt_f32_e32 v82, v50
	s_nop 0
	v_add_u32_e32 v83, -1, v82
	v_fma_f32 v84, -v83, v82, v50
	v_cmp_ge_f32_e64 s[0:1], 0, v84
	v_add_u32_e32 v84, 1, v82
	s_nop 0
	v_cndmask_b32_e64 v83, v82, v83, s[0:1]
	v_fma_f32 v82, -v84, v82, v50
	v_cmp_lt_f32_e64 s[0:1], 0, v82
	s_nop 1
	v_cndmask_b32_e64 v82, v83, v84, s[0:1]
	v_mul_f32_e32 v83, 0x37800000, v82
	v_cndmask_b32_e32 v82, v82, v83, vcc
	v_cmp_class_f32_e32 vcc, v50, v190
	s_nop 1
	v_cndmask_b32_e32 v50, v82, v50, vcc
	v_div_scale_f32 v82, s[0:1], v50, v50, 1.0
	v_rcp_f32_e32 v83, v82
	s_nop 0
	v_fma_f32 v84, -v82, v83, 1.0
	v_fmac_f32_e32 v83, v84, v83
	v_div_scale_f32 v84, vcc, 1.0, v50, 1.0
	v_mul_f32_e32 v85, v84, v83
	v_fma_f32 v86, -v82, v85, v84
	v_fmac_f32_e32 v85, v86, v83
	v_fma_f32 v82, -v82, v85, v84
	v_div_fmas_f32 v82, v82, v83, v85
	v_div_fixup_f32 v82, v82, v50, 1.0
	v_mul_f32_e32 v50, v82, v0
	v_mul_f32_e32 v49, v50, v49
	v_mul_f32_e32 v50, v82, v4
	v_mul_f32_e32 v50, v50, v51
	v_mul_f32_e32 v51, v82, v5
	v_mul_f32_e32 v51, v51, v80
	v_mul_f32_e32 v80, v82, v6
	v_mul_f32_e32 v52, v80, v52
	ds_bpermute_b32 v80, v162, v60
	s_waitcnt lgkmcnt(0)
	v_add_f32_e32 v60, v60, v80
	ds_bpermute_b32 v80, v178, v60
	s_waitcnt lgkmcnt(0)
	v_add_f32_e32 v60, v60, v80
	ds_bpermute_b32 v80, v179, v60
	s_waitcnt lgkmcnt(0)
	v_add_f32_e32 v60, v60, v80
	ds_bpermute_b32 v80, v180, v60
	s_waitcnt lgkmcnt(0)
	v_add_f32_e32 v60, v60, v80
	ds_bpermute_b32 v80, v187, v60
	s_waitcnt lgkmcnt(0)
; __global__ void __launch_bounds__(NTHR) mega_fwd(Params p) {
;     ...
;                       for (int r = 0; r < 16; ++r) { float q = ss[r]; q += __shfl_xor(q, 1); q += __shfl_xor(q, 2); q += __shfl_xor(q, 4); q += __shfl_xor(q, 8); q += __shfl_xor(q, 16);
;                           const float rstd = 1.0f / sqrtf(q * (1.0f / 128.0f) + EPS);
; #pragma unroll
;                           for (int d = 0; d < 4; ++d) o[d][r] *= rstd * gsub[d]; } }
	v_add_f32_e32 v60, v60, v80
	v_fmamk_f32 v60, v60, 0x3c000000, v189
	v_cmp_gt_f32_e32 vcc, s2, v60
	v_mul_f32_e32 v80, 0x4f800000, v60
	s_nop 0
	v_cndmask_b32_e32 v60, v60, v80, vcc
	v_sqrt_f32_e32 v80, v60
	s_nop 0
	v_add_u32_e32 v82, -1, v80
	v_fma_f32 v83, -v82, v80, v60
	v_cmp_ge_f32_e64 s[0:1], 0, v83
	v_add_u32_e32 v83, 1, v80
	s_nop 0
	v_cndmask_b32_e64 v82, v80, v82, s[0:1]
	v_fma_f32 v80, -v83, v80, v60
	v_cmp_lt_f32_e64 s[0:1], 0, v80
	s_nop 1
	v_cndmask_b32_e64 v80, v82, v83, s[0:1]
	v_mul_f32_e32 v82, 0x37800000, v80
	v_cndmask_b32_e32 v80, v80, v82, vcc
	v_cmp_class_f32_e32 vcc, v60, v190
	s_nop 1
	v_cndmask_b32_e32 v60, v80, v60, vcc
	v_div_scale_f32 v80, s[0:1], v60, v60, 1.0
	v_rcp_f32_e32 v82, v80
	s_nop 0
	v_fma_f32 v83, -v80, v82, 1.0
	v_fmac_f32_e32 v82, v83, v82
	v_div_scale_f32 v83, vcc, 1.0, v60, 1.0
	v_mul_f32_e32 v84, v83, v82
	v_fma_f32 v85, -v80, v84, v83
	v_fmac_f32_e32 v84, v85, v82
	v_fma_f32 v80, -v80, v84, v83
	v_div_fmas_f32 v80, v80, v82, v84
	v_div_fixup_f32 v80, v80, v60, 1.0
	v_mul_f32_e32 v60, v80, v0
	v_mul_f32_e32 v58, v60, v58
	v_mul_f32_e32 v60, v80, v4
	v_mul_f32_e32 v59, v60, v59
	v_mul_f32_e32 v60, v80, v5
	v_mul_f32_e32 v60, v60, v61
	v_mul_f32_e32 v61, v80, v6
	ds_bpermute_b32 v80, v162, v68
	v_mul_f32_e32 v61, v61, v81
	s_waitcnt lgkmcnt(0)
	v_add_f32_e32 v68, v68, v80
	ds_bpermute_b32 v80, v178, v68
	s_waitcnt lgkmcnt(0)
	v_add_f32_e32 v68, v68, v80
	ds_bpermute_b32 v80, v179, v68
	s_waitcnt lgkmcnt(0)
	v_add_f32_e32 v68, v68, v80
	ds_bpermute_b32 v80, v180, v68
	s_waitcnt lgkmcnt(0)
	v_add_f32_e32 v68, v68, v80
	ds_bpermute_b32 v80, v187, v68
	s_waitcnt lgkmcnt(0)
	v_add_f32_e32 v68, v68, v80
	v_fmamk_f32 v68, v68, 0x3c000000, v189
	v_cmp_gt_f32_e32 vcc, s2, v68
	v_mul_f32_e32 v80, 0x4f800000, v68
	s_nop 0
	v_cndmask_b32_e32 v68, v68, v80, vcc
	v_sqrt_f32_e32 v80, v68
	s_nop 0
	v_add_u32_e32 v81, -1, v80
	v_fma_f32 v82, -v81, v80, v68
	v_cmp_ge_f32_e64 s[0:1], 0, v82
	v_add_u32_e32 v82, 1, v80
	s_nop 0
	v_cndmask_b32_e64 v81, v80, v81, s[0:1]
	v_fma_f32 v80, -v82, v80, v68
	v_cmp_lt_f32_e64 s[0:1], 0, v80
	s_nop 1
	v_cndmask_b32_e64 v80, v81, v82, s[0:1]
	v_mul_f32_e32 v81, 0x37800000, v80
	v_cndmask_b32_e32 v80, v80, v81, vcc
	v_cmp_class_f32_e32 vcc, v68, v190
	s_nop 1
	v_cndmask_b32_e32 v68, v80, v68, vcc
	v_div_scale_f32 v80, s[0:1], v68, v68, 1.0
	v_rcp_f32_e32 v81, v80
	s_nop 0
	v_fma_f32 v82, -v80, v81, 1.0
	v_fmac_f32_e32 v81, v82, v81
	v_div_scale_f32 v82, vcc, 1.0, v68, 1.0
	v_mul_f32_e32 v83, v82, v81
	v_fma_f32 v84, -v80, v83, v82
	v_fmac_f32_e32 v83, v84, v81
	v_fma_f32 v80, -v80, v83, v82
	v_div_fmas_f32 v80, v80, v81, v83
	v_div_fixup_f32 v80, v80, v68, 1.0
	v_mul_f32_e32 v68, v80, v0
	v_mul_f32_e32 v67, v68, v67
	v_mul_f32_e32 v68, v80, v4
	v_mul_f32_e32 v68, v68, v69
	v_mul_f32_e32 v69, v80, v5
	v_mul_f32_e32 v69, v69, v70
	v_mul_f32_e32 v70, v80, v6
	v_mul_f32_e32 v70, v70, v79
	ds_bpermute_b32 v79, v162, v74
	s_waitcnt lgkmcnt(0)
	v_add_f32_e32 v74, v74, v79
	ds_bpermute_b32 v79, v178, v74
	s_waitcnt lgkmcnt(0)
	v_add_f32_e32 v74, v74, v79
	ds_bpermute_b32 v79, v179, v74
	s_waitcnt lgkmcnt(0)
	v_add_f32_e32 v74, v74, v79
	ds_bpermute_b32 v79, v180, v74
	s_waitcnt lgkmcnt(0)
	v_add_f32_e32 v74, v74, v79
	ds_bpermute_b32 v79, v187, v74
	s_waitcnt lgkmcnt(0)
	v_add_f32_e32 v74, v74, v79
	v_fmamk_f32 v74, v74, 0x3c000000, v189
	v_cmp_gt_f32_e32 vcc, s2, v74
	v_mul_f32_e32 v79, 0x4f800000, v74
	s_nop 0
	v_cndmask_b32_e32 v74, v74, v79, vcc
	v_sqrt_f32_e32 v79, v74
	s_nop 0
	v_add_u32_e32 v80, -1, v79
	v_fma_f32 v81, -v80, v79, v74
	v_cmp_ge_f32_e64 s[0:1], 0, v81
	v_add_u32_e32 v81, 1, v79
	s_nop 0
	v_cndmask_b32_e64 v80, v79, v80, s[0:1]
	v_fma_f32 v79, -v81, v79, v74
	v_cmp_lt_f32_e64 s[0:1], 0, v79
	s_nop 1
	v_cndmask_b32_e64 v79, v80, v81, s[0:1]
	v_mul_f32_e32 v80, 0x37800000, v79
	v_cndmask_b32_e32 v79, v79, v80, vcc
	v_cmp_class_f32_e32 vcc, v74, v190
	s_nop 1
	v_cndmask_b32_e32 v74, v79, v74, vcc
	v_div_scale_f32 v79, s[0:1], v74, v74, 1.0
	v_rcp_f32_e32 v80, v79
	s_nop 0
	v_fma_f32 v81, -v79, v80, 1.0
	v_fmac_f32_e32 v80, v81, v80
	v_div_scale_f32 v81, vcc, 1.0, v74, 1.0
	v_mul_f32_e32 v82, v81, v80
	v_fma_f32 v83, -v79, v82, v81
	v_fmac_f32_e32 v82, v83, v80
	v_fma_f32 v79, -v79, v82, v81
	v_div_fmas_f32 v79, v79, v80, v82
	v_div_fixup_f32 v79, v79, v74, 1.0
	v_mul_f32_e32 v74, v79, v0
	v_mul_f32_e32 v64, v74, v64
	v_mul_f32_e32 v74, v79, v4
	v_mul_f32_e32 v72, v74, v72
	v_mul_f32_e32 v74, v79, v5
	v_mul_f32_e32 v74, v74, v76
	v_mul_f32_e32 v76, v79, v6
	v_mul_f32_e32 v76, v76, v78
	ds_bpermute_b32 v78, v162, v55
	s_waitcnt lgkmcnt(0)
	v_add_f32_e32 v55, v55, v78
	ds_bpermute_b32 v78, v178, v55
	s_waitcnt lgkmcnt(0)
	v_add_f32_e32 v55, v55, v78
	ds_bpermute_b32 v78, v179, v55
	s_waitcnt lgkmcnt(0)
	v_add_f32_e32 v55, v55, v78
	ds_bpermute_b32 v78, v180, v55
	s_waitcnt lgkmcnt(0)
	v_add_f32_e32 v55, v55, v78
	ds_bpermute_b32 v78, v187, v55
	s_waitcnt lgkmcnt(0)
	v_add_f32_e32 v55, v55, v78
	v_fmamk_f32 v55, v55, 0x3c000000, v189
	v_cmp_gt_f32_e32 vcc, s2, v55
	v_mul_f32_e32 v78, 0x4f800000, v55
	s_nop 0
	v_cndmask_b32_e32 v55, v55, v78, vcc
	v_sqrt_f32_e32 v78, v55
	s_nop 0
	v_add_u32_e32 v79, -1, v78
	v_fma_f32 v80, -v79, v78, v55
	v_cmp_ge_f32_e64 s[0:1], 0, v80
	v_add_u32_e32 v80, 1, v78
	s_nop 0
	v_cndmask_b32_e64 v79, v78, v79, s[0:1]
	v_fma_f32 v78, -v80, v78, v55
	v_cmp_lt_f32_e64 s[0:1], 0, v78
	s_nop 1
	v_cndmask_b32_e64 v78, v79, v80, s[0:1]
	v_mul_f32_e32 v79, 0x37800000, v78
	v_cndmask_b32_e32 v78, v78, v79, vcc
	v_cmp_class_f32_e32 vcc, v55, v190
	s_nop 1
	v_cndmask_b32_e32 v55, v78, v55, vcc
	v_div_scale_f32 v78, s[0:1], v55, v55, 1.0
	v_rcp_f32_e32 v79, v78
	s_nop 0
	v_fma_f32 v80, -v78, v79, 1.0
	v_fmac_f32_e32 v79, v80, v79
	v_div_scale_f32 v80, vcc, 1.0, v55, 1.0
	v_mul_f32_e32 v81, v80, v79
	v_fma_f32 v82, -v78, v81, v80
	v_fmac_f32_e32 v81, v82, v79
	v_fma_f32 v78, -v78, v81, v80
	v_div_fmas_f32 v78, v78, v79, v81
	v_div_fixup_f32 v78, v78, v55, 1.0
	v_mul_f32_e32 v55, v78, v0
	v_mul_f32_e32 v54, v55, v54
	v_mul_f32_e32 v55, v78, v4
	v_mul_f32_e32 v55, v55, v63
	v_mul_f32_e32 v63, v78, v5
	v_mul_f32_e32 v63, v63, v73
	v_mul_f32_e32 v73, v78, v6
	v_mul_f32_e32 v73, v73, v77
	ds_bpermute_b32 v77, v162, v65
	s_waitcnt lgkmcnt(0)
; __global__ void __launch_bounds__(NTHR) mega_fwd(Params p) {
;     ...
;                       for (int r = 0; r < 16; ++r) { float q = ss[r]; q += __shfl_xor(q, 1); q += __shfl_xor(q, 2); q += __shfl_xor(q, 4); q += __shfl_xor(q, 8); q += __shfl_xor(q, 16);
;                           const float rstd = 1.0f / sqrtf(q * (1.0f / 128.0f) + EPS);
; #pragma unroll
;                           for (int d = 0; d < 4; ++d) o[d][r] *= rstd * gsub[d]; } }
	v_add_f32_e32 v65, v65, v77
	ds_bpermute_b32 v77, v178, v65
	s_waitcnt lgkmcnt(0)
	v_add_f32_e32 v65, v65, v77
	ds_bpermute_b32 v77, v179, v65
	s_waitcnt lgkmcnt(0)
	v_add_f32_e32 v65, v65, v77
	ds_bpermute_b32 v77, v180, v65
	s_waitcnt lgkmcnt(0)
	v_add_f32_e32 v65, v65, v77
	ds_bpermute_b32 v77, v187, v65
	s_waitcnt lgkmcnt(0)
	v_add_f32_e32 v65, v65, v77
	v_fmamk_f32 v65, v65, 0x3c000000, v189
	v_cmp_gt_f32_e32 vcc, s2, v65
	v_mul_f32_e32 v77, 0x4f800000, v65
	s_nop 0
	v_cndmask_b32_e32 v65, v65, v77, vcc
	v_sqrt_f32_e32 v77, v65
	s_nop 0
	v_add_u32_e32 v78, -1, v77
	v_fma_f32 v79, -v78, v77, v65
	v_cmp_ge_f32_e64 s[0:1], 0, v79
	v_add_u32_e32 v79, 1, v77
	s_nop 0
	v_cndmask_b32_e64 v78, v77, v78, s[0:1]
	v_fma_f32 v77, -v79, v77, v65
	v_cmp_lt_f32_e64 s[0:1], 0, v77
	s_nop 1
	v_cndmask_b32_e64 v77, v78, v79, s[0:1]
	v_mul_f32_e32 v78, 0x37800000, v77
	v_cndmask_b32_e32 v77, v77, v78, vcc
	v_cmp_class_f32_e32 vcc, v65, v190
	s_nop 1
	v_cndmask_b32_e32 v65, v77, v65, vcc
	v_div_scale_f32 v77, s[0:1], v65, v65, 1.0
	v_rcp_f32_e32 v78, v77
	s_nop 0
	v_fma_f32 v79, -v77, v78, 1.0
	v_fmac_f32_e32 v78, v79, v78
	v_div_scale_f32 v79, vcc, 1.0, v65, 1.0
	v_mul_f32_e32 v80, v79, v78
	v_fma_f32 v81, -v77, v80, v79
	v_fmac_f32_e32 v80, v81, v78
	v_fma_f32 v77, -v77, v80, v79
	v_div_fmas_f32 v77, v77, v78, v80
	v_div_fixup_f32 v77, v77, v65, 1.0
	v_mul_f32_e32 v65, v77, v0
	v_mul_f32_e32 v47, v65, v47
	v_mul_f32_e32 v65, v77, v4
	v_mul_f32_e32 v57, v65, v57
	v_mul_f32_e32 v65, v77, v5
	v_mul_f32_e32 v65, v65, v71
	v_mul_f32_e32 v71, v77, v6
	v_mul_f32_e32 v71, v71, v75
	ds_bpermute_b32 v75, v162, v44
	s_waitcnt lgkmcnt(0)
	v_add_f32_e32 v44, v44, v75
	ds_bpermute_b32 v75, v178, v44
	s_waitcnt lgkmcnt(0)
	v_add_f32_e32 v44, v44, v75
	ds_bpermute_b32 v75, v179, v44
	s_waitcnt lgkmcnt(0)
	v_add_f32_e32 v44, v44, v75
	ds_bpermute_b32 v75, v180, v44
	s_waitcnt lgkmcnt(0)
	v_add_f32_e32 v44, v44, v75
	ds_bpermute_b32 v75, v187, v44
	s_waitcnt lgkmcnt(0)
	v_add_f32_e32 v44, v44, v75
	v_fmamk_f32 v44, v44, 0x3c000000, v189
	v_cmp_gt_f32_e32 vcc, s2, v44
	v_mul_f32_e32 v75, 0x4f800000, v44
	s_nop 0
	v_cndmask_b32_e32 v44, v44, v75, vcc
	v_sqrt_f32_e32 v75, v44
	s_nop 0
	v_add_u32_e32 v77, -1, v75
	v_fma_f32 v78, -v77, v75, v44
	v_cmp_ge_f32_e64 s[0:1], 0, v78
	v_add_u32_e32 v78, 1, v75
	s_nop 0
	v_cndmask_b32_e64 v77, v75, v77, s[0:1]
	v_fma_f32 v75, -v78, v75, v44
	v_cmp_lt_f32_e64 s[0:1], 0, v75
	s_nop 1
	v_cndmask_b32_e64 v75, v77, v78, s[0:1]
	v_mul_f32_e32 v77, 0x37800000, v75
	v_cndmask_b32_e32 v75, v75, v77, vcc
	v_cmp_class_f32_e32 vcc, v44, v190
	s_nop 1
	v_cndmask_b32_e32 v44, v75, v44, vcc
	v_div_scale_f32 v75, s[0:1], v44, v44, 1.0
	v_rcp_f32_e32 v77, v75
	s_nop 0
	v_fma_f32 v78, -v75, v77, 1.0
	v_fmac_f32_e32 v77, v78, v77
	v_div_scale_f32 v78, vcc, 1.0, v44, 1.0
	v_mul_f32_e32 v79, v78, v77
	v_fma_f32 v80, -v75, v79, v78
	v_fmac_f32_e32 v79, v80, v77
	v_fma_f32 v75, -v75, v79, v78
	v_div_fmas_f32 v75, v75, v77, v79
	v_div_fixup_f32 v75, v75, v44, 1.0
	v_mul_f32_e32 v44, v75, v0
	v_mul_f32_e32 v37, v44, v37
	v_mul_f32_e32 v44, v75, v4
	v_mul_f32_e32 v44, v44, v48
	v_mul_f32_e32 v48, v75, v5
	v_mul_f32_e32 v48, v48, v62
	v_mul_f32_e32 v62, v75, v6
	v_mul_f32_e32 v62, v62, v66
	ds_bpermute_b32 v66, v162, v45
	s_waitcnt lgkmcnt(0)
	v_add_f32_e32 v45, v45, v66
	ds_bpermute_b32 v66, v178, v45
	s_waitcnt lgkmcnt(0)
	v_add_f32_e32 v45, v45, v66
	ds_bpermute_b32 v66, v179, v45
	s_waitcnt lgkmcnt(0)
	v_add_f32_e32 v45, v45, v66
	ds_bpermute_b32 v66, v180, v45
	s_waitcnt lgkmcnt(0)
	v_add_f32_e32 v45, v45, v66
	ds_bpermute_b32 v66, v187, v45
	s_waitcnt lgkmcnt(0)
	v_add_f32_e32 v45, v45, v66
	v_fmamk_f32 v45, v45, 0x3c000000, v189
	v_cmp_gt_f32_e32 vcc, s2, v45
	v_mul_f32_e32 v66, 0x4f800000, v45
	s_nop 0
	v_cndmask_b32_e32 v45, v45, v66, vcc
	v_sqrt_f32_e32 v66, v45
	s_nop 0
	v_add_u32_e32 v75, -1, v66
	v_fma_f32 v77, -v75, v66, v45
	v_cmp_ge_f32_e64 s[0:1], 0, v77
	v_add_u32_e32 v77, 1, v66
	s_nop 0
	v_cndmask_b32_e64 v75, v66, v75, s[0:1]
	v_fma_f32 v66, -v77, v66, v45
	v_cmp_lt_f32_e64 s[0:1], 0, v66
	s_nop 1
	v_cndmask_b32_e64 v66, v75, v77, s[0:1]
	v_mul_f32_e32 v75, 0x37800000, v66
	v_cndmask_b32_e32 v66, v66, v75, vcc
	v_cmp_class_f32_e32 vcc, v45, v190
	s_nop 1
	v_cndmask_b32_e32 v45, v66, v45, vcc
	v_div_scale_f32 v66, s[0:1], v45, v45, 1.0
	v_rcp_f32_e32 v75, v66
	s_nop 0
	v_fma_f32 v77, -v66, v75, 1.0
	v_fmac_f32_e32 v75, v77, v75
	v_div_scale_f32 v77, vcc, 1.0, v45, 1.0
	v_mul_f32_e32 v78, v77, v75
	v_fma_f32 v79, -v66, v78, v77
	v_fmac_f32_e32 v78, v79, v75
	v_fma_f32 v66, -v66, v78, v77
	v_div_fmas_f32 v66, v66, v75, v78
	v_div_fixup_f32 v66, v66, v45, 1.0
	v_mul_f32_e32 v45, v66, v0
	v_mul_f32_e32 v29, v45, v29
	v_mul_f32_e32 v45, v66, v4
	v_mul_f32_e32 v38, v45, v38
	v_mul_f32_e32 v45, v66, v5
	v_mul_f32_e32 v45, v45, v53
	v_mul_f32_e32 v53, v66, v6
	v_mul_f32_e32 v53, v53, v56
	ds_bpermute_b32 v56, v162, v26
	s_waitcnt lgkmcnt(0)
	v_add_f32_e32 v26, v26, v56
	ds_bpermute_b32 v56, v178, v26
	s_waitcnt lgkmcnt(0)
	v_add_f32_e32 v26, v26, v56
	ds_bpermute_b32 v56, v179, v26
	s_waitcnt lgkmcnt(0)
	v_add_f32_e32 v26, v26, v56
	ds_bpermute_b32 v56, v180, v26
	s_waitcnt lgkmcnt(0)
	v_add_f32_e32 v26, v26, v56
	ds_bpermute_b32 v56, v187, v26
	s_waitcnt lgkmcnt(0)
; __global__ void __launch_bounds__(NTHR) mega_fwd(Params p) {
;     ...
;                       for (int r = 0; r < 16; ++r) { float q = ss[r]; q += __shfl_xor(q, 1); q += __shfl_xor(q, 2); q += __shfl_xor(q, 4); q += __shfl_xor(q, 8); q += __shfl_xor(q, 16);
;                           const float rstd = 1.0f / sqrtf(q * (1.0f / 128.0f) + EPS);
; #pragma unroll
;                           for (int d = 0; d < 4; ++d) o[d][r] *= rstd * gsub[d]; } }
	v_add_f32_e32 v26, v26, v56
	v_fmamk_f32 v26, v26, 0x3c000000, v189
	v_cmp_gt_f32_e32 vcc, s2, v26
	v_mul_f32_e32 v56, 0x4f800000, v26
	s_nop 0
	v_cndmask_b32_e32 v26, v26, v56, vcc
	v_sqrt_f32_e32 v56, v26
	s_nop 0
	v_add_u32_e32 v66, -1, v56
	v_fma_f32 v75, -v66, v56, v26
	v_cmp_ge_f32_e64 s[0:1], 0, v75
	v_add_u32_e32 v75, 1, v56
	s_nop 0
	v_cndmask_b32_e64 v66, v56, v66, s[0:1]
	v_fma_f32 v56, -v75, v56, v26
	v_cmp_lt_f32_e64 s[0:1], 0, v56
	s_nop 1
	v_cndmask_b32_e64 v56, v66, v75, s[0:1]
	v_mul_f32_e32 v66, 0x37800000, v56
	v_cndmask_b32_e32 v56, v56, v66, vcc
	v_cmp_class_f32_e32 vcc, v26, v190
	s_nop 1
	v_cndmask_b32_e32 v26, v56, v26, vcc
	v_div_scale_f32 v56, s[0:1], v26, v26, 1.0
	v_rcp_f32_e32 v66, v56
	s_nop 0
	v_fma_f32 v75, -v56, v66, 1.0
	v_fmac_f32_e32 v66, v75, v66
	v_div_scale_f32 v75, vcc, 1.0, v26, 1.0
	v_mul_f32_e32 v77, v75, v66
	v_fma_f32 v78, -v56, v77, v75
	v_fmac_f32_e32 v77, v78, v66
	v_fma_f32 v56, -v56, v77, v75
	v_div_fmas_f32 v56, v56, v66, v77
	v_div_fixup_f32 v56, v56, v26, 1.0
	v_mul_f32_e32 v26, v56, v0
	v_mul_f32_e32 v19, v26, v19
	v_mul_f32_e32 v26, v56, v4
	v_mul_f32_e32 v26, v26, v30
	v_mul_f32_e32 v30, v56, v5
	v_mul_f32_e32 v30, v30, v43
	v_mul_f32_e32 v43, v56, v6
	v_mul_f32_e32 v43, v43, v46
	ds_bpermute_b32 v46, v162, v27
	s_waitcnt lgkmcnt(0)
	v_add_f32_e32 v27, v27, v46
	ds_bpermute_b32 v46, v178, v27
	s_waitcnt lgkmcnt(0)
	v_add_f32_e32 v27, v27, v46
	ds_bpermute_b32 v46, v179, v27
	s_waitcnt lgkmcnt(0)
	v_add_f32_e32 v27, v27, v46
	ds_bpermute_b32 v46, v180, v27
	s_waitcnt lgkmcnt(0)
	v_add_f32_e32 v27, v27, v46
	ds_bpermute_b32 v46, v187, v27
	s_waitcnt lgkmcnt(0)
	v_add_f32_e32 v27, v27, v46
	v_fmamk_f32 v27, v27, 0x3c000000, v189
	v_cmp_gt_f32_e32 vcc, s2, v27
	v_mul_f32_e32 v46, 0x4f800000, v27
	s_nop 0
	v_cndmask_b32_e32 v27, v27, v46, vcc
	v_sqrt_f32_e32 v46, v27
	s_nop 0
	v_add_u32_e32 v56, -1, v46
	v_fma_f32 v66, -v56, v46, v27
	v_cmp_ge_f32_e64 s[0:1], 0, v66
	v_add_u32_e32 v66, 1, v46
	s_nop 0
	v_cndmask_b32_e64 v56, v46, v56, s[0:1]
	v_fma_f32 v46, -v66, v46, v27
	v_cmp_lt_f32_e64 s[0:1], 0, v46
	s_nop 1
	v_cndmask_b32_e64 v46, v56, v66, s[0:1]
	v_mul_f32_e32 v56, 0x37800000, v46
	v_cndmask_b32_e32 v46, v46, v56, vcc
	v_cmp_class_f32_e32 vcc, v27, v190
	s_nop 1
	v_cndmask_b32_e32 v27, v46, v27, vcc
	v_div_scale_f32 v46, s[0:1], v27, v27, 1.0
	v_rcp_f32_e32 v56, v46
	s_nop 0
	v_fma_f32 v66, -v46, v56, 1.0
	v_fmac_f32_e32 v56, v66, v56
	v_div_scale_f32 v66, vcc, 1.0, v27, 1.0
	v_mul_f32_e32 v75, v66, v56
	v_fma_f32 v77, -v46, v75, v66
	v_fmac_f32_e32 v75, v77, v56
	v_fma_f32 v46, -v46, v75, v66
	v_div_fmas_f32 v46, v46, v56, v75
	v_div_fixup_f32 v46, v46, v27, 1.0
	v_mul_f32_e32 v27, v46, v0
	v_mul_f32_e32 v15, v27, v15
	v_mul_f32_e32 v27, v46, v4
	v_mul_f32_e32 v21, v27, v21
	v_mul_f32_e32 v27, v46, v5
	v_mul_f32_e32 v27, v27, v35
	v_mul_f32_e32 v35, v46, v6
	v_mul_f32_e32 v35, v35, v36
	ds_bpermute_b32 v36, v162, v12
	s_waitcnt lgkmcnt(0)
	v_add_f32_e32 v12, v12, v36
	ds_bpermute_b32 v36, v178, v12
	s_waitcnt lgkmcnt(0)
	v_add_f32_e32 v12, v12, v36
	ds_bpermute_b32 v36, v179, v12
	s_waitcnt lgkmcnt(0)
	v_add_f32_e32 v12, v12, v36
	ds_bpermute_b32 v36, v180, v12
	s_waitcnt lgkmcnt(0)
	v_add_f32_e32 v12, v12, v36
	ds_bpermute_b32 v36, v187, v12
	s_waitcnt lgkmcnt(0)
	v_add_f32_e32 v12, v12, v36
	v_fmamk_f32 v12, v12, 0x3c000000, v189
	v_cmp_gt_f32_e32 vcc, s2, v12
	v_mul_f32_e32 v36, 0x4f800000, v12
	s_nop 0
	v_cndmask_b32_e32 v12, v12, v36, vcc
	v_sqrt_f32_e32 v36, v12
	s_nop 0
	v_add_u32_e32 v46, -1, v36
	v_fma_f32 v56, -v46, v36, v12
	v_cmp_ge_f32_e64 s[0:1], 0, v56
	v_add_u32_e32 v56, 1, v36
	s_nop 0
	v_cndmask_b32_e64 v46, v36, v46, s[0:1]
	v_fma_f32 v36, -v56, v36, v12
	v_cmp_lt_f32_e64 s[0:1], 0, v36
	s_nop 1
	v_cndmask_b32_e64 v36, v46, v56, s[0:1]
	v_mul_f32_e32 v46, 0x37800000, v36
	v_cndmask_b32_e32 v36, v36, v46, vcc
	v_cmp_class_f32_e32 vcc, v12, v190
	s_nop 1
	v_cndmask_b32_e32 v12, v36, v12, vcc
	v_div_scale_f32 v36, s[0:1], v12, v12, 1.0
	v_rcp_f32_e32 v46, v36
	s_nop 0
	v_fma_f32 v56, -v36, v46, 1.0
	v_fmac_f32_e32 v46, v56, v46
	v_div_scale_f32 v56, vcc, 1.0, v12, 1.0
	v_mul_f32_e32 v66, v56, v46
	v_fma_f32 v75, -v36, v66, v56
	v_fmac_f32_e32 v66, v75, v46
	v_fma_f32 v36, -v36, v66, v56
	v_div_fmas_f32 v36, v36, v46, v66
	v_div_fixup_f32 v36, v36, v12, 1.0
	v_mul_f32_e32 v12, v36, v0
	v_mul_f32_e32 v9, v12, v9
	v_mul_f32_e32 v12, v36, v4
	v_mul_f32_e32 v12, v12, v16
	v_mul_f32_e32 v16, v36, v5
	v_mul_f32_e32 v16, v16, v25
	v_mul_f32_e32 v25, v36, v6
	v_mul_f32_e32 v25, v25, v28
	ds_bpermute_b32 v28, v162, v13
	s_waitcnt lgkmcnt(0)
	v_add_f32_e32 v13, v13, v28
	ds_bpermute_b32 v28, v178, v13
	s_waitcnt lgkmcnt(0)
	v_add_f32_e32 v13, v13, v28
	ds_bpermute_b32 v28, v179, v13
	s_waitcnt lgkmcnt(0)
	v_add_f32_e32 v13, v13, v28
	ds_bpermute_b32 v28, v180, v13
	s_waitcnt lgkmcnt(0)
	v_add_f32_e32 v13, v13, v28
	ds_bpermute_b32 v28, v187, v13
	s_waitcnt lgkmcnt(0)
	v_add_f32_e32 v13, v13, v28
	v_fmamk_f32 v13, v13, 0x3c000000, v189
	v_cmp_gt_f32_e32 vcc, s2, v13
	v_mul_f32_e32 v28, 0x4f800000, v13
	s_nop 0
	v_cndmask_b32_e32 v13, v13, v28, vcc
	v_sqrt_f32_e32 v28, v13
	s_nop 0
	v_add_u32_e32 v36, -1, v28
	v_fma_f32 v46, -v36, v28, v13
	v_cmp_ge_f32_e64 s[0:1], 0, v46
	v_add_u32_e32 v46, 1, v28
	s_nop 0
	v_cndmask_b32_e64 v36, v28, v36, s[0:1]
	v_fma_f32 v28, -v46, v28, v13
	v_cmp_lt_f32_e64 s[0:1], 0, v28
	s_nop 1
	v_cndmask_b32_e64 v28, v36, v46, s[0:1]
	v_mul_f32_e32 v36, 0x37800000, v28
	v_cndmask_b32_e32 v28, v28, v36, vcc
	v_cmp_class_f32_e32 vcc, v13, v190
	s_nop 1
	v_cndmask_b32_e32 v13, v28, v13, vcc
	v_div_scale_f32 v28, s[0:1], v13, v13, 1.0
	v_rcp_f32_e32 v36, v28
	s_nop 0
	v_fma_f32 v46, -v28, v36, 1.0
	v_fmac_f32_e32 v36, v46, v36
	v_div_scale_f32 v46, vcc, 1.0, v13, 1.0
	v_mul_f32_e32 v56, v46, v36
	v_fma_f32 v66, -v28, v56, v46
	v_fmac_f32_e32 v56, v66, v36
	v_fma_f32 v28, -v28, v56, v46
	v_div_fmas_f32 v28, v28, v36, v56
	v_div_fixup_f32 v13, v28, v13, 1.0
	v_mul_f32_e32 v28, v13, v0
	v_mul_f32_e32 v7, v28, v7
	v_mul_f32_e32 v28, v13, v4
	v_mul_f32_e32 v11, v28, v11
	v_mul_f32_e32 v28, v13, v5
	v_mul_f32_e32 v13, v13, v6
	v_mul_f32_e32 v13, v13, v18
	ds_bpermute_b32 v18, v162, v3
	v_mul_f32_e32 v17, v28, v17
	s_waitcnt lgkmcnt(0)
; __device__ __forceinline__ int opaque_tid() { int t = threadIdx.x; asm volatile("" : "+v"(t)); return t; }
; __device__ __forceinline__ void store_o_bf16(const att::f32x16 (&o)[4], bf16* base  , unsigned char* lds) {
;     const int tid = opaque_tid(), lane = tid & 63, wave = __builtin_amdgcn_readfirstlane(tid >> 6), r32 = lane & 31, hi = lane >> 5;
;     __syncthreads();
;     float* T = (float*)(lds + wave * 16896);
; __global__ void __launch_bounds__(NTHR) mega_fwd(Params p) {
;     ...
;                       for (int r = 0; r < 16; ++r) { float q = ss[r]; q += __shfl_xor(q, 1); q += __shfl_xor(q, 2); q += __shfl_xor(q, 4); q += __shfl_xor(q, 8); q += __shfl_xor(q, 16);
;                           const float rstd = 1.0f / sqrtf(q * (1.0f / 128.0f) + EPS);
; #pragma unroll
;                           for (int d = 0; d < 4; ++d) o[d][r] *= rstd * gsub[d]; } }
	v_add_f32_e32 v3, v3, v18
	ds_bpermute_b32 v18, v178, v3
	s_waitcnt lgkmcnt(0)
	v_add_f32_e32 v3, v3, v18
	ds_bpermute_b32 v18, v179, v3
	s_waitcnt lgkmcnt(0)
	v_add_f32_e32 v3, v3, v18
	ds_bpermute_b32 v18, v180, v3
	s_waitcnt lgkmcnt(0)
	v_add_f32_e32 v3, v3, v18
	ds_bpermute_b32 v18, v187, v3
	s_waitcnt lgkmcnt(0)
	v_add_f32_e32 v3, v3, v18
	v_fmamk_f32 v3, v3, 0x3c000000, v189
	v_cmp_gt_f32_e32 vcc, s2, v3
	v_mul_f32_e32 v18, 0x4f800000, v3
	v_readlane_b32 s2, v253, 7
	v_cndmask_b32_e32 v3, v3, v18, vcc
	v_sqrt_f32_e32 v18, v3
	v_readlane_b32 s3, v253, 8
	v_add_u32_e32 v28, -1, v18
	v_fma_f32 v36, -v28, v18, v3
	v_cmp_ge_f32_e64 s[0:1], 0, v36
	v_add_u32_e32 v36, 1, v18
	s_nop 0
	v_cndmask_b32_e64 v28, v18, v28, s[0:1]
	v_fma_f32 v18, -v36, v18, v3
	v_cmp_lt_f32_e64 s[0:1], 0, v18
	s_nop 1
	v_cndmask_b32_e64 v18, v28, v36, s[0:1]
	v_mul_f32_e32 v28, 0x37800000, v18
	v_cndmask_b32_e32 v18, v18, v28, vcc
	v_cmp_class_f32_e32 vcc, v3, v190
	s_nop 1
	v_cndmask_b32_e32 v3, v18, v3, vcc
	v_div_scale_f32 v18, s[0:1], v3, v3, 1.0
	v_rcp_f32_e32 v28, v18
	s_nop 0
	v_fma_f32 v36, -v18, v28, 1.0
	v_fmac_f32_e32 v28, v36, v28
	v_div_scale_f32 v36, vcc, 1.0, v3, 1.0
	v_mul_f32_e32 v46, v36, v28
	v_fma_f32 v56, -v18, v46, v36
	v_fmac_f32_e32 v46, v56, v28
	v_fma_f32 v18, -v18, v46, v36
	v_div_fmas_f32 v18, v18, v28, v46
	v_div_fixup_f32 v3, v18, v3, 1.0
	v_mul_f32_e32 v0, v3, v0
	v_mul_f32_e32 v0, v0, v2
	v_mul_f32_e32 v2, v3, v4
	v_mul_f32_e32 v4, v3, v5
	v_mov_b32_e32 v5, v188
	v_mul_f32_e32 v2, v2, v8
	v_readfirstlane_b32 s0, v5
	s_ashr_i32 s0, s0, 6
	v_lshrrev_b32_e32 v8, 3, v5
	v_mul_f32_e32 v3, v3, v6
	v_and_b32_e32 v6, 31, v5
	s_mul_i32 s1, s0, 0x4200
	v_and_b32_e32 v8, 4, v8
	s_add_i32 s1, s1, 0
	v_lshlrev_b32_e32 v6, 2, v6
	v_mul_u32_u24_e32 v8, 0x210, v8
	v_add3_u32 v6, s1, v6, v8
	v_add_u32_e32 v8, 0x400, v6
	s_barrier
; __device__ __forceinline__ int crow(int r, int hi) { return (r & 3) + 8 * (r >> 2) + 4 * hi; }
; __device__ __forceinline__ unsigned cvtpk(float lo, float hi) { unsigned r; asm volatile("v_cvt_pk_bf16_f32 %0, %1, %2" : "=v"(r) : "v"(lo), "v"(hi)); return r; }
; __device__ __forceinline__ void store_o_bf16(const att::f32x16 (&o)[4], bf16* base  , unsigned char* lds) {
;     ...
; #pragma unroll
;     for (int r = 0; r < 16; ++r) { float* tp = T + att::crow(r, hi) * 132 + r32;
; #pragma unroll
;         for (int d = 0; d < 4; ++d) tp[32 * d] = o[d][r]; }
; #pragma unroll
;     for (int k = 0; k < 8; ++k) { const int chunk = k * 64 + lane, row = chunk >> 4, c8 = chunk & 15;
;         const f32x4 a = *(const f32x4*)(T + row * 132 + c8 * 8), b = *(const f32x4*)(T + row * 132 + c8 * 8 + 4);
;         v4u w; w.x = att::cvtpk(a.x, a.y); w.y = att::cvtpk(a.z, a.w); w.z = att::cvtpk(b.x, b.y); w.w = att::cvtpk(b.z, b.w);
;         *(v4u*)(base + (size_t)(wave * 32 + row) * DM + c8 * 8) = w; }
	ds_write2_b32 v6, v20, v22 offset1:32
	ds_write2_b32 v6, v23, v24 offset0:64 offset1:96
	ds_write2_b32 v6, v31, v32 offset0:132 offset1:164
	ds_write2_b32 v6, v33, v34 offset0:196 offset1:228
	ds_write2_b32 v8, v39, v40 offset0:8 offset1:40
	ds_write2_b32 v8, v41, v42 offset0:72 offset1:104
	ds_write2_b32 v8, v49, v50 offset0:140 offset1:172
	ds_write2_b32 v8, v51, v52 offset0:204 offset1:236
	v_add_u32_e32 v8, 0x1000, v6
	ds_write2_b32 v8, v58, v59 offset0:32 offset1:64
	ds_write2_b32 v8, v60, v61 offset0:96 offset1:128
	ds_write2_b32 v8, v67, v68 offset0:164 offset1:196
	v_add_u32_e32 v8, 0x1200, v6
	ds_write2_b32 v8, v69, v70 offset0:100 offset1:132
	v_add_u32_e32 v8, 0x1400, v6
	ds_write2_b32 v8, v64, v72 offset0:40 offset1:72
	ds_write2_b32 v8, v74, v76 offset0:104 offset1:136
	ds_write2_b32 v8, v54, v55 offset0:172 offset1:204
	v_add_u32_e32 v8, 0x1600, v6
	ds_write2_b32 v8, v63, v73 offset0:108 offset1:140
	v_add_u32_e32 v8, 0x2000, v6
	ds_write2_b32 v8, v47, v57 offset0:64 offset1:96
	ds_write2_b32 v8, v65, v71 offset0:128 offset1:160
	ds_write2_b32 v8, v37, v44 offset0:196 offset1:228
	v_add_u32_e32 v8, 0x2400, v6
	ds_write2_b32 v8, v48, v62 offset0:4 offset1:36
	ds_write2_b32 v8, v29, v38 offset0:72 offset1:104
	ds_write2_b32 v8, v45, v53 offset0:136 offset1:168
	ds_write2_b32 v8, v19, v26 offset0:204 offset1:236
	v_add_u32_e32 v8, 0x2800, v6
	ds_write2_b32 v8, v30, v43 offset0:12 offset1:44
	v_add_u32_e32 v8, 0x3000, v6
	ds_write2_b32 v8, v15, v21 offset0:96 offset1:128
	ds_write2_b32 v8, v27, v35 offset0:160 offset1:192
	v_add_u32_e32 v8, 0x3200, v6
	ds_write2_b32 v8, v9, v12 offset0:100 offset1:132
	v_add_u32_e32 v8, 0x3400, v6
	ds_write2_b32 v8, v16, v25 offset0:36 offset1:68
	ds_write2_b32 v8, v7, v11 offset0:104 offset1:136
	ds_write2_b32 v8, v17, v13 offset0:168 offset1:200
	v_add_u32_e32 v7, 0x3600, v6
	v_mul_f32_e32 v4, v4, v10
	v_mul_f32_e32 v3, v3, v14
	ds_write2_b32 v7, v0, v2 offset0:108 offset1:140
	v_add_u32_e32 v0, 0x3800, v6
	ds_write2_b32 v0, v4, v3 offset0:44 offset1:76
	v_lshlrev_b32_e32 v0, 3, v5
	v_and_b32_e32 v0, 0x78, v0
	v_lshlrev_b32_e32 v2, 2, v0
	v_lshlrev_b32_e32 v0, 1, v0
	v_lshl_add_u64 v[6:7], s[2:3], 0, v[0:1]
	v_bfe_u32 v0, v5, 4, 2
	v_mul_u32_u24_e32 v3, 0x210, v0
	v_add3_u32 v14, s1, v2, v3
	ds_read_b128 v[2:5], v14
	ds_read_b128 v[8:11], v14 offset:16
	s_waitcnt lgkmcnt(1)
	v_cvt_pk_bf16_f32 v2, v2, v3
	v_cvt_pk_bf16_f32 v3, v4, v5
	s_waitcnt lgkmcnt(0)
	v_cvt_pk_bf16_f32 v4, v8, v9
	v_lshl_or_b32 v8, s0, 5, v0
	v_ashrrev_i32_e32 v9, 31, v8
	v_cvt_pk_bf16_f32 v5, v10, v11
	v_lshlrev_b64 v[10:11], 12, v[8:9]
	v_lshl_add_u64 v[10:11], v[6:7], 0, v[10:11]
	global_store_dwordx4 v[10:11], v[2:5], off
	ds_read_b128 v[2:5], v14 offset:2112
	ds_read_b128 v[10:13], v14 offset:2128
	s_waitcnt lgkmcnt(1)
	v_cvt_pk_bf16_f32 v2, v2, v3
	v_cvt_pk_bf16_f32 v3, v4, v5
	s_waitcnt lgkmcnt(0)
	v_cvt_pk_bf16_f32 v4, v10, v11
	v_or_b32_e32 v10, 4, v8
	v_ashrrev_i32_e32 v11, 31, v10
	v_lshlrev_b64 v[10:11], 12, v[10:11]
	v_lshl_add_u64 v[10:11], v[6:7], 0, v[10:11]
	v_cvt_pk_bf16_f32 v5, v12, v13
	global_store_dwordx4 v[10:11], v[2:5], off
	ds_read_b128 v[2:5], v14 offset:4224
	ds_read_b128 v[10:13], v14 offset:4240
	s_waitcnt lgkmcnt(1)
	v_cvt_pk_bf16_f32 v2, v2, v3
	v_cvt_pk_bf16_f32 v3, v4, v5
	s_waitcnt lgkmcnt(0)
	v_cvt_pk_bf16_f32 v4, v10, v11
	v_or_b32_e32 v10, 8, v8
	v_ashrrev_i32_e32 v11, 31, v10
	v_lshlrev_b64 v[10:11], 12, v[10:11]
	v_lshl_add_u64 v[10:11], v[6:7], 0, v[10:11]
	v_cvt_pk_bf16_f32 v5, v12, v13
	global_store_dwordx4 v[10:11], v[2:5], off
	ds_read_b128 v[2:5], v14 offset:6336
	ds_read_b128 v[10:13], v14 offset:6352
	s_waitcnt lgkmcnt(1)
	v_cvt_pk_bf16_f32 v2, v2, v3
	v_cvt_pk_bf16_f32 v3, v4, v5
	s_waitcnt lgkmcnt(0)
	v_cvt_pk_bf16_f32 v4, v10, v11
	v_or_b32_e32 v10, 12, v8
	v_ashrrev_i32_e32 v11, 31, v10
	v_lshlrev_b64 v[10:11], 12, v[10:11]
	v_lshl_add_u64 v[10:11], v[6:7], 0, v[10:11]
	v_cvt_pk_bf16_f32 v5, v12, v13
	global_store_dwordx4 v[10:11], v[2:5], off
	ds_read_b128 v[2:5], v14 offset:8448
	ds_read_b128 v[10:13], v14 offset:8464
	s_waitcnt lgkmcnt(1)
	v_cvt_pk_bf16_f32 v2, v2, v3
	v_cvt_pk_bf16_f32 v3, v4, v5
	s_waitcnt lgkmcnt(0)
	v_cvt_pk_bf16_f32 v4, v10, v11
	v_or_b32_e32 v10, 16, v8
	v_ashrrev_i32_e32 v11, 31, v10
	v_lshlrev_b64 v[10:11], 12, v[10:11]
	v_lshl_add_u64 v[10:11], v[6:7], 0, v[10:11]
	v_cvt_pk_bf16_f32 v5, v12, v13
	global_store_dwordx4 v[10:11], v[2:5], off
	ds_read_b128 v[2:5], v14 offset:10560
	ds_read_b128 v[10:13], v14 offset:10576
	s_waitcnt lgkmcnt(1)
	v_cvt_pk_bf16_f32 v2, v2, v3
	v_cvt_pk_bf16_f32 v3, v4, v5
	s_waitcnt lgkmcnt(0)
	v_cvt_pk_bf16_f32 v4, v10, v11
	v_or_b32_e32 v10, 20, v8
	v_ashrrev_i32_e32 v11, 31, v10
	v_lshlrev_b64 v[10:11], 12, v[10:11]
	v_lshl_add_u64 v[10:11], v[6:7], 0, v[10:11]
	v_cvt_pk_bf16_f32 v5, v12, v13
	global_store_dwordx4 v[10:11], v[2:5], off
	ds_read_b128 v[2:5], v14 offset:12672
	ds_read_b128 v[10:13], v14 offset:12688
	s_waitcnt lgkmcnt(1)
	v_cvt_pk_bf16_f32 v2, v2, v3
	v_cvt_pk_bf16_f32 v3, v4, v5
	s_waitcnt lgkmcnt(0)
	v_cvt_pk_bf16_f32 v4, v10, v11
	v_or_b32_e32 v10, 24, v8
	v_ashrrev_i32_e32 v11, 31, v10
	v_lshlrev_b64 v[10:11], 12, v[10:11]
	v_lshl_add_u64 v[10:11], v[6:7], 0, v[10:11]
	v_cvt_pk_bf16_f32 v5, v12, v13
	global_store_dwordx4 v[10:11], v[2:5], off
	ds_read_b128 v[2:5], v14 offset:14784
	ds_read_b128 v[10:13], v14 offset:14800
	v_or_b32_e32 v8, 28, v8
	s_waitcnt lgkmcnt(1)
	v_cvt_pk_bf16_f32 v2, v2, v3
	v_cvt_pk_bf16_f32 v3, v4, v5
	s_waitcnt lgkmcnt(0)
	v_cvt_pk_bf16_f32 v4, v10, v11
	v_cvt_pk_bf16_f32 v5, v12, v13

; #define SBAR() __builtin_amdgcn_sched_barrier(0)
; #define SLOAD(i, k0) do { sr_[i].vs0 = *reinterpret_cast<const bf16x8*>(&Vh[(long)((k0) + sr) * LDP + sc]); sr_[i].vs1 = *reinterpret_cast<const bf16x8*>(&Vh[(long)((k0) + 32 + sr) * LDP + sc]); \
;     sr_[i].ks0 = *reinterpret_cast<const bf16x8*>(&Kh[(long)((k0) + ksr) * LDP + ksc]); if (DK == 128) sr_[i].ks1 = *reinterpret_cast<const bf16x8*>(&Kh[(long)((k0) + 32 + ksr) * LDP + ksc]); } while (0)
; #define HOOK(P0, P1, j) do { if (NA) na_hook(P0, P1, krow0 + (j), q_row, q_col, win_r, win_c, rpb, inv_scale, hi); } while (0)
; __device__ __forceinline__ void finishSM(f32x16& p0, f32x16& p1, float alpha, float& l_reg, bf16x8& pa0, bf16x8& pa1, bf16x8& pa2, bf16x8& pa3) {
; #pragma unroll
;   for (int r = 0; r < 16; ++r) p1[r] = __builtin_amdgcn_exp2f(p1[r]);
;   float ps = 0;
; #pragma unroll
;   for (int r = 0; r < 16; ++r) ps += p0[r];
; #pragma unroll
;   for (int r = 0; r < 16; ++r) ps += p1[r];
;   { auto rr = __builtin_amdgcn_permlane32_swap(__float_as_uint(ps), __float_as_uint(ps), false, false);
;     ps = __uint_as_float(rr[0]) + __uint_as_float(rr[1]); }
;   l_reg = l_reg * alpha + ps;
;     ...
;   PK4(p0, 0, pa0); PK4(p0, 8, pa1); PK4(p1, 0, pa2); PK4(p1, 8, pa3);
;     ...
; }
; template <int DK, bool NA, bool QL, int SD> ...
;     ...
;   for (int j = 1; j + 1 < NT; j += 2) {
;     SBAR(); qkt<DK, QL>(pB0, pB1, (bf16*)((char*)K_lds + SHM_K), qr, ql, r32, hi); HOOK(pB0, pB1, j);
;     finishSM(pA0, pA1, alA, l_reg, pa0, pa1, pa2, pa3); SBAR();
;     SLOAD(SO, (j + SD) * KVBLK); SBAR();
;     pv_d0(o, vb0, pa0, pa1, pa2, pa3); partialSM(pB0, pB1, m_reg, mnB, alB, C, thrRaw);
.LBB0_682:
	ds_read_b128 v[66:69], v212 offset:49152
	ds_read_b128 v[70:73], v212 offset:53248
	v_exp_f32_e32 v143, v138
	v_add_f32_e32 v138, 0, v177
	v_add_f32_e32 v138, v226, v138
	s_waitcnt lgkmcnt(1)
	v_mfma_f32_32x32x16_bf16 v[82:97], v[66:69], v[110:113], 0
	v_add_f32_e32 v138, v161, v138
	v_add_f32_e32 v138, v223, v138
	v_add_f32_e32 v138, v153, v138
	ds_read_b128 v[228:231], v216 offset:49152
	ds_read_b128 v[232:235], v216 offset:53248
	v_add_f32_e32 v138, v176, v138
	v_add_f32_e32 v138, v152, v138
	v_add_f32_e32 v138, v160, v138
	s_waitcnt lgkmcnt(2)
	v_mfma_f32_32x32x16_bf16 v[66:81], v[70:73], v[110:113], 0
	v_add_f32_e32 v138, v149, v138
	v_add_f32_e32 v138, v151, v138
	v_add_f32_e32 v138, v147, v138
	v_add_f32_e32 v138, v150, v138
	v_add_f32_e32 v138, v145, v138
	v_exp_f32_e32 v164, v139
	v_add_f32_e32 v138, v148, v138
	s_waitcnt lgkmcnt(1)
	v_mfma_f32_32x32x16_bf16 v[82:97], v[228:231], v[106:109], v[82:97]
	v_exp_f32_e32 v136, v136
	v_add_f32_e32 v138, v144, v138
	v_exp_f32_e32 v137, v137
	v_add_f32_e32 v138, v146, v138
	v_exp_f32_e32 v130, v130
	v_add_f32_e32 v138, v143, v138
	v_exp_f32_e32 v131, v131
	s_waitcnt lgkmcnt(0)
	v_mfma_f32_32x32x16_bf16 v[66:81], v[232:235], v[106:109], v[66:81]
	ds_read_b128 v[228:231], v217 offset:49152
	ds_read_b128 v[232:235], v217 offset:53248
	v_add_f32_e32 v138, v164, v138
	v_exp_f32_e32 v128, v128
	v_add_f32_e32 v138, v136, v138
	v_exp_f32_e32 v129, v129
	v_add_f32_e32 v138, v137, v138
	v_exp_f32_e32 v126, v126
	s_waitcnt lgkmcnt(1)
	v_mfma_f32_32x32x16_bf16 v[82:97], v[228:231], v[98:101], v[82:97]
	v_add_f32_e32 v138, v130, v138
	v_exp_f32_e32 v127, v127
	v_add_f32_e32 v138, v131, v138
	v_exp_f32_e32 v165, v140
	v_add_f32_e32 v138, v128, v138
	v_exp_f32_e32 v166, v141
	v_add_f32_e32 v138, v129, v138
	s_waitcnt lgkmcnt(0)
	v_mfma_f32_32x32x16_bf16 v[66:81], v[232:235], v[98:101], v[66:81]
	ds_read_b128 v[228:231], v218 offset:49152
	ds_read_b128 v[232:235], v218 offset:53248
	v_exp_f32_e32 v134, v134
	v_add_f32_e32 v138, v126, v138
	v_exp_f32_e32 v135, v135
	v_add_f32_e32 v138, v127, v138
	v_exp_f32_e32 v132, v132
	v_add_f32_e32 v138, v165, v138
	s_waitcnt lgkmcnt(1)
	v_mfma_f32_32x32x16_bf16 v[82:97], v[228:231], v[102:105], v[82:97]
	v_exp_f32_e32 v133, v133
	v_add_f32_e32 v138, v166, v138
	v_add_f32_e32 v138, v134, v138
	v_add_f32_e32 v138, v135, v138
	v_add_f32_e32 v138, v132, v138
	v_add_f32_e32 v220, v133, v138
	v_mov_b32_e32 v221, v220
	s_waitcnt lgkmcnt(0)
	v_mfma_f32_32x32x16_bf16 v[66:81], v[232:235], v[102:105], v[66:81]
	v_cvt_pk_bf16_f32 v138, v177, v226
	v_cvt_pk_bf16_f32 v139, v161, v223
	v_cvt_pk_bf16_f32 v140, v153, v176
	v_cvt_pk_bf16_f32 v141, v152, v160
	v_cvt_pk_bf16_f32 v222, v149, v151
	v_cvt_pk_bf16_f32 v223, v147, v150
	v_cvt_pk_bf16_f32 v224, v145, v148
	v_permlane32_swap_b32_e32 v220, v221
	v_permlane32_swap_b32_e32 v138, v140
	v_cvt_pk_bf16_f32 v225, v144, v146
	v_permlane32_swap_b32_e32 v222, v224
	v_cvt_pk_bf16_f32 v144, v143, v164
	v_cvt_pk_bf16_f32 v145, v136, v137
	v_cvt_pk_bf16_f32 v146, v130, v131
	v_cvt_pk_bf16_f32 v147, v128, v129
	v_cvt_pk_bf16_f32 v148, v126, v127
	v_cvt_pk_bf16_f32 v149, v165, v166
	v_cvt_pk_bf16_f32 v150, v134, v135
	v_cvt_pk_bf16_f32 v151, v132, v133
	v_permlane32_swap_b32_e32 v139, v141
	v_permlane32_swap_b32_e32 v223, v225
	v_permlane32_swap_b32_e32 v144, v146
	v_permlane32_swap_b32_e32 v145, v147
	v_permlane32_swap_b32_e32 v148, v150
	v_permlane32_swap_b32_e32 v149, v151
	v_readlane_b32 s2, v254, 32
	v_readlane_b32 s3, v254, 33
	s_mov_b32 s4, 0xe0e0000
	s_mov_b32 s5, 0xe130000
	v_lshl_add_u64 v[160:161], v[156:157], 0, s[2:3]
	v_add_co_u32_e32 v126, vcc, s4, v160
	v_lshl_add_u64 v[176:177], v[158:159], 0, s[2:3]
	s_nop 0
	v_addc_co_u32_e32 v127, vcc, 0, v161, vcc
	v_add_co_u32_e32 v130, vcc, s5, v160
	s_nop 1
	v_addc_co_u32_e32 v131, vcc, 0, v161, vcc
	v_add_co_u32_e32 v134, vcc, s4, v176
	global_load_dwordx4 v[126:129], v[126:127], off offset:2048
	s_nop 0
	global_load_dwordx4 v[130:133], v[130:131], off offset:2048
	v_addc_co_u32_e32 v135, vcc, 0, v177, vcc
	global_load_dwordx4 v[134:137], v[134:135], off offset:1024
	ds_read_b64_tr_b16 v[226:227], v211 offset:0
	ds_read_b64_tr_b16 v[228:229], v211 offset:0x800
	ds_read_b64_tr_b16 v[230:231], v211 offset:0x1000
	ds_read_b64_tr_b16 v[232:233], v211 offset:0x1800
	ds_read_b64_tr_b16 v[234:235], v211 offset:0x2000
	ds_read_b64_tr_b16 v[236:237], v211 offset:0x2800
	ds_read_b64_tr_b16 v[238:239], v211 offset:0x3000
	ds_read_b64_tr_b16 v[240:241], v211 offset:0x3800
	s_waitcnt lgkmcnt(0)
	s_nop 0
	v_mfma_f32_32x32x16_bf16 v[18:33], v[138:141], v[226:229], v[18:33]
	ds_read_b64_tr_b16 v[226:227], v211 offset:0x200
	ds_read_b64_tr_b16 v[228:229], v211 offset:0xa00
	v_mfma_f32_32x32x16_bf16 v[18:33], v[222:225], v[230:233], v[18:33]
	ds_read_b64_tr_b16 v[230:231], v211 offset:0x1200
	ds_read_b64_tr_b16 v[232:233], v211 offset:0x1a00
	v_mfma_f32_32x32x16_bf16 v[18:33], v[144:147], v[234:237], v[18:33]
	ds_read_b64_tr_b16 v[234:235], v211 offset:0x2200
	ds_read_b64_tr_b16 v[236:237], v211 offset:0x2a00
	v_mfma_f32_32x32x16_bf16 v[18:33], v[148:151], v[238:241], v[18:33]
	ds_read_b64_tr_b16 v[238:239], v211 offset:0x3200
	ds_read_b64_tr_b16 v[240:241], v211 offset:0x3a00
	s_waitcnt lgkmcnt(0)
	v_mfma_f32_32x32x16_bf16 v[2:17], v[138:141], v[226:229], v[2:17]
	ds_read_b64_tr_b16 v[226:227], v211 offset:0x400
	ds_read_b64_tr_b16 v[228:229], v211 offset:0xc00
	v_mfma_f32_32x32x16_bf16 v[2:17], v[222:225], v[230:233], v[2:17]
	ds_read_b64_tr_b16 v[230:231], v211 offset:0x1400
	ds_read_b64_tr_b16 v[232:233], v211 offset:0x1c00
	v_mfma_f32_32x32x16_bf16 v[2:17], v[144:147], v[234:237], v[2:17]
	ds_read_b64_tr_b16 v[234:235], v211 offset:0x2400
	ds_read_b64_tr_b16 v[236:237], v211 offset:0x2c00
	v_mfma_f32_32x32x16_bf16 v[2:17], v[148:151], v[238:241], v[2:17]
	ds_read_b64_tr_b16 v[238:239], v211 offset:0x3400
	ds_read_b64_tr_b16 v[240:241], v211 offset:0x3c00
	s_waitcnt lgkmcnt(0)
; #define SWAIT() do { if (SD == 1) asm volatile("s_waitcnt vmcnt(0)" ::: "memory"); else if (DK == 128) asm volatile("s_waitcnt vmcnt(4)" ::: "memory"); else asm volatile("s_waitcnt vmcnt(3)" ::: "memory"); } while (0)
; #define RESC(a) do { if (__any((a) < 1.f)) { if (hi == 0) al_l[r32] = (a); asm volatile("s_waitcnt lgkmcnt(0)" ::: "memory"); \
;     _Pragma("unroll") for (int d = 0; d < 4; ++d) _Pragma("unroll") for (int r = 0; r < 16; ++r) o[d][r] *= al_l[crow(r, hi)]; } } while (0)
; __device__ __forceinline__ void partialSM(f32x16& p0, f32x16& p1, float& m_reg, float& mn, float& alpha, float C, float thrRaw) {
;   float pmax = p0[0];
; #pragma unroll
;   for (int r = 1; r < 16; ++r) pmax = fmaxf(pmax, p0[r]);
; #pragma unroll
;   for (int r = 0; r < 16; ++r) pmax = fmaxf(pmax, p1[r]);
;   { auto rr = __builtin_amdgcn_permlane32_swap(__float_as_uint(pmax), __float_as_uint(pmax), false, false);
;     pmax = fmaxf(__uint_as_float(rr[0]), __uint_as_float(rr[1])); }
;   if (__builtin_expect(__all(pmax - m_reg <= thrRaw), 1)) { mn = m_reg; alpha = 1.f; }
;   else { mn = fmaxf(m_reg, pmax); alpha = __builtin_amdgcn_exp2f((m_reg - mn) * C); m_reg = mn; }
;   float mnC = -mn * C;
; #pragma unroll
;   for (int r = 0; r < 16; ++r) p0[r] = fmaf(p0[r], C, mnC);
; #pragma unroll
;   for (int r = 0; r < 16; ++r) p1[r] = fmaf(p1[r], C, mnC);
; #pragma unroll
;   for (int r = 0; r < 16; ++r) p0[r] = __builtin_amdgcn_exp2f(p0[r]);
; template <int DK, bool NA, bool QL, int SD> ...
;     ...
;     pv_d0(o, vb0, pa0, pa1, pa2, pa3); partialSM(pB0, pB1, m_reg, mnB, alB, C, thrRaw);
;     __syncthreads(); SWAIT(); SWRITE(0, SE);
;     RESC(alB); __syncthreads();
	v_mfma_f32_32x32x16_bf16 v[50:65], v[138:141], v[226:229], v[50:65]
	ds_read_b64_tr_b16 v[226:227], v211 offset:0x600
	ds_read_b64_tr_b16 v[228:229], v211 offset:0xe00
	v_mfma_f32_32x32x16_bf16 v[50:65], v[222:225], v[230:233], v[50:65]
	ds_read_b64_tr_b16 v[230:231], v211 offset:0x1600
	ds_read_b64_tr_b16 v[232:233], v211 offset:0x1e00
	v_mfma_f32_32x32x16_bf16 v[50:65], v[144:147], v[234:237], v[50:65]
	ds_read_b64_tr_b16 v[234:235], v211 offset:0x2600
	ds_read_b64_tr_b16 v[236:237], v211 offset:0x2e00
	v_mfma_f32_32x32x16_bf16 v[50:65], v[148:151], v[238:241], v[50:65]
	ds_read_b64_tr_b16 v[238:239], v211 offset:0x3600
	ds_read_b64_tr_b16 v[240:241], v211 offset:0x3e00
	s_waitcnt lgkmcnt(0)
	v_mfma_f32_32x32x16_bf16 v[34:49], v[138:141], v[226:229], v[34:49]
	v_max_f32_e32 v138, v83, v83
	v_max_f32_e32 v139, v82, v82
	v_max_f32_e32 v138, v139, v138
	v_max3_f32 v138, v138, v84, v85
	v_max3_f32 v138, v138, v86, v87
	v_max3_f32 v138, v138, v88, v89
	v_max3_f32 v138, v138, v90, v91
	v_max3_f32 v138, v138, v92, v93
	v_max3_f32 v138, v138, v94, v95
	v_mfma_f32_32x32x16_bf16 v[34:49], v[222:225], v[230:233], v[34:49]
	v_max3_f32 v138, v138, v96, v97
	v_max3_f32 v138, v138, v66, v67
	v_max3_f32 v138, v138, v68, v69
	v_max3_f32 v138, v138, v70, v71
	v_max3_f32 v138, v138, v72, v73
	v_max3_f32 v138, v138, v74, v75
	v_max3_f32 v138, v138, v76, v77
	v_max3_f32 v138, v138, v78, v79
	v_mfma_f32_32x32x16_bf16 v[34:49], v[144:147], v[234:237], v[34:49]
	v_max3_f32 v138, v138, v80, v81
	v_mov_b32_e32 v139, v138
	s_nop 1
	v_permlane32_swap_b32_e32 v138, v139
	v_max_f32_e32 v139, v139, v139
	v_max_f32_e32 v138, v138, v138
	v_max_f32_e32 v138, v138, v139
	v_sub_f32_e32 v139, v138, v142
	s_mov_b32 s2, 0x42800000
	v_cmp_ge_f32_e32 vcc, s2, v139
	v_max_f32_e32 v139, v142, v142
	v_max_f32_e32 v138, v139, v138
	v_mfma_f32_32x32x16_bf16 v[34:49], v[148:151], v[238:241], v[34:49]
	v_sub_f32_e32 v139, v142, v138
	v_mul_f32_e32 v139, 0x3e38aa3b, v139
	v_exp_f32_e32 v139, v139
	s_cmp_eq_u64 vcc, exec
	s_cselect_b64 s[2:3], -1, 0
	s_waitcnt vmcnt(3)
	v_cndmask_b32_e64 v222, v139, 1.0, s[2:3]
	v_cmp_gt_f32_e32 vcc, 1.0, v222
	s_waitcnt vmcnt(3)
	ds_write_b128 v213, v[122:125] offset:32768
	s_cbranch_vccz .LBB0_686
	s_and_saveexec_b64 s[4:5], s[0:1]
	ds_write_b32 v208, v222 offset:128
	s_or_b64 exec, exec, s[4:5]
	s_waitcnt lgkmcnt(0)
	v_add_u32_e32 v139, v207, v0
	ds_read_b128 v[144:147], v139 offset:128
	ds_read_b128 v[148:151], v139 offset:160
	ds_read_b128 v[224:227], v139 offset:192
	ds_read_b128 v[228:231], v139 offset:224
	s_waitcnt lgkmcnt(3)
	v_pk_mul_f32 v[2:3], v[144:145], v[2:3]
	v_pk_mul_f32 v[4:5], v[4:5], v[146:147]
	s_waitcnt lgkmcnt(2)
	v_pk_mul_f32 v[6:7], v[6:7], v[148:149]
	v_pk_mul_f32 v[8:9], v[8:9], v[150:151]
	s_waitcnt lgkmcnt(1)
	v_pk_mul_f32 v[10:11], v[10:11], v[224:225]
	v_pk_mul_f32 v[12:13], v[12:13], v[226:227]
	s_waitcnt lgkmcnt(0)
	v_pk_mul_f32 v[14:15], v[14:15], v[228:229]
	v_pk_mul_f32 v[30:31], v[30:31], v[228:229]
	v_pk_mul_f32 v[26:27], v[26:27], v[224:225]
	v_pk_mul_f32 v[22:23], v[22:23], v[148:149]
	v_pk_mul_f32 v[32:33], v[32:33], v[230:231]
	v_pk_mul_f32 v[28:29], v[28:29], v[226:227]
	v_pk_mul_f32 v[24:25], v[24:25], v[150:151]
	v_pk_mul_f32 v[20:21], v[20:21], v[146:147]
	v_pk_mul_f32 v[18:19], v[18:19], v[144:145]
	v_pk_mul_f32 v[16:17], v[16:17], v[230:231]
	v_pk_mul_f32 v[34:35], v[144:145], v[34:35]
	v_pk_mul_f32 v[36:37], v[36:37], v[146:147]
	v_pk_mul_f32 v[38:39], v[38:39], v[148:149]
	v_pk_mul_f32 v[40:41], v[40:41], v[150:151]
	v_pk_mul_f32 v[42:43], v[42:43], v[224:225]
	v_pk_mul_f32 v[44:45], v[44:45], v[226:227]
	v_pk_mul_f32 v[46:47], v[46:47], v[228:229]
	v_pk_mul_f32 v[62:63], v[62:63], v[228:229]
	v_pk_mul_f32 v[58:59], v[58:59], v[224:225]
	v_pk_mul_f32 v[54:55], v[54:55], v[148:149]
	v_pk_mul_f32 v[64:65], v[64:65], v[230:231]
	v_pk_mul_f32 v[60:61], v[60:61], v[226:227]
	v_pk_mul_f32 v[56:57], v[56:57], v[150:151]
	v_pk_mul_f32 v[52:53], v[52:53], v[146:147]
	v_pk_mul_f32 v[50:51], v[50:51], v[144:145]
	v_pk_mul_f32 v[48:49], v[48:49], v[230:231]
.LBB0_686:
	v_cndmask_b32_e64 v223, v138, v142, s[2:3]
	v_mul_f32_e32 v224, 0xbe38aa3b, v223
	v_fmamk_f32 v82, v82, 0x3e38aa3b, v224
	v_fmamk_f32 v83, v83, 0x3e38aa3b, v224
	v_fmamk_f32 v84, v84, 0x3e38aa3b, v224
	v_fmamk_f32 v85, v85, 0x3e38aa3b, v224
	v_fmamk_f32 v86, v86, 0x3e38aa3b, v224
	v_fmamk_f32 v87, v87, 0x3e38aa3b, v224
	v_fmamk_f32 v88, v88, 0x3e38aa3b, v224
	v_fmamk_f32 v89, v89, 0x3e38aa3b, v224
	v_fmamk_f32 v90, v90, 0x3e38aa3b, v224
	v_fmamk_f32 v91, v91, 0x3e38aa3b, v224
	v_fmamk_f32 v92, v92, 0x3e38aa3b, v224
	v_fmamk_f32 v93, v93, 0x3e38aa3b, v224
	v_fmamk_f32 v94, v94, 0x3e38aa3b, v224
	v_fmamk_f32 v95, v95, 0x3e38aa3b, v224
	v_fmamk_f32 v96, v96, 0x3e38aa3b, v224
	v_fmamk_f32 v97, v97, 0x3e38aa3b, v224
	v_exp_f32_e32 v138, v82
	v_exp_f32_e32 v153, v83
	v_exp_f32_e32 v139, v84
	v_exp_f32_e32 v152, v85
	v_exp_f32_e32 v140, v86
	v_exp_f32_e32 v151, v87
	v_exp_f32_e32 v141, v88
	v_exp_f32_e32 v150, v89
	v_exp_f32_e32 v142, v90
	v_exp_f32_e32 v149, v91
	v_exp_f32_e32 v143, v92
	v_exp_f32_e32 v148, v93
	v_exp_f32_e32 v144, v94
	v_exp_f32_e32 v147, v95
	v_exp_f32_e32 v145, v96
	v_exp_f32_e32 v146, v97
	v_fmamk_f32 v233, v66, 0x3e38aa3b, v224
	v_fmamk_f32 v234, v67, 0x3e38aa3b, v224
	v_fmamk_f32 v235, v68, 0x3e38aa3b, v224
	v_fmamk_f32 v236, v69, 0x3e38aa3b, v224
	v_fmamk_f32 v237, v70, 0x3e38aa3b, v224
	v_fmamk_f32 v226, v71, 0x3e38aa3b, v224
	v_fmamk_f32 v227, v72, 0x3e38aa3b, v224
	v_fmamk_f32 v228, v73, 0x3e38aa3b, v224
	v_fmamk_f32 v229, v74, 0x3e38aa3b, v224
	v_fmamk_f32 v230, v75, 0x3e38aa3b, v224
	v_fmamk_f32 v231, v76, 0x3e38aa3b, v224
	v_fmamk_f32 v232, v77, 0x3e38aa3b, v224
	v_fmamk_f32 v225, v78, 0x3e38aa3b, v224
	v_fmamk_f32 v238, v79, 0x3e38aa3b, v224
	v_fmamk_f32 v239, v80, 0x3e38aa3b, v224
	v_fmac_f32_e32 v224, 0x3e38aa3b, v81
	s_waitcnt lgkmcnt(0)
	s_barrier
; #define SBAR() __builtin_amdgcn_sched_barrier(0)
; #define SLOAD(i, k0) do { sr_[i].vs0 = *reinterpret_cast<const bf16x8*>(&Vh[(long)((k0) + sr) * LDP + sc]); sr_[i].vs1 = *reinterpret_cast<const bf16x8*>(&Vh[(long)((k0) + 32 + sr) * LDP + sc]); \
;     sr_[i].ks0 = *reinterpret_cast<const bf16x8*>(&Kh[(long)((k0) + ksr) * LDP + ksc]); if (DK == 128) sr_[i].ks1 = *reinterpret_cast<const bf16x8*>(&Kh[(long)((k0) + 32 + ksr) * LDP + ksc]); } while (0)
; #define HOOK(P0, P1, j) do { if (NA) na_hook(P0, P1, krow0 + (j), q_row, q_col, win_r, win_c, rpb, inv_scale, hi); } while (0)
; __device__ __forceinline__ void finishSM(f32x16& p0, f32x16& p1, float alpha, float& l_reg, bf16x8& pa0, bf16x8& pa1, bf16x8& pa2, bf16x8& pa3) {
; #pragma unroll
;   for (int r = 0; r < 16; ++r) p1[r] = __builtin_amdgcn_exp2f(p1[r]);
;   float ps = 0;
; #pragma unroll
;   for (int r = 0; r < 16; ++r) ps += p0[r];
; #pragma unroll
;   for (int r = 0; r < 16; ++r) ps += p1[r];
;   { auto rr = __builtin_amdgcn_permlane32_swap(__float_as_uint(ps), __float_as_uint(ps), false, false);
;     ps = __uint_as_float(rr[0]) + __uint_as_float(rr[1]); }
;   l_reg = l_reg * alpha + ps;
;     ...
;   PK4(p0, 0, pa0); PK4(p0, 8, pa1); PK4(p1, 0, pa2); PK4(p1, 8, pa3);
;     ...
; }
; template <int DK, bool NA, bool QL, int SD> ...
;     ...
;     SBAR(); qkt<DK, QL>(pA0, pA1, K_lds, qr, ql, r32, hi); HOOK(pA0, pA1, j + 1);
;     finishSM(pB0, pB1, alB, l_reg, pa0, pa1, pa2, pa3); SBAR();
;     if (SD == 1 || j + 3 < NT) SLOAD(SE, (j + 1 + SD) * KVBLK); SBAR();
;     pv_d0(o, vb0 + (int)SHM_V, pa0, pa1, pa2, pa3); partialSM(pA0, pA1, m_reg, mnA, alA, C, thrRaw);
	ds_write_b128 v214, v[114:117]
	ds_write_b128 v215, v[118:121]
	ds_read_b128 v[66:69], v212 offset:32768
	ds_read_b128 v[70:73], v212 offset:36864
	v_exp_f32_e32 v164, v233
	v_exp_f32_e32 v233, v224
	v_add_f32_e32 v224, 0, v138
	v_add_f32_e32 v224, v153, v224
	s_waitcnt lgkmcnt(1)
	v_mfma_f32_32x32x16_bf16 v[82:97], v[66:69], v[110:113], 0
	v_add_f32_e32 v224, v139, v224
	v_add_f32_e32 v224, v152, v224
	v_add_f32_e32 v224, v140, v224
	ds_read_b128 v[240:243], v216 offset:32768
	ds_read_b128 v[244:247], v216 offset:36864
	v_add_f32_e32 v224, v151, v224
	v_add_f32_e32 v224, v141, v224
	v_add_f32_e32 v224, v150, v224
	s_waitcnt lgkmcnt(2)
	v_mfma_f32_32x32x16_bf16 v[66:81], v[70:73], v[110:113], 0
	v_add_f32_e32 v224, v142, v224
	v_add_f32_e32 v224, v149, v224
	v_add_f32_e32 v224, v143, v224
	v_add_f32_e32 v224, v148, v224
	v_add_f32_e32 v224, v144, v224
	v_exp_f32_e32 v165, v234
	v_add_f32_e32 v224, v147, v224
	s_waitcnt lgkmcnt(1)
	v_mfma_f32_32x32x16_bf16 v[82:97], v[240:243], v[106:109], v[82:97]
	v_exp_f32_e32 v166, v235
	v_add_f32_e32 v224, v145, v224
	v_exp_f32_e32 v167, v236
	v_add_f32_e32 v224, v146, v224
	v_exp_f32_e32 v172, v237
	v_add_f32_e32 v224, v164, v224
	v_exp_f32_e32 v173, v226
	s_waitcnt lgkmcnt(0)
	v_mfma_f32_32x32x16_bf16 v[66:81], v[244:247], v[106:109], v[66:81]
	ds_read_b128 v[240:243], v217 offset:32768
	ds_read_b128 v[244:247], v217 offset:36864
	v_add_f32_e32 v224, v165, v224
	v_exp_f32_e32 v174, v227
	v_add_f32_e32 v224, v166, v224
	v_exp_f32_e32 v175, v228
	v_add_f32_e32 v224, v167, v224
	v_exp_f32_e32 v226, v229
	s_waitcnt lgkmcnt(1)
	v_mfma_f32_32x32x16_bf16 v[82:97], v[240:243], v[98:101], v[82:97]
	v_add_f32_e32 v224, v172, v224
	v_exp_f32_e32 v227, v230
	v_add_f32_e32 v224, v173, v224
	v_exp_f32_e32 v228, v231
	v_add_f32_e32 v224, v174, v224
	v_exp_f32_e32 v229, v232
	v_add_f32_e32 v224, v175, v224
	s_waitcnt lgkmcnt(0)
	v_mfma_f32_32x32x16_bf16 v[66:81], v[244:247], v[98:101], v[66:81]
	ds_read_b128 v[240:243], v218 offset:32768
	ds_read_b128 v[244:247], v218 offset:36864
	v_exp_f32_e32 v230, v225
	v_add_f32_e32 v224, v226, v224
	v_exp_f32_e32 v231, v238
	v_add_f32_e32 v224, v227, v224
	v_exp_f32_e32 v232, v239
	v_add_f32_e32 v224, v228, v224
	s_waitcnt lgkmcnt(1)
	v_mfma_f32_32x32x16_bf16 v[82:97], v[240:243], v[102:105], v[82:97]
	v_add_f32_e32 v224, v229, v224
	v_add_f32_e32 v224, v230, v224
	v_add_f32_e32 v224, v231, v224
	v_add_f32_e32 v224, v232, v224
	v_add_f32_e32 v224, v233, v224
	v_mov_b32_e32 v225, v224
	v_cvt_pk_bf16_f32 v138, v138, v153
	s_waitcnt lgkmcnt(0)
	v_mfma_f32_32x32x16_bf16 v[66:81], v[244:247], v[102:105], v[66:81]
	v_cvt_pk_bf16_f32 v139, v139, v152
	v_cvt_pk_bf16_f32 v140, v140, v151
	v_cvt_pk_bf16_f32 v141, v141, v150
	v_cvt_pk_bf16_f32 v142, v142, v149
	v_cvt_pk_bf16_f32 v143, v143, v148
	v_cvt_pk_bf16_f32 v144, v144, v147
	v_cvt_pk_bf16_f32 v145, v145, v146
	v_cvt_pk_bf16_f32 v146, v164, v165
	v_cvt_pk_bf16_f32 v147, v166, v167
	v_cvt_pk_bf16_f32 v148, v172, v173
	v_cvt_pk_bf16_f32 v149, v174, v175
	v_cvt_pk_bf16_f32 v150, v226, v227
	v_cvt_pk_bf16_f32 v151, v228, v229
	v_cvt_pk_bf16_f32 v152, v230, v231
	v_cvt_pk_bf16_f32 v153, v232, v233
	v_permlane32_swap_b32_e32 v224, v225
	v_permlane32_swap_b32_e32 v138, v140
	v_permlane32_swap_b32_e32 v139, v141
	v_permlane32_swap_b32_e32 v142, v144
	v_permlane32_swap_b32_e32 v143, v145
	v_permlane32_swap_b32_e32 v146, v148
	v_permlane32_swap_b32_e32 v147, v149
	v_permlane32_swap_b32_e32 v150, v152
	v_permlane32_swap_b32_e32 v151, v153
	s_cmp_gt_u32 s9, 60
	s_cselect_b64 s[4:5], -1, 0
	s_and_b64 vcc, exec, s[4:5]
	s_cbranch_vccnz .Lod_d1
	v_add_co_u32_e32 v114, vcc, 0xe180000, v160
	s_nop 1
	v_addc_co_u32_e32 v115, vcc, 0, v161, vcc
	v_add_co_u32_e32 v118, vcc, 0xe1d0000, v160
	s_nop 1
	v_addc_co_u32_e32 v119, vcc, 0, v161, vcc
	v_add_co_u32_e32 v122, vcc, 0xe180000, v176
	global_load_dwordx4 v[114:117], v[114:115], off offset:2048
	s_nop 0
	global_load_dwordx4 v[118:121], v[118:119], off offset:2048
	v_addc_co_u32_e32 v123, vcc, 0, v177, vcc
	global_load_dwordx4 v[122:125], v[122:123], off offset:1024
.LBB0_688:
	ds_read_b64_tr_b16 v[226:227], v210 offset:0
	ds_read_b64_tr_b16 v[228:229], v210 offset:0x800
	ds_read_b64_tr_b16 v[230:231], v210 offset:0x1000
	ds_read_b64_tr_b16 v[232:233], v210 offset:0x1800
	ds_read_b64_tr_b16 v[234:235], v210 offset:0x2000
	ds_read_b64_tr_b16 v[236:237], v210 offset:0x2800
	ds_read_b64_tr_b16 v[238:239], v210 offset:0x3000
	ds_read_b64_tr_b16 v[240:241], v210 offset:0x3800
	s_waitcnt lgkmcnt(0)
	s_nop 0
	v_mfma_f32_32x32x16_bf16 v[18:33], v[138:141], v[226:229], v[18:33]
	ds_read_b64_tr_b16 v[226:227], v210 offset:0x200
	ds_read_b64_tr_b16 v[228:229], v210 offset:0xa00
	v_mfma_f32_32x32x16_bf16 v[18:33], v[142:145], v[230:233], v[18:33]
	ds_read_b64_tr_b16 v[230:231], v210 offset:0x1200
	ds_read_b64_tr_b16 v[232:233], v210 offset:0x1a00
	v_mfma_f32_32x32x16_bf16 v[18:33], v[146:149], v[234:237], v[18:33]
	ds_read_b64_tr_b16 v[234:235], v210 offset:0x2200
	ds_read_b64_tr_b16 v[236:237], v210 offset:0x2a00
	v_mfma_f32_32x32x16_bf16 v[18:33], v[150:153], v[238:241], v[18:33]
	ds_read_b64_tr_b16 v[238:239], v210 offset:0x3200
	ds_read_b64_tr_b16 v[240:241], v210 offset:0x3a00
	s_waitcnt lgkmcnt(0)
	v_mfma_f32_32x32x16_bf16 v[2:17], v[138:141], v[226:229], v[2:17]
	ds_read_b64_tr_b16 v[226:227], v210 offset:0x400
	ds_read_b64_tr_b16 v[228:229], v210 offset:0xc00
	v_mfma_f32_32x32x16_bf16 v[2:17], v[142:145], v[230:233], v[2:17]
	ds_read_b64_tr_b16 v[230:231], v210 offset:0x1400
	ds_read_b64_tr_b16 v[232:233], v210 offset:0x1c00
	v_mfma_f32_32x32x16_bf16 v[2:17], v[146:149], v[234:237], v[2:17]
	ds_read_b64_tr_b16 v[234:235], v210 offset:0x2400
	ds_read_b64_tr_b16 v[236:237], v210 offset:0x2c00
	v_mfma_f32_32x32x16_bf16 v[2:17], v[150:153], v[238:241], v[2:17]
	ds_read_b64_tr_b16 v[238:239], v210 offset:0x3400
	ds_read_b64_tr_b16 v[240:241], v210 offset:0x3c00
	s_waitcnt lgkmcnt(0)
; #define SWAIT() do { if (SD == 1) asm volatile("s_waitcnt vmcnt(0)" ::: "memory"); else if (DK == 128) asm volatile("s_waitcnt vmcnt(4)" ::: "memory"); else asm volatile("s_waitcnt vmcnt(3)" ::: "memory"); } while (0)
; #define RESC(a) do { if (__any((a) < 1.f)) { if (hi == 0) al_l[r32] = (a); asm volatile("s_waitcnt lgkmcnt(0)" ::: "memory"); \
;     _Pragma("unroll") for (int d = 0; d < 4; ++d) _Pragma("unroll") for (int r = 0; r < 16; ++r) o[d][r] *= al_l[crow(r, hi)]; } } while (0)
; __device__ __forceinline__ void partialSM(f32x16& p0, f32x16& p1, float& m_reg, float& mn, float& alpha, float C, float thrRaw) {
;   float pmax = p0[0];
; #pragma unroll
;   for (int r = 1; r < 16; ++r) pmax = fmaxf(pmax, p0[r]);
; #pragma unroll
;   for (int r = 0; r < 16; ++r) pmax = fmaxf(pmax, p1[r]);
;   { auto rr = __builtin_amdgcn_permlane32_swap(__float_as_uint(pmax), __float_as_uint(pmax), false, false);
;     pmax = fmaxf(__uint_as_float(rr[0]), __uint_as_float(rr[1])); }
;   if (__builtin_expect(__all(pmax - m_reg <= thrRaw), 1)) { mn = m_reg; alpha = 1.f; }
;   else { mn = fmaxf(m_reg, pmax); alpha = __builtin_amdgcn_exp2f((m_reg - mn) * C); m_reg = mn; }
;   float mnC = -mn * C;
; #pragma unroll
;   for (int r = 0; r < 16; ++r) p0[r] = fmaf(p0[r], C, mnC);
; #pragma unroll
;   for (int r = 0; r < 16; ++r) p1[r] = fmaf(p1[r], C, mnC);
; #pragma unroll
;   for (int r = 0; r < 16; ++r) p0[r] = __builtin_amdgcn_exp2f(p0[r]);
; template <int DK, bool NA, bool QL, int SD> ...
;     ...
;     pv_d0(o, vb0 + (int)SHM_V, pa0, pa1, pa2, pa3); partialSM(pA0, pA1, m_reg, mnA, alA, C, thrRaw);
;     __syncthreads(); SWAIT(); SWRITE(1, SO);
;     RESC(alA); __syncthreads();
	v_mfma_f32_32x32x16_bf16 v[50:65], v[138:141], v[226:229], v[50:65]
	ds_read_b64_tr_b16 v[226:227], v210 offset:0x600
	ds_read_b64_tr_b16 v[228:229], v210 offset:0xe00
	v_mfma_f32_32x32x16_bf16 v[50:65], v[142:145], v[230:233], v[50:65]
	ds_read_b64_tr_b16 v[230:231], v210 offset:0x1600
	ds_read_b64_tr_b16 v[232:233], v210 offset:0x1e00
	v_mfma_f32_32x32x16_bf16 v[50:65], v[146:149], v[234:237], v[50:65]
	ds_read_b64_tr_b16 v[234:235], v210 offset:0x2600
	ds_read_b64_tr_b16 v[236:237], v210 offset:0x2e00
	v_mfma_f32_32x32x16_bf16 v[50:65], v[150:153], v[238:241], v[50:65]
	ds_read_b64_tr_b16 v[238:239], v210 offset:0x3600
	ds_read_b64_tr_b16 v[240:241], v210 offset:0x3e00
	s_waitcnt lgkmcnt(0)
	v_mfma_f32_32x32x16_bf16 v[34:49], v[138:141], v[226:229], v[34:49]
	v_max_f32_e32 v138, v83, v83
	v_max_f32_e32 v139, v82, v82
	v_max_f32_e32 v138, v139, v138
	v_max3_f32 v138, v138, v84, v85
	v_max3_f32 v138, v138, v86, v87
	v_max3_f32 v138, v138, v88, v89
	v_max3_f32 v138, v138, v90, v91
	v_max3_f32 v138, v138, v92, v93
	v_max3_f32 v138, v138, v94, v95
	v_mfma_f32_32x32x16_bf16 v[34:49], v[142:145], v[230:233], v[34:49]
	v_max3_f32 v138, v138, v96, v97
	v_max3_f32 v138, v138, v66, v67
	v_max3_f32 v138, v138, v68, v69
	v_max3_f32 v138, v138, v70, v71
	v_max3_f32 v138, v138, v72, v73
	v_max3_f32 v138, v138, v74, v75
	v_max3_f32 v138, v138, v76, v77
	v_max3_f32 v138, v138, v78, v79
	v_mfma_f32_32x32x16_bf16 v[34:49], v[146:149], v[234:237], v[34:49]
	v_max3_f32 v138, v138, v80, v81
	v_mov_b32_e32 v139, v138
	s_nop 1
	v_permlane32_swap_b32_e32 v138, v139
	v_max_f32_e32 v139, v139, v139
	v_max_f32_e32 v138, v138, v138
	v_max_f32_e32 v138, v138, v139
	v_sub_f32_e32 v139, v138, v223
	s_mov_b32 s2, 0x42800000
	v_cmp_ge_f32_e32 vcc, s2, v139
	v_max_f32_e32 v139, v223, v223
	v_max_f32_e32 v138, v139, v138
	v_mfma_f32_32x32x16_bf16 v[34:49], v[150:153], v[238:241], v[34:49]
	v_sub_f32_e32 v139, v223, v138
	v_mul_f32_e32 v139, 0x3e38aa3b, v139
	v_exp_f32_e32 v139, v139
	s_cmp_eq_u64 vcc, exec
	s_cselect_b64 s[2:3], -1, 0
	s_waitcnt vmcnt(3)
	v_cndmask_b32_e64 v143, v139, 1.0, s[2:3]
	v_cmp_gt_f32_e32 vcc, 1.0, v143
	v_mov_b64_e32 v[182:183], v[126:127]
	v_mov_b64_e32 v[184:185], v[128:129]
	v_mov_b64_e32 v[194:195], v[130:131]
	v_mov_b64_e32 v[196:197], v[132:133]
	ds_write_b128 v213, v[134:137] offset:49152
	s_cbranch_vccz .LBB0_692
	s_and_saveexec_b64 s[6:7], s[0:1]
	ds_write_b32 v208, v143 offset:128
	s_or_b64 exec, exec, s[6:7]
	s_waitcnt lgkmcnt(0)
	v_add_u32_e32 v139, v207, v0
	ds_read_b128 v[126:129], v139 offset:128
	ds_read_b128 v[130:133], v139 offset:160
	ds_read_b128 v[134:137], v139 offset:224
	ds_read_b128 v[144:147], v139 offset:192
	s_waitcnt lgkmcnt(3)
	v_pk_mul_f32 v[50:51], v[126:127], v[50:51]
	v_pk_mul_f32 v[52:53], v[128:129], v[52:53]
	s_waitcnt lgkmcnt(2)
	v_pk_mul_f32 v[54:55], v[130:131], v[54:55]
	s_waitcnt lgkmcnt(1)
	v_pk_mul_f32 v[30:31], v[30:31], v[134:135]
	s_waitcnt lgkmcnt(0)
	v_pk_mul_f32 v[26:27], v[26:27], v[144:145]
	v_pk_mul_f32 v[22:23], v[22:23], v[130:131]
	v_pk_mul_f32 v[32:33], v[32:33], v[136:137]
	v_pk_mul_f32 v[28:29], v[28:29], v[146:147]
	v_pk_mul_f32 v[24:25], v[24:25], v[132:133]
	v_pk_mul_f32 v[20:21], v[20:21], v[128:129]
	v_pk_mul_f32 v[18:19], v[18:19], v[126:127]
	v_pk_mul_f32 v[14:15], v[134:135], v[14:15]
	v_pk_mul_f32 v[10:11], v[144:145], v[10:11]
	v_pk_mul_f32 v[6:7], v[130:131], v[6:7]
	v_pk_mul_f32 v[16:17], v[136:137], v[16:17]
	v_pk_mul_f32 v[12:13], v[146:147], v[12:13]
	v_pk_mul_f32 v[8:9], v[132:133], v[8:9]
	v_pk_mul_f32 v[4:5], v[128:129], v[4:5]
	v_pk_mul_f32 v[2:3], v[126:127], v[2:3]
	v_pk_mul_f32 v[56:57], v[132:133], v[56:57]
	v_pk_mul_f32 v[34:35], v[126:127], v[34:35]
	v_pk_mul_f32 v[36:37], v[36:37], v[128:129]
	v_pk_mul_f32 v[38:39], v[38:39], v[130:131]
	v_pk_mul_f32 v[40:41], v[40:41], v[132:133]
	v_pk_mul_f32 v[58:59], v[58:59], v[144:145]
	v_pk_mul_f32 v[42:43], v[42:43], v[144:145]
	v_pk_mul_f32 v[60:61], v[60:61], v[146:147]
	v_pk_mul_f32 v[44:45], v[44:45], v[146:147]
	v_pk_mul_f32 v[62:63], v[62:63], v[134:135]
	v_pk_mul_f32 v[46:47], v[46:47], v[134:135]
	v_pk_mul_f32 v[64:65], v[64:65], v[136:137]
	v_pk_mul_f32 v[48:49], v[48:49], v[136:137]
.LBB0_692:
	v_cndmask_b32_e64 v142, v138, v223, s[2:3]
	v_mul_f32_e32 v132, 0xbe38aa3b, v142
	v_mov_b32_e32 v133, v132
	v_fmamk_f32 v82, v82, 0x3e38aa3b, v132
	v_fmamk_f32 v83, v83, 0x3e38aa3b, v132
	v_fmamk_f32 v84, v84, 0x3e38aa3b, v132
	v_fmamk_f32 v85, v85, 0x3e38aa3b, v132
	v_fmamk_f32 v86, v86, 0x3e38aa3b, v132
	v_fmamk_f32 v87, v87, 0x3e38aa3b, v132
	v_fmamk_f32 v88, v88, 0x3e38aa3b, v132
	v_fmamk_f32 v89, v89, 0x3e38aa3b, v132
	v_fmamk_f32 v90, v90, 0x3e38aa3b, v132
	v_fmamk_f32 v91, v91, 0x3e38aa3b, v132
	v_fmamk_f32 v92, v92, 0x3e38aa3b, v132
	v_fmamk_f32 v93, v93, 0x3e38aa3b, v132
	v_fmamk_f32 v94, v94, 0x3e38aa3b, v132
	v_fmamk_f32 v95, v95, 0x3e38aa3b, v132
	v_fmamk_f32 v96, v96, 0x3e38aa3b, v132
	v_fmac_f32_e32 v133, 0x3e38aa3b, v97
	s_mov_b32 s2, 0x3e38aa3b
	v_exp_f32_e32 v177, v82
	v_exp_f32_e32 v226, v83
	v_exp_f32_e32 v161, v84
	v_exp_f32_e32 v223, v85
	v_exp_f32_e32 v153, v86
	v_exp_f32_e32 v176, v87
	v_exp_f32_e32 v152, v88
	v_exp_f32_e32 v160, v89
	v_exp_f32_e32 v149, v90
	v_exp_f32_e32 v151, v91
	v_exp_f32_e32 v147, v92
	v_exp_f32_e32 v150, v93
	v_exp_f32_e32 v145, v94
	v_exp_f32_e32 v148, v95
	v_exp_f32_e32 v144, v96
	v_exp_f32_e32 v146, v133
	v_pk_fma_f32 v[138:139], v[66:67], s[2:3], v[132:133] op_sel_hi:[1,0,0]
	v_add_f32_e32 v66, v220, v221
	v_pk_fma_f32 v[136:137], v[68:69], s[2:3], v[132:133] op_sel_hi:[1,0,0]
	v_pk_fma_f32 v[130:131], v[70:71], s[2:3], v[132:133] op_sel_hi:[1,0,0]
	v_pk_fma_f32 v[128:129], v[72:73], s[2:3], v[132:133] op_sel_hi:[1,0,0]
	v_pk_fma_f32 v[126:127], v[74:75], s[2:3], v[132:133] op_sel_hi:[1,0,0]
	v_pk_fma_f32 v[140:141], v[76:77], s[2:3], v[132:133] op_sel_hi:[1,0,0]
	v_pk_fma_f32 v[134:135], v[78:79], s[2:3], v[132:133] op_sel_hi:[1,0,0]
	v_pk_fma_f32 v[132:133], v[80:81], s[2:3], v[132:133] op_sel_hi:[1,0,0]
	v_fmac_f32_e32 v66, v219, v209
	v_add_f32_e32 v209, v224, v225
	s_mov_b64 s[2:3], 0x140000
	v_fmac_f32_e32 v209, v66, v222
	s_add_i32 s9, s9, 2
	v_lshl_add_u64 v[156:157], v[156:157], 0, s[2:3]
	v_lshl_add_u64 v[158:159], v[158:159], 0, s[2:3]
	s_and_b64 vcc, exec, s[4:5]
	s_waitcnt lgkmcnt(0)
	s_barrier
	s_cbranch_vccnz .LBB0_694
	v_mov_b32_e32 v219, v143
	ds_write_b128 v214, v[182:185] offset:16384
	ds_write_b128 v215, v[194:197] offset:16384
	s_branch .LBB0_682

; #define SBAR() __builtin_amdgcn_sched_barrier(0)
; #define HOOK(P0, P1, j) do { if (NA) na_hook(P0, P1, krow0 + (j), q_row, q_col, win_r, win_c, rpb, inv_scale, hi); } while (0)
; template <int DK, bool NA, bool QL, int SD> ...
;     ...
;   SBAR(); qkt<DK, QL>(pB0, pB1, (bf16*)((char*)K_lds + SHM_K), qr, ql, r32, hi); HOOK(pB0, pB1, NT - 1);
;   finishSM(pA0, pA1, alA, l_reg, pa0, pa1, pa2, pa3); SBAR();
;   pv_d0(o, vb0, pa0, pa1, pa2, pa3); partialSM(pB0, pB1, m_reg, mnB, alB, C, thrRaw);
.LBB0_694:
	ds_write_b128 v214, v[182:185] offset:16384
	ds_write_b128 v215, v[194:197] offset:16384
	ds_read_b128 v[66:69], v212 offset:49152
	ds_read_b128 v[70:73], v212 offset:53248
	v_exp_f32_e32 v118, v140
	v_exp_f32_e32 v119, v141
	v_exp_f32_e32 v120, v134
	s_waitcnt lgkmcnt(1)
	v_mfma_f32_32x32x16_bf16 v[82:97], v[66:69], v[110:113], 0
	v_exp_f32_e32 v121, v135
	v_exp_f32_e32 v122, v132
	v_exp_f32_e32 v123, v133
	s_waitcnt lgkmcnt(0)
	v_mfma_f32_32x32x16_bf16 v[66:81], v[70:73], v[110:113], 0
	ds_read_b128 v[110:113], v216 offset:49152
	ds_read_b128 v[114:117], v216 offset:53248
	s_waitcnt lgkmcnt(1)
	v_mfma_f32_32x32x16_bf16 v[82:97], v[110:113], v[106:109], v[82:97]
	s_waitcnt lgkmcnt(0)
	v_mfma_f32_32x32x16_bf16 v[66:81], v[114:117], v[106:109], v[66:81]
	ds_read_b128 v[106:109], v217 offset:49152
	ds_read_b128 v[110:113], v217 offset:53248
	v_exp_f32_e32 v114, v128
	v_exp_f32_e32 v115, v129
	v_exp_f32_e32 v116, v126
	v_exp_f32_e32 v117, v127
	s_waitcnt lgkmcnt(1)
	v_mfma_f32_32x32x16_bf16 v[82:97], v[106:109], v[98:101], v[82:97]
	s_waitcnt lgkmcnt(0)
	v_mfma_f32_32x32x16_bf16 v[66:81], v[110:113], v[98:101], v[66:81]
	ds_read_b128 v[98:101], v218 offset:49152
	ds_read_b128 v[106:109], v218 offset:53248
	v_exp_f32_e32 v110, v136
	v_exp_f32_e32 v111, v137
	v_exp_f32_e32 v112, v130
	v_exp_f32_e32 v113, v131
	s_waitcnt lgkmcnt(1)
	v_mfma_f32_32x32x16_bf16 v[82:97], v[98:101], v[102:105], v[82:97]
	v_add_f32_e32 v98, 0, v177
	v_add_f32_e32 v98, v226, v98
	v_add_f32_e32 v98, v161, v98
	v_add_f32_e32 v98, v223, v98
	v_add_f32_e32 v98, v153, v98
	v_add_f32_e32 v98, v176, v98
	v_add_f32_e32 v98, v152, v98
	v_add_f32_e32 v98, v160, v98
	v_add_f32_e32 v98, v149, v98
	v_add_f32_e32 v98, v151, v98
	v_add_f32_e32 v98, v147, v98
	v_add_f32_e32 v98, v150, v98
	s_waitcnt lgkmcnt(0)
	v_mfma_f32_32x32x16_bf16 v[66:81], v[106:109], v[102:105], v[66:81]
	v_exp_f32_e32 v108, v138
	v_add_f32_e32 v98, v145, v98
	v_exp_f32_e32 v109, v139
	v_add_f32_e32 v98, v148, v98
	v_add_f32_e32 v98, v144, v98
	v_add_f32_e32 v98, v146, v98
	v_add_f32_e32 v98, v108, v98
	v_add_f32_e32 v98, v109, v98
	v_add_f32_e32 v98, v110, v98
	v_add_f32_e32 v98, v111, v98
	v_add_f32_e32 v98, v112, v98
	v_add_f32_e32 v98, v113, v98
	v_add_f32_e32 v98, v114, v98
	v_add_f32_e32 v98, v115, v98
	v_add_f32_e32 v98, v116, v98
	v_add_f32_e32 v98, v117, v98
	v_add_f32_e32 v98, v118, v98
	v_add_f32_e32 v98, v119, v98
	v_add_f32_e32 v98, v120, v98
	v_add_f32_e32 v98, v121, v98
	v_add_f32_e32 v98, v122, v98
	v_add_f32_e32 v98, v123, v98
	v_mov_b32_e32 v99, v98
	v_cvt_pk_bf16_f32 v100, v177, v226
	v_cvt_pk_bf16_f32 v101, v161, v223
	v_cvt_pk_bf16_f32 v102, v153, v176
	v_cvt_pk_bf16_f32 v103, v152, v160
	s_nop 1
	v_permlane32_swap_b32_e32 v98, v99
	v_permlane32_swap_b32_e32 v100, v102
	v_permlane32_swap_b32_e32 v101, v103
	v_cvt_pk_bf16_f32 v104, v149, v151
	v_cvt_pk_bf16_f32 v105, v147, v150
	v_cvt_pk_bf16_f32 v106, v145, v148
	v_cvt_pk_bf16_f32 v107, v144, v146
	v_cvt_pk_bf16_f32 v108, v108, v109
	v_cvt_pk_bf16_f32 v109, v110, v111
	v_cvt_pk_bf16_f32 v110, v112, v113
	v_cvt_pk_bf16_f32 v111, v114, v115
	v_cvt_pk_bf16_f32 v112, v116, v117
	v_cvt_pk_bf16_f32 v113, v118, v119
	v_cvt_pk_bf16_f32 v114, v120, v121
	v_cvt_pk_bf16_f32 v115, v122, v123
	s_nop 0
	v_permlane32_swap_b32_e32 v104, v106
	v_permlane32_swap_b32_e32 v105, v107
	v_permlane32_swap_b32_e32 v108, v110
	v_permlane32_swap_b32_e32 v109, v111
	v_permlane32_swap_b32_e32 v112, v114
	v_permlane32_swap_b32_e32 v113, v115
	ds_read_b64_tr_b16 v[116:117], v211 offset:0
	ds_read_b64_tr_b16 v[118:119], v211 offset:0x800
	ds_read_b64_tr_b16 v[120:121], v211 offset:0x1000
	ds_read_b64_tr_b16 v[122:123], v211 offset:0x1800
	ds_read_b64_tr_b16 v[124:125], v211 offset:0x2000
	ds_read_b64_tr_b16 v[126:127], v211 offset:0x2800
	ds_read_b64_tr_b16 v[128:129], v211 offset:0x3000
	ds_read_b64_tr_b16 v[130:131], v211 offset:0x3800
	s_waitcnt lgkmcnt(0)
	s_nop 0
	v_mfma_f32_32x32x16_bf16 v[18:33], v[100:103], v[116:119], v[18:33]
	ds_read_b64_tr_b16 v[116:117], v211 offset:0x200
	ds_read_b64_tr_b16 v[118:119], v211 offset:0xa00
	v_mfma_f32_32x32x16_bf16 v[18:33], v[104:107], v[120:123], v[18:33]
	ds_read_b64_tr_b16 v[120:121], v211 offset:0x1200
	ds_read_b64_tr_b16 v[122:123], v211 offset:0x1a00
	v_mfma_f32_32x32x16_bf16 v[18:33], v[108:111], v[124:127], v[18:33]
	ds_read_b64_tr_b16 v[124:125], v211 offset:0x2200
	ds_read_b64_tr_b16 v[126:127], v211 offset:0x2a00
	v_mfma_f32_32x32x16_bf16 v[18:33], v[112:115], v[128:131], v[18:33]
	ds_read_b64_tr_b16 v[128:129], v211 offset:0x3200
	ds_read_b64_tr_b16 v[130:131], v211 offset:0x3a00
	s_waitcnt lgkmcnt(0)
; #define RESC(a) do { if (__any((a) < 1.f)) { if (hi == 0) al_l[r32] = (a); asm volatile("s_waitcnt lgkmcnt(0)" ::: "memory"); \
;     _Pragma("unroll") for (int d = 0; d < 4; ++d) _Pragma("unroll") for (int r = 0; r < 16; ++r) o[d][r] *= al_l[crow(r, hi)]; } } while (0)
; template <int DK, bool NA, bool QL, int SD> ...
;     ...
;   pv_d0(o, vb0, pa0, pa1, pa2, pa3); partialSM(pB0, pB1, m_reg, mnB, alB, C, thrRaw);
;   __syncthreads(); RESC(alB);
	v_mfma_f32_32x32x16_bf16 v[2:17], v[100:103], v[116:119], v[2:17]
	ds_read_b64_tr_b16 v[116:117], v211 offset:0x400
	ds_read_b64_tr_b16 v[118:119], v211 offset:0xc00
	v_mfma_f32_32x32x16_bf16 v[2:17], v[104:107], v[120:123], v[2:17]
	ds_read_b64_tr_b16 v[120:121], v211 offset:0x1400
	ds_read_b64_tr_b16 v[122:123], v211 offset:0x1c00
	v_mfma_f32_32x32x16_bf16 v[2:17], v[108:111], v[124:127], v[2:17]
	ds_read_b64_tr_b16 v[124:125], v211 offset:0x2400
	ds_read_b64_tr_b16 v[126:127], v211 offset:0x2c00
	v_mfma_f32_32x32x16_bf16 v[2:17], v[112:115], v[128:131], v[2:17]
	ds_read_b64_tr_b16 v[128:129], v211 offset:0x3400
	ds_read_b64_tr_b16 v[130:131], v211 offset:0x3c00
	s_waitcnt lgkmcnt(0)
	v_mfma_f32_32x32x16_bf16 v[50:65], v[100:103], v[116:119], v[50:65]
	ds_read_b64_tr_b16 v[116:117], v211 offset:0x600
	ds_read_b64_tr_b16 v[118:119], v211 offset:0xe00
	v_mfma_f32_32x32x16_bf16 v[50:65], v[104:107], v[120:123], v[50:65]
	ds_read_b64_tr_b16 v[120:121], v211 offset:0x1600
	ds_read_b64_tr_b16 v[122:123], v211 offset:0x1e00
	v_mfma_f32_32x32x16_bf16 v[50:65], v[108:111], v[124:127], v[50:65]
	ds_read_b64_tr_b16 v[124:125], v211 offset:0x2600
	ds_read_b64_tr_b16 v[126:127], v211 offset:0x2e00
	v_mfma_f32_32x32x16_bf16 v[50:65], v[112:115], v[128:131], v[50:65]
	ds_read_b64_tr_b16 v[128:129], v211 offset:0x3600
	ds_read_b64_tr_b16 v[130:131], v211 offset:0x3e00
	s_waitcnt lgkmcnt(0)
	v_mfma_f32_32x32x16_bf16 v[34:49], v[100:103], v[116:119], v[34:49]
	v_max_f32_e32 v100, v83, v83
	v_max_f32_e32 v101, v82, v82
	v_max_f32_e32 v100, v101, v100
	v_max3_f32 v100, v100, v84, v85
	v_max3_f32 v100, v100, v86, v87
	v_max3_f32 v100, v100, v88, v89
	v_max3_f32 v100, v100, v90, v91
	v_max3_f32 v100, v100, v92, v93
	v_max3_f32 v100, v100, v94, v95
	v_mfma_f32_32x32x16_bf16 v[34:49], v[104:107], v[120:123], v[34:49]
	v_max3_f32 v100, v100, v96, v97
	v_max3_f32 v100, v100, v66, v67
	v_max3_f32 v100, v100, v68, v69
	v_max3_f32 v100, v100, v70, v71
	v_max3_f32 v100, v100, v72, v73
	v_max3_f32 v100, v100, v74, v75
	v_max3_f32 v100, v100, v76, v77
	v_max3_f32 v100, v100, v78, v79
	v_mfma_f32_32x32x16_bf16 v[34:49], v[108:111], v[124:127], v[34:49]
	v_max3_f32 v100, v100, v80, v81
	v_mov_b32_e32 v101, v100
	s_nop 1
	v_permlane32_swap_b32_e32 v100, v101
	v_max_f32_e32 v101, v101, v101
	v_max_f32_e32 v100, v100, v100
	v_max_f32_e32 v100, v100, v101
	v_sub_f32_e32 v101, v100, v142
	s_mov_b32 s2, 0x42800000
	v_cmp_ge_f32_e32 vcc, s2, v101
	v_max_f32_e32 v101, v142, v142
	v_max_f32_e32 v101, v101, v100
	v_mfma_f32_32x32x16_bf16 v[34:49], v[112:115], v[128:131], v[34:49]
	v_sub_f32_e32 v100, v142, v101
	v_mul_f32_e32 v100, 0x3e38aa3b, v100
	v_exp_f32_e32 v100, v100
	s_cmp_eq_u64 vcc, exec
	s_cselect_b64 s[2:3], -1, 0
	v_cndmask_b32_e64 v100, v100, 1.0, s[2:3]
	v_cmp_gt_f32_e32 vcc, 1.0, v100
	s_barrier
	s_cbranch_vccz .LBB0_698
	s_and_saveexec_b64 s[4:5], s[0:1]
	ds_write_b32 v208, v100 offset:128
	s_or_b64 exec, exec, s[4:5]
	s_waitcnt lgkmcnt(0)
	v_add_u32_e32 v114, v207, v0
	ds_read_b128 v[102:105], v114 offset:224
	ds_read_b128 v[106:109], v114 offset:192
	ds_read_b128 v[110:113], v114 offset:160
	ds_read_b128 v[114:117], v114 offset:128
	s_waitcnt lgkmcnt(3)
	v_pk_mul_f32 v[30:31], v[30:31], v[102:103]
	s_waitcnt lgkmcnt(2)
	v_pk_mul_f32 v[26:27], v[26:27], v[106:107]
	s_waitcnt lgkmcnt(1)
	v_pk_mul_f32 v[22:23], v[22:23], v[110:111]
	v_pk_mul_f32 v[32:33], v[32:33], v[104:105]
	v_pk_mul_f32 v[28:29], v[28:29], v[108:109]
	v_pk_mul_f32 v[24:25], v[24:25], v[112:113]
	s_waitcnt lgkmcnt(0)
	v_pk_mul_f32 v[20:21], v[20:21], v[116:117]
	v_pk_mul_f32 v[18:19], v[18:19], v[114:115]
	v_pk_mul_f32 v[14:15], v[102:103], v[14:15]
	v_pk_mul_f32 v[10:11], v[106:107], v[10:11]
	v_pk_mul_f32 v[6:7], v[110:111], v[6:7]
	v_pk_mul_f32 v[16:17], v[104:105], v[16:17]
	v_pk_mul_f32 v[12:13], v[108:109], v[12:13]
	v_pk_mul_f32 v[8:9], v[112:113], v[8:9]
	v_pk_mul_f32 v[4:5], v[116:117], v[4:5]
	v_pk_mul_f32 v[2:3], v[114:115], v[2:3]
	v_pk_mul_f32 v[62:63], v[102:103], v[62:63]
	v_pk_mul_f32 v[58:59], v[106:107], v[58:59]
	v_pk_mul_f32 v[54:55], v[110:111], v[54:55]
	v_pk_mul_f32 v[64:65], v[104:105], v[64:65]
	v_pk_mul_f32 v[60:61], v[108:109], v[60:61]
	v_pk_mul_f32 v[56:57], v[112:113], v[56:57]
	v_pk_mul_f32 v[52:53], v[116:117], v[52:53]
	v_pk_mul_f32 v[50:51], v[114:115], v[50:51]
	v_pk_mul_f32 v[46:47], v[102:103], v[46:47]
	v_pk_mul_f32 v[42:43], v[106:107], v[42:43]
	v_pk_mul_f32 v[38:39], v[110:111], v[38:39]
	v_pk_mul_f32 v[48:49], v[104:105], v[48:49]
	v_pk_mul_f32 v[44:45], v[108:109], v[44:45]
	v_pk_mul_f32 v[40:41], v[112:113], v[40:41]
	v_pk_mul_f32 v[36:37], v[116:117], v[36:37]
	v_pk_mul_f32 v[34:35], v[114:115], v[34:35]

; #define SBAR() __builtin_amdgcn_sched_barrier(0)
; #define SLOAD(i, k0) do { sr_[i].vs0 = *reinterpret_cast<const bf16x8*>(&Vh[(long)((k0) + sr) * LDP + sc]); sr_[i].vs1 = *reinterpret_cast<const bf16x8*>(&Vh[(long)((k0) + 32 + sr) * LDP + sc]); \
;     sr_[i].ks0 = *reinterpret_cast<const bf16x8*>(&Kh[(long)((k0) + ksr) * LDP + ksc]); if (DK == 128) sr_[i].ks1 = *reinterpret_cast<const bf16x8*>(&Kh[(long)((k0) + 32 + ksr) * LDP + ksc]); } while (0)
; #define HOOK(P0, P1, j) do { if (NA) na_hook(P0, P1, krow0 + (j), q_row, q_col, win_r, win_c, rpb, inv_scale, hi); } while (0)
; __device__ __forceinline__ void finishSM(f32x16& p0, f32x16& p1, float alpha, float& l_reg, bf16x8& pa0, bf16x8& pa1, bf16x8& pa2, bf16x8& pa3) {
; #pragma unroll
;   for (int r = 0; r < 16; ++r) p1[r] = __builtin_amdgcn_exp2f(p1[r]);
;   float ps = 0;
; #pragma unroll
;   for (int r = 0; r < 16; ++r) ps += p0[r];
; #pragma unroll
;   for (int r = 0; r < 16; ++r) ps += p1[r];
;   { auto rr = __builtin_amdgcn_permlane32_swap(__float_as_uint(ps), __float_as_uint(ps), false, false);
;     ps = __uint_as_float(rr[0]) + __uint_as_float(rr[1]); }
;   l_reg = l_reg * alpha + ps;
;     ...
;   PK4(p0, 0, pa0); PK4(p0, 8, pa1); PK4(p1, 0, pa2); PK4(p1, 8, pa3);
;     ...
; }
; template <int DK, bool NA, bool QL, int SD> ...
;     ...
;   for (int j = 1; j + 1 < NT; j += 2) {
;     SBAR(); qkt<DK, QL>(pB0, pB1, (bf16*)((char*)K_lds + SHM_K), qr, ql, r32, hi); HOOK(pB0, pB1, j);
;     finishSM(pA0, pA1, alA, l_reg, pa0, pa1, pa2, pa3); SBAR();
;     SLOAD(SO, (j + SD) * KVBLK); SBAR();
;     pv_d0(o, vb0, pa0, pa1, pa2, pa3); partialSM(pB0, pB1, m_reg, mnB, alB, C, thrRaw);
.LBB0_701:
	ds_read_b128 v[66:69], v215 offset:49152
	ds_read_b128 v[70:73], v215 offset:53248
	v_exp_f32_e32 v143, v138
	v_add_f32_e32 v138, 0, v177
	v_add_f32_e32 v138, v226, v138
	s_waitcnt lgkmcnt(1)
	v_mfma_f32_32x32x16_bf16 v[82:97], v[66:69], v[110:113], 0
	v_add_f32_e32 v138, v161, v138
	v_add_f32_e32 v138, v223, v138
	v_add_f32_e32 v138, v153, v138
	ds_read_b128 v[228:231], v216 offset:49152
	ds_read_b128 v[232:235], v216 offset:53248
	v_add_f32_e32 v138, v176, v138
	v_add_f32_e32 v138, v152, v138
	v_add_f32_e32 v138, v160, v138
	s_waitcnt lgkmcnt(2)
	v_mfma_f32_32x32x16_bf16 v[66:81], v[70:73], v[110:113], 0
	v_add_f32_e32 v138, v149, v138
	v_add_f32_e32 v138, v151, v138
	v_add_f32_e32 v138, v147, v138
	v_add_f32_e32 v138, v150, v138
	v_add_f32_e32 v138, v145, v138
	v_exp_f32_e32 v164, v139
	v_add_f32_e32 v138, v148, v138
	s_waitcnt lgkmcnt(1)
	v_mfma_f32_32x32x16_bf16 v[82:97], v[228:231], v[106:109], v[82:97]
	v_exp_f32_e32 v136, v136
	v_add_f32_e32 v138, v144, v138
	v_exp_f32_e32 v137, v137
	v_add_f32_e32 v138, v146, v138
	v_exp_f32_e32 v130, v130
	v_add_f32_e32 v138, v143, v138
	v_exp_f32_e32 v131, v131
	s_waitcnt lgkmcnt(0)
	v_mfma_f32_32x32x16_bf16 v[66:81], v[232:235], v[106:109], v[66:81]
	ds_read_b128 v[228:231], v217 offset:49152
	ds_read_b128 v[232:235], v217 offset:53248
	v_add_f32_e32 v138, v164, v138
	v_exp_f32_e32 v128, v128
	v_add_f32_e32 v138, v136, v138
	v_exp_f32_e32 v129, v129
	v_add_f32_e32 v138, v137, v138
	v_exp_f32_e32 v126, v126
	s_waitcnt lgkmcnt(1)
	v_mfma_f32_32x32x16_bf16 v[82:97], v[228:231], v[102:105], v[82:97]
	v_add_f32_e32 v138, v130, v138
	v_exp_f32_e32 v127, v127
	v_add_f32_e32 v138, v131, v138
	v_exp_f32_e32 v165, v140
	v_add_f32_e32 v138, v128, v138
	v_exp_f32_e32 v166, v141
	v_add_f32_e32 v138, v129, v138
	s_waitcnt lgkmcnt(0)
	v_mfma_f32_32x32x16_bf16 v[66:81], v[232:235], v[102:105], v[66:81]
	ds_read_b128 v[228:231], v218 offset:49152
	ds_read_b128 v[232:235], v218 offset:53248
	v_exp_f32_e32 v134, v134
	v_add_f32_e32 v138, v126, v138
	v_exp_f32_e32 v135, v135
	v_add_f32_e32 v138, v127, v138
	v_exp_f32_e32 v132, v132
	v_add_f32_e32 v138, v165, v138
	s_waitcnt lgkmcnt(1)
	v_mfma_f32_32x32x16_bf16 v[82:97], v[228:231], v[98:101], v[82:97]
	v_exp_f32_e32 v133, v133
	v_add_f32_e32 v138, v166, v138
	v_add_f32_e32 v138, v134, v138
	v_add_f32_e32 v138, v135, v138
	v_add_f32_e32 v138, v132, v138
	v_add_f32_e32 v220, v133, v138
	v_mov_b32_e32 v221, v220
	s_waitcnt lgkmcnt(0)
	v_mfma_f32_32x32x16_bf16 v[66:81], v[232:235], v[98:101], v[66:81]
	v_cvt_pk_bf16_f32 v138, v177, v226
	v_cvt_pk_bf16_f32 v139, v161, v223
	v_cvt_pk_bf16_f32 v140, v153, v176
	v_cvt_pk_bf16_f32 v141, v152, v160
	v_cvt_pk_bf16_f32 v222, v149, v151
	v_cvt_pk_bf16_f32 v223, v147, v150
	v_cvt_pk_bf16_f32 v224, v145, v148
	v_permlane32_swap_b32_e32 v220, v221
	v_permlane32_swap_b32_e32 v138, v140
	v_cvt_pk_bf16_f32 v225, v144, v146
	v_permlane32_swap_b32_e32 v222, v224
	v_cvt_pk_bf16_f32 v144, v143, v164
	v_cvt_pk_bf16_f32 v145, v136, v137
	v_cvt_pk_bf16_f32 v146, v130, v131
	v_cvt_pk_bf16_f32 v147, v128, v129
	v_cvt_pk_bf16_f32 v148, v126, v127
	v_cvt_pk_bf16_f32 v149, v165, v166
	v_cvt_pk_bf16_f32 v150, v134, v135
	v_cvt_pk_bf16_f32 v151, v132, v133
	v_permlane32_swap_b32_e32 v139, v141
	v_permlane32_swap_b32_e32 v223, v225
	v_permlane32_swap_b32_e32 v144, v146
	v_permlane32_swap_b32_e32 v145, v147
	v_permlane32_swap_b32_e32 v148, v150
	v_permlane32_swap_b32_e32 v149, v151
	v_readlane_b32 s2, v254, 32
	v_readlane_b32 s3, v254, 33
	s_mov_b32 s4, 0xe0e0000
	s_mov_b32 s5, 0xe130000
	v_lshl_add_u64 v[160:161], v[156:157], 0, s[2:3]
	v_add_co_u32_e32 v126, vcc, s4, v160
	v_lshl_add_u64 v[176:177], v[158:159], 0, s[2:3]
	s_nop 0
	v_addc_co_u32_e32 v127, vcc, 0, v161, vcc
	v_add_co_u32_e32 v130, vcc, s5, v160
	s_nop 1
	v_addc_co_u32_e32 v131, vcc, 0, v161, vcc
	v_add_co_u32_e32 v134, vcc, s4, v176
	global_load_dwordx4 v[126:129], v[126:127], off offset:2048
	s_nop 0
	global_load_dwordx4 v[130:133], v[130:131], off offset:2048
	v_addc_co_u32_e32 v135, vcc, 0, v177, vcc
	global_load_dwordx4 v[134:137], v[134:135], off offset:1152
	ds_read_b64_tr_b16 v[226:227], v211 offset:0
	ds_read_b64_tr_b16 v[228:229], v211 offset:0x800
	ds_read_b64_tr_b16 v[230:231], v211 offset:0x1000
	ds_read_b64_tr_b16 v[232:233], v211 offset:0x1800
	ds_read_b64_tr_b16 v[234:235], v211 offset:0x2000
	ds_read_b64_tr_b16 v[236:237], v211 offset:0x2800
	ds_read_b64_tr_b16 v[238:239], v211 offset:0x3000
	ds_read_b64_tr_b16 v[240:241], v211 offset:0x3800
	s_waitcnt lgkmcnt(0)
	s_nop 0
	v_mfma_f32_32x32x16_bf16 v[2:17], v[138:141], v[226:229], v[2:17]
	ds_read_b64_tr_b16 v[226:227], v211 offset:0x200
	ds_read_b64_tr_b16 v[228:229], v211 offset:0xa00
	v_mfma_f32_32x32x16_bf16 v[2:17], v[222:225], v[230:233], v[2:17]
	ds_read_b64_tr_b16 v[230:231], v211 offset:0x1200
	ds_read_b64_tr_b16 v[232:233], v211 offset:0x1a00
	v_mfma_f32_32x32x16_bf16 v[2:17], v[144:147], v[234:237], v[2:17]
	ds_read_b64_tr_b16 v[234:235], v211 offset:0x2200
	ds_read_b64_tr_b16 v[236:237], v211 offset:0x2a00
	v_mfma_f32_32x32x16_bf16 v[2:17], v[148:151], v[238:241], v[2:17]
	ds_read_b64_tr_b16 v[238:239], v211 offset:0x3200
	ds_read_b64_tr_b16 v[240:241], v211 offset:0x3a00
	s_waitcnt lgkmcnt(0)
	v_mfma_f32_32x32x16_bf16 v[50:65], v[138:141], v[226:229], v[50:65]
	ds_read_b64_tr_b16 v[226:227], v211 offset:0x400
	ds_read_b64_tr_b16 v[228:229], v211 offset:0xc00
	v_mfma_f32_32x32x16_bf16 v[50:65], v[222:225], v[230:233], v[50:65]
	ds_read_b64_tr_b16 v[230:231], v211 offset:0x1400
	ds_read_b64_tr_b16 v[232:233], v211 offset:0x1c00
	v_mfma_f32_32x32x16_bf16 v[50:65], v[144:147], v[234:237], v[50:65]
	ds_read_b64_tr_b16 v[234:235], v211 offset:0x2400
	ds_read_b64_tr_b16 v[236:237], v211 offset:0x2c00
	v_mfma_f32_32x32x16_bf16 v[50:65], v[148:151], v[238:241], v[50:65]
	ds_read_b64_tr_b16 v[238:239], v211 offset:0x3400
	ds_read_b64_tr_b16 v[240:241], v211 offset:0x3c00
	s_waitcnt lgkmcnt(0)
; #define SWAIT() do { if (SD == 1) asm volatile("s_waitcnt vmcnt(0)" ::: "memory"); else if (DK == 128) asm volatile("s_waitcnt vmcnt(4)" ::: "memory"); else asm volatile("s_waitcnt vmcnt(3)" ::: "memory"); } while (0)
; #define RESC(a) do { if (__any((a) < 1.f)) { if (hi == 0) al_l[r32] = (a); asm volatile("s_waitcnt lgkmcnt(0)" ::: "memory"); \
;     _Pragma("unroll") for (int d = 0; d < 4; ++d) _Pragma("unroll") for (int r = 0; r < 16; ++r) o[d][r] *= al_l[crow(r, hi)]; } } while (0)
; __device__ __forceinline__ void partialSM(f32x16& p0, f32x16& p1, float& m_reg, float& mn, float& alpha, float C, float thrRaw) {
;   float pmax = p0[0];
; #pragma unroll
;   for (int r = 1; r < 16; ++r) pmax = fmaxf(pmax, p0[r]);
; #pragma unroll
;   for (int r = 0; r < 16; ++r) pmax = fmaxf(pmax, p1[r]);
;   { auto rr = __builtin_amdgcn_permlane32_swap(__float_as_uint(pmax), __float_as_uint(pmax), false, false);
;     pmax = fmaxf(__uint_as_float(rr[0]), __uint_as_float(rr[1])); }
;   if (__builtin_expect(__all(pmax - m_reg <= thrRaw), 1)) { mn = m_reg; alpha = 1.f; }
;   else { mn = fmaxf(m_reg, pmax); alpha = __builtin_amdgcn_exp2f((m_reg - mn) * C); m_reg = mn; }
;   float mnC = -mn * C;
; #pragma unroll
;   for (int r = 0; r < 16; ++r) p0[r] = fmaf(p0[r], C, mnC);
; #pragma unroll
;   for (int r = 0; r < 16; ++r) p1[r] = fmaf(p1[r], C, mnC);
; #pragma unroll
;   for (int r = 0; r < 16; ++r) p0[r] = __builtin_amdgcn_exp2f(p0[r]);
; template <int DK, bool NA, bool QL, int SD> ...
;     ...
;     pv_d0(o, vb0, pa0, pa1, pa2, pa3); partialSM(pB0, pB1, m_reg, mnB, alB, C, thrRaw);
;     __syncthreads(); SWAIT(); SWRITE(0, SE);
;     RESC(alB); __syncthreads();
	v_mfma_f32_32x32x16_bf16 v[34:49], v[138:141], v[226:229], v[34:49]
	ds_read_b64_tr_b16 v[226:227], v211 offset:0x600
	ds_read_b64_tr_b16 v[228:229], v211 offset:0xe00
	v_mfma_f32_32x32x16_bf16 v[34:49], v[222:225], v[230:233], v[34:49]
	ds_read_b64_tr_b16 v[230:231], v211 offset:0x1600
	ds_read_b64_tr_b16 v[232:233], v211 offset:0x1e00
	v_mfma_f32_32x32x16_bf16 v[34:49], v[144:147], v[234:237], v[34:49]
	ds_read_b64_tr_b16 v[234:235], v211 offset:0x2600
	ds_read_b64_tr_b16 v[236:237], v211 offset:0x2e00
	v_mfma_f32_32x32x16_bf16 v[34:49], v[148:151], v[238:241], v[34:49]
	ds_read_b64_tr_b16 v[238:239], v211 offset:0x3600
	ds_read_b64_tr_b16 v[240:241], v211 offset:0x3e00
	s_waitcnt lgkmcnt(0)
	v_mfma_f32_32x32x16_bf16 v[18:33], v[138:141], v[226:229], v[18:33]
	v_max_f32_e32 v138, v83, v83
	v_max_f32_e32 v139, v82, v82
	v_max_f32_e32 v138, v139, v138
	v_max3_f32 v138, v138, v84, v85
	v_max3_f32 v138, v138, v86, v87
	v_max3_f32 v138, v138, v88, v89
	v_max3_f32 v138, v138, v90, v91
	v_max3_f32 v138, v138, v92, v93
	v_max3_f32 v138, v138, v94, v95
	v_mfma_f32_32x32x16_bf16 v[18:33], v[222:225], v[230:233], v[18:33]
	v_max3_f32 v138, v138, v96, v97
	v_max3_f32 v138, v138, v66, v67
	v_max3_f32 v138, v138, v68, v69
	v_max3_f32 v138, v138, v70, v71
	v_max3_f32 v138, v138, v72, v73
	v_max3_f32 v138, v138, v74, v75
	v_max3_f32 v138, v138, v76, v77
	v_max3_f32 v138, v138, v78, v79
	v_mfma_f32_32x32x16_bf16 v[18:33], v[144:147], v[234:237], v[18:33]
	v_max3_f32 v138, v138, v80, v81
	v_mov_b32_e32 v139, v138
	s_nop 1
	v_permlane32_swap_b32_e32 v138, v139
	v_max_f32_e32 v139, v139, v139
	v_max_f32_e32 v138, v138, v138
	v_max_f32_e32 v138, v138, v139
	v_sub_f32_e32 v139, v138, v142
	s_mov_b32 s2, 0x42800000
	v_cmp_ge_f32_e32 vcc, s2, v139
	v_max_f32_e32 v139, v142, v142
	v_max_f32_e32 v138, v139, v138
	v_mfma_f32_32x32x16_bf16 v[18:33], v[148:151], v[238:241], v[18:33]
	v_sub_f32_e32 v139, v142, v138
	v_mul_f32_e32 v139, 0x3e38aa3b, v139
	v_exp_f32_e32 v139, v139
	s_cmp_eq_u64 vcc, exec
	s_cselect_b64 s[2:3], -1, 0
	s_waitcnt vmcnt(3)
	v_cndmask_b32_e64 v222, v139, 1.0, s[2:3]
	v_cmp_gt_f32_e32 vcc, 1.0, v222
	s_waitcnt vmcnt(3)
	ds_write_b128 v214, v[122:125] offset:32768
	s_cbranch_vccz .LBB0_705
	s_and_saveexec_b64 s[4:5], s[0:1]
	ds_write_b32 v208, v222 offset:128
	s_or_b64 exec, exec, s[4:5]
	s_waitcnt lgkmcnt(0)
	v_add_u32_e32 v139, v207, v0
	ds_read_b128 v[144:147], v139 offset:224
	ds_read_b128 v[148:151], v139 offset:192
	ds_read_b128 v[224:227], v139 offset:160
	ds_read_b128 v[228:231], v139 offset:128
	s_waitcnt lgkmcnt(3)
	v_pk_mul_f32 v[14:15], v[14:15], v[144:145]
	s_waitcnt lgkmcnt(2)
	v_pk_mul_f32 v[10:11], v[10:11], v[148:149]
	s_waitcnt lgkmcnt(1)
	v_pk_mul_f32 v[6:7], v[6:7], v[224:225]
	v_pk_mul_f32 v[16:17], v[16:17], v[146:147]
	v_pk_mul_f32 v[12:13], v[12:13], v[150:151]
	v_pk_mul_f32 v[8:9], v[8:9], v[226:227]
	s_waitcnt lgkmcnt(0)
	v_pk_mul_f32 v[4:5], v[4:5], v[230:231]
	v_pk_mul_f32 v[2:3], v[2:3], v[228:229]
	v_pk_mul_f32 v[62:63], v[144:145], v[62:63]
	v_pk_mul_f32 v[58:59], v[148:149], v[58:59]
	v_pk_mul_f32 v[54:55], v[224:225], v[54:55]
	v_pk_mul_f32 v[64:65], v[146:147], v[64:65]
	v_pk_mul_f32 v[60:61], v[150:151], v[60:61]
	v_pk_mul_f32 v[56:57], v[226:227], v[56:57]
	v_pk_mul_f32 v[52:53], v[230:231], v[52:53]
	v_pk_mul_f32 v[50:51], v[228:229], v[50:51]
	v_pk_mul_f32 v[46:47], v[144:145], v[46:47]
	v_pk_mul_f32 v[42:43], v[148:149], v[42:43]
	v_pk_mul_f32 v[38:39], v[224:225], v[38:39]
	v_pk_mul_f32 v[48:49], v[146:147], v[48:49]
	v_pk_mul_f32 v[44:45], v[150:151], v[44:45]
	v_pk_mul_f32 v[40:41], v[226:227], v[40:41]
	v_pk_mul_f32 v[36:37], v[230:231], v[36:37]
	v_pk_mul_f32 v[34:35], v[228:229], v[34:35]
	v_pk_mul_f32 v[30:31], v[144:145], v[30:31]
	v_pk_mul_f32 v[26:27], v[148:149], v[26:27]
	v_pk_mul_f32 v[22:23], v[224:225], v[22:23]
	v_pk_mul_f32 v[32:33], v[146:147], v[32:33]
	v_pk_mul_f32 v[28:29], v[150:151], v[28:29]
	v_pk_mul_f32 v[24:25], v[226:227], v[24:25]
	v_pk_mul_f32 v[20:21], v[230:231], v[20:21]
	v_pk_mul_f32 v[18:19], v[228:229], v[18:19]
.LBB0_705:
	v_cndmask_b32_e64 v223, v138, v142, s[2:3]
	v_mul_f32_e32 v224, 0xbe38aa3b, v223
	v_fmamk_f32 v82, v82, 0x3e38aa3b, v224
	v_fmamk_f32 v83, v83, 0x3e38aa3b, v224
	v_fmamk_f32 v84, v84, 0x3e38aa3b, v224
	v_fmamk_f32 v85, v85, 0x3e38aa3b, v224
	v_fmamk_f32 v86, v86, 0x3e38aa3b, v224
	v_fmamk_f32 v87, v87, 0x3e38aa3b, v224
	v_fmamk_f32 v88, v88, 0x3e38aa3b, v224
	v_fmamk_f32 v89, v89, 0x3e38aa3b, v224
	v_fmamk_f32 v90, v90, 0x3e38aa3b, v224
	v_fmamk_f32 v91, v91, 0x3e38aa3b, v224
	v_fmamk_f32 v92, v92, 0x3e38aa3b, v224
	v_fmamk_f32 v93, v93, 0x3e38aa3b, v224
	v_fmamk_f32 v94, v94, 0x3e38aa3b, v224
	v_fmamk_f32 v95, v95, 0x3e38aa3b, v224
	v_fmamk_f32 v96, v96, 0x3e38aa3b, v224
	v_fmamk_f32 v97, v97, 0x3e38aa3b, v224
	v_exp_f32_e32 v138, v82
	v_exp_f32_e32 v153, v83
	v_exp_f32_e32 v139, v84
	v_exp_f32_e32 v152, v85
	v_exp_f32_e32 v140, v86
	v_exp_f32_e32 v151, v87
	v_exp_f32_e32 v141, v88
	v_exp_f32_e32 v150, v89
	v_exp_f32_e32 v142, v90
	v_exp_f32_e32 v149, v91
	v_exp_f32_e32 v143, v92
	v_exp_f32_e32 v148, v93
	v_exp_f32_e32 v144, v94
	v_exp_f32_e32 v147, v95
	v_exp_f32_e32 v145, v96
	v_exp_f32_e32 v146, v97
	v_fmamk_f32 v233, v66, 0x3e38aa3b, v224
	v_fmamk_f32 v234, v67, 0x3e38aa3b, v224
	v_fmamk_f32 v235, v68, 0x3e38aa3b, v224
	v_fmamk_f32 v236, v69, 0x3e38aa3b, v224
	v_fmamk_f32 v237, v70, 0x3e38aa3b, v224
	v_fmamk_f32 v226, v71, 0x3e38aa3b, v224
	v_fmamk_f32 v227, v72, 0x3e38aa3b, v224
	v_fmamk_f32 v228, v73, 0x3e38aa3b, v224
	v_fmamk_f32 v229, v74, 0x3e38aa3b, v224
	v_fmamk_f32 v230, v75, 0x3e38aa3b, v224
	v_fmamk_f32 v231, v76, 0x3e38aa3b, v224
	v_fmamk_f32 v232, v77, 0x3e38aa3b, v224
	v_fmamk_f32 v225, v78, 0x3e38aa3b, v224
	v_fmamk_f32 v238, v79, 0x3e38aa3b, v224
	v_fmamk_f32 v239, v80, 0x3e38aa3b, v224
	v_fmac_f32_e32 v224, 0x3e38aa3b, v81
	s_waitcnt lgkmcnt(0)
	s_barrier
; #define SBAR() __builtin_amdgcn_sched_barrier(0)
; #define SLOAD(i, k0) do { sr_[i].vs0 = *reinterpret_cast<const bf16x8*>(&Vh[(long)((k0) + sr) * LDP + sc]); sr_[i].vs1 = *reinterpret_cast<const bf16x8*>(&Vh[(long)((k0) + 32 + sr) * LDP + sc]); \
;     sr_[i].ks0 = *reinterpret_cast<const bf16x8*>(&Kh[(long)((k0) + ksr) * LDP + ksc]); if (DK == 128) sr_[i].ks1 = *reinterpret_cast<const bf16x8*>(&Kh[(long)((k0) + 32 + ksr) * LDP + ksc]); } while (0)
; #define HOOK(P0, P1, j) do { if (NA) na_hook(P0, P1, krow0 + (j), q_row, q_col, win_r, win_c, rpb, inv_scale, hi); } while (0)
; __device__ __forceinline__ void finishSM(f32x16& p0, f32x16& p1, float alpha, float& l_reg, bf16x8& pa0, bf16x8& pa1, bf16x8& pa2, bf16x8& pa3) {
; #pragma unroll
;   for (int r = 0; r < 16; ++r) p1[r] = __builtin_amdgcn_exp2f(p1[r]);
;   float ps = 0;
; #pragma unroll
;   for (int r = 0; r < 16; ++r) ps += p0[r];
; #pragma unroll
;   for (int r = 0; r < 16; ++r) ps += p1[r];
;   { auto rr = __builtin_amdgcn_permlane32_swap(__float_as_uint(ps), __float_as_uint(ps), false, false);
;     ps = __uint_as_float(rr[0]) + __uint_as_float(rr[1]); }
;   l_reg = l_reg * alpha + ps;
;     ...
;   PK4(p0, 0, pa0); PK4(p0, 8, pa1); PK4(p1, 0, pa2); PK4(p1, 8, pa3);
;     ...
; }
; template <int DK, bool NA, bool QL, int SD> ...
;     ...
;     SBAR(); qkt<DK, QL>(pA0, pA1, K_lds, qr, ql, r32, hi); HOOK(pA0, pA1, j + 1);
;     finishSM(pB0, pB1, alB, l_reg, pa0, pa1, pa2, pa3); SBAR();
;     if (SD == 1 || j + 3 < NT) SLOAD(SE, (j + 1 + SD) * KVBLK); SBAR();
;     pv_d0(o, vb0 + (int)SHM_V, pa0, pa1, pa2, pa3); partialSM(pA0, pA1, m_reg, mnA, alA, C, thrRaw);
	ds_write_b128 v212, v[114:117]
	ds_write_b128 v213, v[118:121]
	ds_read_b128 v[66:69], v215 offset:32768
	ds_read_b128 v[70:73], v215 offset:36864
	v_exp_f32_e32 v164, v233
	v_exp_f32_e32 v233, v224
	v_add_f32_e32 v224, 0, v138
	v_add_f32_e32 v224, v153, v224
	s_waitcnt lgkmcnt(1)
	v_mfma_f32_32x32x16_bf16 v[82:97], v[66:69], v[110:113], 0
	v_add_f32_e32 v224, v139, v224
	v_add_f32_e32 v224, v152, v224
	v_add_f32_e32 v224, v140, v224
	ds_read_b128 v[240:243], v216 offset:32768
	ds_read_b128 v[244:247], v216 offset:36864
	v_add_f32_e32 v224, v151, v224
	v_add_f32_e32 v224, v141, v224
	v_add_f32_e32 v224, v150, v224
	s_waitcnt lgkmcnt(2)
	v_mfma_f32_32x32x16_bf16 v[66:81], v[70:73], v[110:113], 0
	v_add_f32_e32 v224, v142, v224
	v_add_f32_e32 v224, v149, v224
	v_add_f32_e32 v224, v143, v224
	v_add_f32_e32 v224, v148, v224
	v_add_f32_e32 v224, v144, v224
	v_exp_f32_e32 v165, v234
	v_add_f32_e32 v224, v147, v224
	s_waitcnt lgkmcnt(1)
	v_mfma_f32_32x32x16_bf16 v[82:97], v[240:243], v[106:109], v[82:97]
	v_exp_f32_e32 v166, v235
	v_add_f32_e32 v224, v145, v224
	v_exp_f32_e32 v167, v236
	v_add_f32_e32 v224, v146, v224
	v_exp_f32_e32 v172, v237
	v_add_f32_e32 v224, v164, v224
	v_exp_f32_e32 v173, v226
	s_waitcnt lgkmcnt(0)
	v_mfma_f32_32x32x16_bf16 v[66:81], v[244:247], v[106:109], v[66:81]
	ds_read_b128 v[240:243], v217 offset:32768
	ds_read_b128 v[244:247], v217 offset:36864
	v_add_f32_e32 v224, v165, v224
	v_exp_f32_e32 v174, v227
	v_add_f32_e32 v224, v166, v224
	v_exp_f32_e32 v175, v228
	v_add_f32_e32 v224, v167, v224
	v_exp_f32_e32 v226, v229
	s_waitcnt lgkmcnt(1)
	v_mfma_f32_32x32x16_bf16 v[82:97], v[240:243], v[102:105], v[82:97]
	v_add_f32_e32 v224, v172, v224
	v_exp_f32_e32 v227, v230
	v_add_f32_e32 v224, v173, v224
	v_exp_f32_e32 v228, v231
	v_add_f32_e32 v224, v174, v224
	v_exp_f32_e32 v229, v232
	v_add_f32_e32 v224, v175, v224
	s_waitcnt lgkmcnt(0)
	v_mfma_f32_32x32x16_bf16 v[66:81], v[244:247], v[102:105], v[66:81]
	ds_read_b128 v[240:243], v218 offset:32768
	ds_read_b128 v[244:247], v218 offset:36864
	v_exp_f32_e32 v230, v225
	v_add_f32_e32 v224, v226, v224
	v_exp_f32_e32 v231, v238
	v_add_f32_e32 v224, v227, v224
	v_exp_f32_e32 v232, v239
	v_add_f32_e32 v224, v228, v224
	s_waitcnt lgkmcnt(1)
	v_mfma_f32_32x32x16_bf16 v[82:97], v[240:243], v[98:101], v[82:97]
	v_add_f32_e32 v224, v229, v224
	v_add_f32_e32 v224, v230, v224
	v_add_f32_e32 v224, v231, v224
	v_add_f32_e32 v224, v232, v224
	v_add_f32_e32 v224, v233, v224
	v_mov_b32_e32 v225, v224
	v_cvt_pk_bf16_f32 v138, v138, v153
	s_waitcnt lgkmcnt(0)
	v_mfma_f32_32x32x16_bf16 v[66:81], v[244:247], v[98:101], v[66:81]
	v_cvt_pk_bf16_f32 v139, v139, v152
	v_cvt_pk_bf16_f32 v140, v140, v151
	v_cvt_pk_bf16_f32 v141, v141, v150
	v_cvt_pk_bf16_f32 v142, v142, v149
	v_cvt_pk_bf16_f32 v143, v143, v148
	v_cvt_pk_bf16_f32 v144, v144, v147
	v_cvt_pk_bf16_f32 v145, v145, v146
	v_cvt_pk_bf16_f32 v146, v164, v165
	v_cvt_pk_bf16_f32 v147, v166, v167
	v_cvt_pk_bf16_f32 v148, v172, v173
	v_cvt_pk_bf16_f32 v149, v174, v175
	v_cvt_pk_bf16_f32 v150, v226, v227
	v_cvt_pk_bf16_f32 v151, v228, v229
	v_cvt_pk_bf16_f32 v152, v230, v231
	v_cvt_pk_bf16_f32 v153, v232, v233
	v_permlane32_swap_b32_e32 v224, v225
	v_permlane32_swap_b32_e32 v138, v140
	v_permlane32_swap_b32_e32 v139, v141
	v_permlane32_swap_b32_e32 v142, v144
	v_permlane32_swap_b32_e32 v143, v145
	v_permlane32_swap_b32_e32 v146, v148
	v_permlane32_swap_b32_e32 v147, v149
	v_permlane32_swap_b32_e32 v150, v152
	v_permlane32_swap_b32_e32 v151, v153
	s_cmp_gt_u32 s8, 60
	s_cselect_b64 s[4:5], -1, 0
	s_and_b64 vcc, exec, s[4:5]
	s_cbranch_vccnz .Lod_d2
	v_add_co_u32_e32 v114, vcc, 0xe180000, v160
	s_nop 1
	v_addc_co_u32_e32 v115, vcc, 0, v161, vcc
	v_add_co_u32_e32 v118, vcc, 0xe1d0000, v160
	s_nop 1
	v_addc_co_u32_e32 v119, vcc, 0, v161, vcc
	v_add_co_u32_e32 v122, vcc, 0xe180000, v176
	global_load_dwordx4 v[114:117], v[114:115], off offset:2048
	s_nop 0
	global_load_dwordx4 v[118:121], v[118:119], off offset:2048
	v_addc_co_u32_e32 v123, vcc, 0, v177, vcc
	global_load_dwordx4 v[122:125], v[122:123], off offset:1152
.LBB0_707:
	ds_read_b64_tr_b16 v[226:227], v210 offset:0
	ds_read_b64_tr_b16 v[228:229], v210 offset:0x800
	ds_read_b64_tr_b16 v[230:231], v210 offset:0x1000
	ds_read_b64_tr_b16 v[232:233], v210 offset:0x1800
	ds_read_b64_tr_b16 v[234:235], v210 offset:0x2000
	ds_read_b64_tr_b16 v[236:237], v210 offset:0x2800
	ds_read_b64_tr_b16 v[238:239], v210 offset:0x3000
	ds_read_b64_tr_b16 v[240:241], v210 offset:0x3800
	s_waitcnt lgkmcnt(0)
	s_nop 0
	v_mfma_f32_32x32x16_bf16 v[2:17], v[138:141], v[226:229], v[2:17]
	ds_read_b64_tr_b16 v[226:227], v210 offset:0x200
	ds_read_b64_tr_b16 v[228:229], v210 offset:0xa00
	v_mfma_f32_32x32x16_bf16 v[2:17], v[142:145], v[230:233], v[2:17]
	ds_read_b64_tr_b16 v[230:231], v210 offset:0x1200
	ds_read_b64_tr_b16 v[232:233], v210 offset:0x1a00
	v_mfma_f32_32x32x16_bf16 v[2:17], v[146:149], v[234:237], v[2:17]
	ds_read_b64_tr_b16 v[234:235], v210 offset:0x2200
	ds_read_b64_tr_b16 v[236:237], v210 offset:0x2a00
	v_mfma_f32_32x32x16_bf16 v[2:17], v[150:153], v[238:241], v[2:17]
	ds_read_b64_tr_b16 v[238:239], v210 offset:0x3200
	ds_read_b64_tr_b16 v[240:241], v210 offset:0x3a00
	s_waitcnt lgkmcnt(0)
	v_mfma_f32_32x32x16_bf16 v[50:65], v[138:141], v[226:229], v[50:65]
	ds_read_b64_tr_b16 v[226:227], v210 offset:0x400
	ds_read_b64_tr_b16 v[228:229], v210 offset:0xc00
	v_mfma_f32_32x32x16_bf16 v[50:65], v[142:145], v[230:233], v[50:65]
	ds_read_b64_tr_b16 v[230:231], v210 offset:0x1400
	ds_read_b64_tr_b16 v[232:233], v210 offset:0x1c00
	v_mfma_f32_32x32x16_bf16 v[50:65], v[146:149], v[234:237], v[50:65]
	ds_read_b64_tr_b16 v[234:235], v210 offset:0x2400
	ds_read_b64_tr_b16 v[236:237], v210 offset:0x2c00
	v_mfma_f32_32x32x16_bf16 v[50:65], v[150:153], v[238:241], v[50:65]
	ds_read_b64_tr_b16 v[238:239], v210 offset:0x3400
	ds_read_b64_tr_b16 v[240:241], v210 offset:0x3c00
	s_waitcnt lgkmcnt(0)
; #define SWAIT() do { if (SD == 1) asm volatile("s_waitcnt vmcnt(0)" ::: "memory"); else if (DK == 128) asm volatile("s_waitcnt vmcnt(4)" ::: "memory"); else asm volatile("s_waitcnt vmcnt(3)" ::: "memory"); } while (0)
; #define RESC(a) do { if (__any((a) < 1.f)) { if (hi == 0) al_l[r32] = (a); asm volatile("s_waitcnt lgkmcnt(0)" ::: "memory"); \
;     _Pragma("unroll") for (int d = 0; d < 4; ++d) _Pragma("unroll") for (int r = 0; r < 16; ++r) o[d][r] *= al_l[crow(r, hi)]; } } while (0)
; __device__ __forceinline__ void partialSM(f32x16& p0, f32x16& p1, float& m_reg, float& mn, float& alpha, float C, float thrRaw) {
;   float pmax = p0[0];
; #pragma unroll
;   for (int r = 1; r < 16; ++r) pmax = fmaxf(pmax, p0[r]);
; #pragma unroll
;   for (int r = 0; r < 16; ++r) pmax = fmaxf(pmax, p1[r]);
;   { auto rr = __builtin_amdgcn_permlane32_swap(__float_as_uint(pmax), __float_as_uint(pmax), false, false);
;     pmax = fmaxf(__uint_as_float(rr[0]), __uint_as_float(rr[1])); }
;   if (__builtin_expect(__all(pmax - m_reg <= thrRaw), 1)) { mn = m_reg; alpha = 1.f; }
;   else { mn = fmaxf(m_reg, pmax); alpha = __builtin_amdgcn_exp2f((m_reg - mn) * C); m_reg = mn; }
;   float mnC = -mn * C;
; #pragma unroll
;   for (int r = 0; r < 16; ++r) p0[r] = fmaf(p0[r], C, mnC);
; #pragma unroll
;   for (int r = 0; r < 16; ++r) p1[r] = fmaf(p1[r], C, mnC);
; #pragma unroll
;   for (int r = 0; r < 16; ++r) p0[r] = __builtin_amdgcn_exp2f(p0[r]);
; template <int DK, bool NA, bool QL, int SD> ...
;     ...
;     pv_d0(o, vb0 + (int)SHM_V, pa0, pa1, pa2, pa3); partialSM(pA0, pA1, m_reg, mnA, alA, C, thrRaw);
;     __syncthreads(); SWAIT(); SWRITE(1, SO);
;     RESC(alA); __syncthreads();
	v_mfma_f32_32x32x16_bf16 v[34:49], v[138:141], v[226:229], v[34:49]
	ds_read_b64_tr_b16 v[226:227], v210 offset:0x600
	ds_read_b64_tr_b16 v[228:229], v210 offset:0xe00
	v_mfma_f32_32x32x16_bf16 v[34:49], v[142:145], v[230:233], v[34:49]
	ds_read_b64_tr_b16 v[230:231], v210 offset:0x1600
	ds_read_b64_tr_b16 v[232:233], v210 offset:0x1e00
	v_mfma_f32_32x32x16_bf16 v[34:49], v[146:149], v[234:237], v[34:49]
	ds_read_b64_tr_b16 v[234:235], v210 offset:0x2600
	ds_read_b64_tr_b16 v[236:237], v210 offset:0x2e00
	v_mfma_f32_32x32x16_bf16 v[34:49], v[150:153], v[238:241], v[34:49]
	ds_read_b64_tr_b16 v[238:239], v210 offset:0x3600
	ds_read_b64_tr_b16 v[240:241], v210 offset:0x3e00
	s_waitcnt lgkmcnt(0)
	v_mfma_f32_32x32x16_bf16 v[18:33], v[138:141], v[226:229], v[18:33]
	v_max_f32_e32 v138, v83, v83
	v_max_f32_e32 v139, v82, v82
	v_max_f32_e32 v138, v139, v138
	v_max3_f32 v138, v138, v84, v85
	v_max3_f32 v138, v138, v86, v87
	v_max3_f32 v138, v138, v88, v89
	v_max3_f32 v138, v138, v90, v91
	v_max3_f32 v138, v138, v92, v93
	v_max3_f32 v138, v138, v94, v95
	v_mfma_f32_32x32x16_bf16 v[18:33], v[142:145], v[230:233], v[18:33]
	v_max3_f32 v138, v138, v96, v97
	v_max3_f32 v138, v138, v66, v67
	v_max3_f32 v138, v138, v68, v69
	v_max3_f32 v138, v138, v70, v71
	v_max3_f32 v138, v138, v72, v73
	v_max3_f32 v138, v138, v74, v75
	v_max3_f32 v138, v138, v76, v77
	v_max3_f32 v138, v138, v78, v79
	v_mfma_f32_32x32x16_bf16 v[18:33], v[146:149], v[234:237], v[18:33]
	v_max3_f32 v138, v138, v80, v81
	v_mov_b32_e32 v139, v138
	s_nop 1
	v_permlane32_swap_b32_e32 v138, v139
	v_max_f32_e32 v139, v139, v139
	v_max_f32_e32 v138, v138, v138
	v_max_f32_e32 v138, v138, v139
	v_sub_f32_e32 v139, v138, v223
	s_mov_b32 s2, 0x42800000
	v_cmp_ge_f32_e32 vcc, s2, v139
	v_max_f32_e32 v139, v223, v223
	v_max_f32_e32 v138, v139, v138
	v_mfma_f32_32x32x16_bf16 v[18:33], v[150:153], v[238:241], v[18:33]
	v_sub_f32_e32 v139, v223, v138
	v_mul_f32_e32 v139, 0x3e38aa3b, v139
	v_exp_f32_e32 v139, v139
	s_cmp_eq_u64 vcc, exec
	s_cselect_b64 s[2:3], -1, 0
	s_waitcnt vmcnt(3)
	v_cndmask_b32_e64 v143, v139, 1.0, s[2:3]
	v_cmp_gt_f32_e32 vcc, 1.0, v143
	v_mov_b64_e32 v[182:183], v[126:127]
	v_mov_b64_e32 v[184:185], v[128:129]
	v_mov_b64_e32 v[194:195], v[130:131]
	v_mov_b64_e32 v[196:197], v[132:133]
	ds_write_b128 v214, v[134:137] offset:49152
	s_cbranch_vccz .LBB0_711
	s_and_saveexec_b64 s[6:7], s[0:1]
	ds_write_b32 v208, v143 offset:128
	s_or_b64 exec, exec, s[6:7]
	s_waitcnt lgkmcnt(0)
	v_add_u32_e32 v139, v207, v0
	ds_read_b128 v[126:129], v139 offset:224
	ds_read_b128 v[130:133], v139 offset:192
	ds_read_b128 v[134:137], v139 offset:160
	ds_read_b128 v[144:147], v139 offset:128
	s_waitcnt lgkmcnt(3)
	v_pk_mul_f32 v[14:15], v[14:15], v[126:127]
	s_waitcnt lgkmcnt(2)
	v_pk_mul_f32 v[10:11], v[10:11], v[130:131]
	s_waitcnt lgkmcnt(1)
	v_pk_mul_f32 v[6:7], v[6:7], v[134:135]
	v_pk_mul_f32 v[16:17], v[16:17], v[128:129]
	v_pk_mul_f32 v[12:13], v[12:13], v[132:133]
	v_pk_mul_f32 v[8:9], v[8:9], v[136:137]
	s_waitcnt lgkmcnt(0)
	v_pk_mul_f32 v[4:5], v[4:5], v[146:147]
	v_pk_mul_f32 v[2:3], v[2:3], v[144:145]
	v_pk_mul_f32 v[62:63], v[126:127], v[62:63]
	v_pk_mul_f32 v[58:59], v[130:131], v[58:59]
	v_pk_mul_f32 v[54:55], v[134:135], v[54:55]
	v_pk_mul_f32 v[64:65], v[128:129], v[64:65]
	v_pk_mul_f32 v[60:61], v[132:133], v[60:61]
	v_pk_mul_f32 v[56:57], v[136:137], v[56:57]
	v_pk_mul_f32 v[52:53], v[146:147], v[52:53]
	v_pk_mul_f32 v[50:51], v[144:145], v[50:51]
	v_pk_mul_f32 v[46:47], v[126:127], v[46:47]
	v_pk_mul_f32 v[42:43], v[130:131], v[42:43]
	v_pk_mul_f32 v[38:39], v[134:135], v[38:39]
	v_pk_mul_f32 v[48:49], v[128:129], v[48:49]
	v_pk_mul_f32 v[44:45], v[132:133], v[44:45]
	v_pk_mul_f32 v[40:41], v[136:137], v[40:41]
	v_pk_mul_f32 v[36:37], v[146:147], v[36:37]
	v_pk_mul_f32 v[34:35], v[144:145], v[34:35]
	v_pk_mul_f32 v[30:31], v[126:127], v[30:31]
	v_pk_mul_f32 v[26:27], v[130:131], v[26:27]
	v_pk_mul_f32 v[22:23], v[134:135], v[22:23]
	v_pk_mul_f32 v[32:33], v[128:129], v[32:33]
	v_pk_mul_f32 v[28:29], v[132:133], v[28:29]
	v_pk_mul_f32 v[24:25], v[136:137], v[24:25]
	v_pk_mul_f32 v[20:21], v[146:147], v[20:21]
	v_pk_mul_f32 v[18:19], v[144:145], v[18:19]
.LBB0_711:
	v_cndmask_b32_e64 v142, v138, v223, s[2:3]
	v_mul_f32_e32 v132, 0xbe38aa3b, v142
	v_mov_b32_e32 v133, v132
	v_fmamk_f32 v82, v82, 0x3e38aa3b, v132
	v_fmamk_f32 v83, v83, 0x3e38aa3b, v132
	v_fmamk_f32 v84, v84, 0x3e38aa3b, v132
	v_fmamk_f32 v85, v85, 0x3e38aa3b, v132
	v_fmamk_f32 v86, v86, 0x3e38aa3b, v132
	v_fmamk_f32 v87, v87, 0x3e38aa3b, v132
	v_fmamk_f32 v88, v88, 0x3e38aa3b, v132
	v_fmamk_f32 v89, v89, 0x3e38aa3b, v132
	v_fmamk_f32 v90, v90, 0x3e38aa3b, v132
	v_fmamk_f32 v91, v91, 0x3e38aa3b, v132
	v_fmamk_f32 v92, v92, 0x3e38aa3b, v132
	v_fmamk_f32 v93, v93, 0x3e38aa3b, v132
	v_fmamk_f32 v94, v94, 0x3e38aa3b, v132
	v_fmamk_f32 v95, v95, 0x3e38aa3b, v132
	v_fmamk_f32 v96, v96, 0x3e38aa3b, v132
	v_fmac_f32_e32 v133, 0x3e38aa3b, v97
	s_mov_b32 s2, 0x3e38aa3b
	v_exp_f32_e32 v177, v82
	v_exp_f32_e32 v226, v83
	v_exp_f32_e32 v161, v84
	v_exp_f32_e32 v223, v85
	v_exp_f32_e32 v153, v86
	v_exp_f32_e32 v176, v87
	v_exp_f32_e32 v152, v88
	v_exp_f32_e32 v160, v89
	v_exp_f32_e32 v149, v90
	v_exp_f32_e32 v151, v91
	v_exp_f32_e32 v147, v92
	v_exp_f32_e32 v150, v93
	v_exp_f32_e32 v145, v94
	v_exp_f32_e32 v148, v95
	v_exp_f32_e32 v144, v96
	v_exp_f32_e32 v146, v133
	v_pk_fma_f32 v[138:139], v[66:67], s[2:3], v[132:133] op_sel_hi:[1,0,0]
	v_add_f32_e32 v66, v220, v221
	v_pk_fma_f32 v[136:137], v[68:69], s[2:3], v[132:133] op_sel_hi:[1,0,0]
	v_pk_fma_f32 v[130:131], v[70:71], s[2:3], v[132:133] op_sel_hi:[1,0,0]
	v_pk_fma_f32 v[128:129], v[72:73], s[2:3], v[132:133] op_sel_hi:[1,0,0]
	v_pk_fma_f32 v[126:127], v[74:75], s[2:3], v[132:133] op_sel_hi:[1,0,0]
	v_pk_fma_f32 v[140:141], v[76:77], s[2:3], v[132:133] op_sel_hi:[1,0,0]
	v_pk_fma_f32 v[134:135], v[78:79], s[2:3], v[132:133] op_sel_hi:[1,0,0]
	v_pk_fma_f32 v[132:133], v[80:81], s[2:3], v[132:133] op_sel_hi:[1,0,0]
	v_fmac_f32_e32 v66, v219, v209
	v_add_f32_e32 v209, v224, v225
	s_mov_b64 s[2:3], 0x140000
	v_fmac_f32_e32 v209, v66, v222
	s_add_i32 s8, s8, 2
	v_lshl_add_u64 v[156:157], v[156:157], 0, s[2:3]
	v_lshl_add_u64 v[158:159], v[158:159], 0, s[2:3]
	s_and_b64 vcc, exec, s[4:5]
	s_waitcnt lgkmcnt(0)
	s_barrier
	s_cbranch_vccnz .LBB0_713
	v_mov_b32_e32 v219, v143
	ds_write_b128 v212, v[182:185] offset:16384
	ds_write_b128 v213, v[194:197] offset:16384
	s_branch .LBB0_701

; #define SBAR() __builtin_amdgcn_sched_barrier(0)
; #define HOOK(P0, P1, j) do { if (NA) na_hook(P0, P1, krow0 + (j), q_row, q_col, win_r, win_c, rpb, inv_scale, hi); } while (0)
; template <int DK, bool NA, bool QL, int SD> ...
;     ...
;   SBAR(); qkt<DK, QL>(pB0, pB1, (bf16*)((char*)K_lds + SHM_K), qr, ql, r32, hi); HOOK(pB0, pB1, NT - 1);
;   finishSM(pA0, pA1, alA, l_reg, pa0, pa1, pa2, pa3); SBAR();
;   pv_d0(o, vb0, pa0, pa1, pa2, pa3); partialSM(pB0, pB1, m_reg, mnB, alB, C, thrRaw);
.LBB0_713:
	ds_write_b128 v212, v[182:185] offset:16384
	ds_write_b128 v213, v[194:197] offset:16384
	ds_read_b128 v[66:69], v215 offset:49152
	ds_read_b128 v[70:73], v215 offset:53248
	v_exp_f32_e32 v118, v140
	v_exp_f32_e32 v119, v141
	v_exp_f32_e32 v120, v134
	s_waitcnt lgkmcnt(1)
	v_mfma_f32_32x32x16_bf16 v[82:97], v[66:69], v[110:113], 0
	v_exp_f32_e32 v121, v135
	v_exp_f32_e32 v122, v132
	v_exp_f32_e32 v123, v133
	s_waitcnt lgkmcnt(0)
	v_mfma_f32_32x32x16_bf16 v[66:81], v[70:73], v[110:113], 0
	ds_read_b128 v[110:113], v216 offset:49152
	ds_read_b128 v[114:117], v216 offset:53248
	s_waitcnt lgkmcnt(1)
	v_mfma_f32_32x32x16_bf16 v[82:97], v[110:113], v[106:109], v[82:97]
	s_waitcnt lgkmcnt(0)
	v_mfma_f32_32x32x16_bf16 v[66:81], v[114:117], v[106:109], v[66:81]
	ds_read_b128 v[106:109], v217 offset:49152
	ds_read_b128 v[110:113], v217 offset:53248
	v_exp_f32_e32 v114, v128
	v_exp_f32_e32 v115, v129
	v_exp_f32_e32 v116, v126
	v_exp_f32_e32 v117, v127
	s_waitcnt lgkmcnt(1)
	v_mfma_f32_32x32x16_bf16 v[82:97], v[106:109], v[102:105], v[82:97]
	s_waitcnt lgkmcnt(0)
	v_mfma_f32_32x32x16_bf16 v[66:81], v[110:113], v[102:105], v[66:81]
	ds_read_b128 v[102:105], v218 offset:49152
	ds_read_b128 v[106:109], v218 offset:53248
	v_exp_f32_e32 v110, v136
	v_exp_f32_e32 v111, v137
	v_exp_f32_e32 v112, v130
	v_exp_f32_e32 v113, v131
	s_waitcnt lgkmcnt(1)
	v_mfma_f32_32x32x16_bf16 v[82:97], v[102:105], v[98:101], v[82:97]
	s_waitcnt lgkmcnt(0)
	v_mfma_f32_32x32x16_bf16 v[66:81], v[106:109], v[98:101], v[66:81]
	v_add_f32_e32 v98, 0, v177
	v_add_f32_e32 v98, v226, v98
	v_add_f32_e32 v98, v161, v98
	v_add_f32_e32 v98, v223, v98
	v_add_f32_e32 v98, v153, v98
	v_add_f32_e32 v98, v176, v98
	v_add_f32_e32 v98, v152, v98
	v_add_f32_e32 v98, v160, v98
	v_add_f32_e32 v98, v149, v98
	v_add_f32_e32 v98, v151, v98
	v_add_f32_e32 v98, v147, v98
	v_add_f32_e32 v98, v150, v98
	v_exp_f32_e32 v108, v138
	v_add_f32_e32 v98, v145, v98
	v_exp_f32_e32 v109, v139
	v_add_f32_e32 v98, v148, v98
	v_add_f32_e32 v98, v144, v98
	v_add_f32_e32 v98, v146, v98
	v_add_f32_e32 v98, v108, v98
	v_add_f32_e32 v98, v109, v98
	v_add_f32_e32 v98, v110, v98
	v_add_f32_e32 v98, v111, v98
	v_add_f32_e32 v98, v112, v98
	v_add_f32_e32 v98, v113, v98
	v_add_f32_e32 v98, v114, v98
	v_add_f32_e32 v98, v115, v98
	v_add_f32_e32 v98, v116, v98
	v_add_f32_e32 v98, v117, v98
	v_add_f32_e32 v98, v118, v98
	v_add_f32_e32 v98, v119, v98
	v_add_f32_e32 v98, v120, v98
	v_add_f32_e32 v98, v121, v98
	v_add_f32_e32 v98, v122, v98
	v_add_f32_e32 v98, v123, v98
	v_mov_b32_e32 v99, v98
	v_cvt_pk_bf16_f32 v100, v177, v226
	v_cvt_pk_bf16_f32 v101, v161, v223
	v_cvt_pk_bf16_f32 v102, v153, v176
	v_cvt_pk_bf16_f32 v103, v152, v160
	s_nop 1
	v_permlane32_swap_b32_e32 v98, v99
	v_permlane32_swap_b32_e32 v100, v102
	v_permlane32_swap_b32_e32 v101, v103
	v_cvt_pk_bf16_f32 v104, v149, v151
	v_cvt_pk_bf16_f32 v105, v147, v150
	v_cvt_pk_bf16_f32 v106, v145, v148
	v_cvt_pk_bf16_f32 v107, v144, v146
	v_cvt_pk_bf16_f32 v108, v108, v109
	v_cvt_pk_bf16_f32 v109, v110, v111
	v_cvt_pk_bf16_f32 v110, v112, v113
	v_cvt_pk_bf16_f32 v111, v114, v115
	v_cvt_pk_bf16_f32 v112, v116, v117
	v_cvt_pk_bf16_f32 v113, v118, v119
	v_cvt_pk_bf16_f32 v114, v120, v121
	v_cvt_pk_bf16_f32 v115, v122, v123
	s_nop 0
	v_permlane32_swap_b32_e32 v104, v106
	v_permlane32_swap_b32_e32 v105, v107
	v_permlane32_swap_b32_e32 v108, v110
	v_permlane32_swap_b32_e32 v109, v111
	v_permlane32_swap_b32_e32 v112, v114
	v_permlane32_swap_b32_e32 v113, v115
	ds_read_b64_tr_b16 v[116:117], v211 offset:0
	ds_read_b64_tr_b16 v[118:119], v211 offset:0x800
	ds_read_b64_tr_b16 v[120:121], v211 offset:0x1000
	ds_read_b64_tr_b16 v[122:123], v211 offset:0x1800
	ds_read_b64_tr_b16 v[124:125], v211 offset:0x2000
	ds_read_b64_tr_b16 v[126:127], v211 offset:0x2800
	ds_read_b64_tr_b16 v[128:129], v211 offset:0x3000
	ds_read_b64_tr_b16 v[130:131], v211 offset:0x3800
	s_waitcnt lgkmcnt(0)
	s_nop 0
	v_mfma_f32_32x32x16_bf16 v[2:17], v[100:103], v[116:119], v[2:17]
	ds_read_b64_tr_b16 v[116:117], v211 offset:0x200
	ds_read_b64_tr_b16 v[118:119], v211 offset:0xa00
	v_mfma_f32_32x32x16_bf16 v[2:17], v[104:107], v[120:123], v[2:17]
	ds_read_b64_tr_b16 v[120:121], v211 offset:0x1200
	ds_read_b64_tr_b16 v[122:123], v211 offset:0x1a00
	v_mfma_f32_32x32x16_bf16 v[2:17], v[108:111], v[124:127], v[2:17]
	ds_read_b64_tr_b16 v[124:125], v211 offset:0x2200
	ds_read_b64_tr_b16 v[126:127], v211 offset:0x2a00
	v_mfma_f32_32x32x16_bf16 v[2:17], v[112:115], v[128:131], v[2:17]
	ds_read_b64_tr_b16 v[128:129], v211 offset:0x3200
	ds_read_b64_tr_b16 v[130:131], v211 offset:0x3a00
	s_waitcnt lgkmcnt(0)
; #define RESC(a) do { if (__any((a) < 1.f)) { if (hi == 0) al_l[r32] = (a); asm volatile("s_waitcnt lgkmcnt(0)" ::: "memory"); \
;     _Pragma("unroll") for (int d = 0; d < 4; ++d) _Pragma("unroll") for (int r = 0; r < 16; ++r) o[d][r] *= al_l[crow(r, hi)]; } } while (0)
; template <int DK, bool NA, bool QL, int SD> ...
;     ...
;   pv_d0(o, vb0, pa0, pa1, pa2, pa3); partialSM(pB0, pB1, m_reg, mnB, alB, C, thrRaw);
;   __syncthreads(); RESC(alB);
	v_mfma_f32_32x32x16_bf16 v[50:65], v[100:103], v[116:119], v[50:65]
	ds_read_b64_tr_b16 v[116:117], v211 offset:0x400
	ds_read_b64_tr_b16 v[118:119], v211 offset:0xc00
	v_mfma_f32_32x32x16_bf16 v[50:65], v[104:107], v[120:123], v[50:65]
	ds_read_b64_tr_b16 v[120:121], v211 offset:0x1400
	ds_read_b64_tr_b16 v[122:123], v211 offset:0x1c00
	v_mfma_f32_32x32x16_bf16 v[50:65], v[108:111], v[124:127], v[50:65]
	ds_read_b64_tr_b16 v[124:125], v211 offset:0x2400
	ds_read_b64_tr_b16 v[126:127], v211 offset:0x2c00
	v_mfma_f32_32x32x16_bf16 v[50:65], v[112:115], v[128:131], v[50:65]
	ds_read_b64_tr_b16 v[128:129], v211 offset:0x3400
	ds_read_b64_tr_b16 v[130:131], v211 offset:0x3c00
	s_waitcnt lgkmcnt(0)
	v_mfma_f32_32x32x16_bf16 v[34:49], v[100:103], v[116:119], v[34:49]
	ds_read_b64_tr_b16 v[116:117], v211 offset:0x600
	ds_read_b64_tr_b16 v[118:119], v211 offset:0xe00
	v_mfma_f32_32x32x16_bf16 v[34:49], v[104:107], v[120:123], v[34:49]
	ds_read_b64_tr_b16 v[120:121], v211 offset:0x1600
	ds_read_b64_tr_b16 v[122:123], v211 offset:0x1e00
	v_mfma_f32_32x32x16_bf16 v[34:49], v[108:111], v[124:127], v[34:49]
	ds_read_b64_tr_b16 v[124:125], v211 offset:0x2600
	ds_read_b64_tr_b16 v[126:127], v211 offset:0x2e00
	v_mfma_f32_32x32x16_bf16 v[34:49], v[112:115], v[128:131], v[34:49]
	ds_read_b64_tr_b16 v[128:129], v211 offset:0x3600
	ds_read_b64_tr_b16 v[130:131], v211 offset:0x3e00
	s_waitcnt lgkmcnt(0)
	v_mfma_f32_32x32x16_bf16 v[18:33], v[100:103], v[116:119], v[18:33]
	v_max_f32_e32 v100, v83, v83
	v_max_f32_e32 v101, v82, v82
	v_max_f32_e32 v100, v101, v100
	v_max3_f32 v100, v100, v84, v85
	v_max3_f32 v100, v100, v86, v87
	v_max3_f32 v100, v100, v88, v89
	v_max3_f32 v100, v100, v90, v91
	v_max3_f32 v100, v100, v92, v93
	v_max3_f32 v100, v100, v94, v95
	v_mfma_f32_32x32x16_bf16 v[18:33], v[104:107], v[120:123], v[18:33]
	v_max3_f32 v100, v100, v96, v97
	v_max3_f32 v100, v100, v66, v67
	v_max3_f32 v100, v100, v68, v69
	v_max3_f32 v100, v100, v70, v71
	v_max3_f32 v100, v100, v72, v73
	v_max3_f32 v100, v100, v74, v75
	v_max3_f32 v100, v100, v76, v77
	v_max3_f32 v100, v100, v78, v79
	v_mfma_f32_32x32x16_bf16 v[18:33], v[108:111], v[124:127], v[18:33]
	v_max3_f32 v100, v100, v80, v81
	v_mov_b32_e32 v101, v100
	s_nop 1
	v_permlane32_swap_b32_e32 v100, v101
	v_max_f32_e32 v101, v101, v101
	v_max_f32_e32 v100, v100, v100
	v_max_f32_e32 v100, v100, v101
	v_sub_f32_e32 v101, v100, v142
	s_mov_b32 s2, 0x42800000
	v_cmp_ge_f32_e32 vcc, s2, v101
	v_max_f32_e32 v101, v142, v142
	v_max_f32_e32 v101, v101, v100
	v_mfma_f32_32x32x16_bf16 v[18:33], v[112:115], v[128:131], v[18:33]
	v_sub_f32_e32 v100, v142, v101
	v_mul_f32_e32 v100, 0x3e38aa3b, v100
	v_exp_f32_e32 v100, v100
	s_cmp_eq_u64 vcc, exec
	s_cselect_b64 s[2:3], -1, 0
	v_cndmask_b32_e64 v100, v100, 1.0, s[2:3]
	v_cmp_gt_f32_e32 vcc, 1.0, v100
	s_barrier
	s_cbranch_vccz .LBB0_717
	s_and_saveexec_b64 s[4:5], s[0:1]
	ds_write_b32 v208, v100 offset:128
	s_or_b64 exec, exec, s[4:5]
	s_waitcnt lgkmcnt(0)
	v_add_u32_e32 v114, v207, v0
	ds_read_b128 v[102:105], v114 offset:224
	ds_read_b128 v[106:109], v114 offset:192
	ds_read_b128 v[110:113], v114 offset:160
	ds_read_b128 v[114:117], v114 offset:128
	s_waitcnt lgkmcnt(3)
	v_pk_mul_f32 v[14:15], v[14:15], v[102:103]
	s_waitcnt lgkmcnt(2)
	v_pk_mul_f32 v[10:11], v[10:11], v[106:107]
	s_waitcnt lgkmcnt(1)
	v_pk_mul_f32 v[6:7], v[6:7], v[110:111]
	v_pk_mul_f32 v[16:17], v[16:17], v[104:105]
	v_pk_mul_f32 v[12:13], v[12:13], v[108:109]
	v_pk_mul_f32 v[8:9], v[8:9], v[112:113]
	s_waitcnt lgkmcnt(0)
	v_pk_mul_f32 v[4:5], v[4:5], v[116:117]
	v_pk_mul_f32 v[2:3], v[2:3], v[114:115]
	v_pk_mul_f32 v[62:63], v[102:103], v[62:63]
	v_pk_mul_f32 v[58:59], v[106:107], v[58:59]
	v_pk_mul_f32 v[54:55], v[110:111], v[54:55]
	v_pk_mul_f32 v[64:65], v[104:105], v[64:65]
	v_pk_mul_f32 v[60:61], v[108:109], v[60:61]
	v_pk_mul_f32 v[56:57], v[112:113], v[56:57]
	v_pk_mul_f32 v[52:53], v[116:117], v[52:53]
	v_pk_mul_f32 v[50:51], v[114:115], v[50:51]
	v_pk_mul_f32 v[46:47], v[102:103], v[46:47]
	v_pk_mul_f32 v[42:43], v[106:107], v[42:43]
	v_pk_mul_f32 v[38:39], v[110:111], v[38:39]
	v_pk_mul_f32 v[48:49], v[104:105], v[48:49]
	v_pk_mul_f32 v[44:45], v[108:109], v[44:45]
	v_pk_mul_f32 v[40:41], v[112:113], v[40:41]
	v_pk_mul_f32 v[36:37], v[116:117], v[36:37]
	v_pk_mul_f32 v[34:35], v[114:115], v[34:35]
	v_pk_mul_f32 v[30:31], v[102:103], v[30:31]
	v_pk_mul_f32 v[26:27], v[106:107], v[26:27]
	v_pk_mul_f32 v[22:23], v[110:111], v[22:23]
	v_pk_mul_f32 v[32:33], v[104:105], v[32:33]
	v_pk_mul_f32 v[28:29], v[108:109], v[28:29]
	v_pk_mul_f32 v[24:25], v[112:113], v[24:25]
	v_pk_mul_f32 v[20:21], v[116:117], v[20:21]
	v_pk_mul_f32 v[18:19], v[114:115], v[18:19]
